# lane^k butterfly sums in LN0 and the fused-LayerNorm epilogues via DPP / permlane swaps instead of ds_bpermute (bit-identical)
# baseline (speedup 1.0000x reference)
; __device__ __forceinline__ float wave_sum(float v) {
;     ...
;     for (int o = 1; o < 64; o <<= 1) v += __shfl_xor(v, o);
; template <bool GATES, bool WRITE_B, bool WRITE_F, bool SRC_BF16> ...
;     ...
;         f32x4 v[8]; float s = 0.f;
; #pragma unroll
;         for (int j = 0; j < 8; ++j) {
;             if (SRC_BF16) v[j] = (f32x4){bflo(rawb[j].x), bfhi(rawb[j].x), bflo(rawb[j].y), bfhi(rawb[j].y)}; else v[j] = rawf[j];
;             s += (v[j][0] + v[j][1]) + (v[j][2] + v[j][3]);
;         }
;         if (row + rstep < T) {
; #pragma unroll
;             for (int j = 0; j < 8; ++j) { if (SRC_BF16) rawb[j] = *(const u32x2*)((const bf16_t*)src + (size_t)(row + rstep) * D + 256 * j + 4 * lane); else rawf[j] = *(const f32x4*)(src + (size_t)(row + rstep) * D + 256 * j + 4 * lane); }
;         }
;         const float mean = wave_sum(s) * (1.0f / D); float s2 = 0.f;
; #pragma unroll
;         for (int j = 0; j < 8; ++j) { v[j] = v[j] - mean; s2 += (v[j][0] * v[j][0] + v[j][1] * v[j][1]) + (v[j][2] * v[j][2] + v[j][3] * v[j][3]); }
;         const float rstd = 1.0f / sqrtf(wave_sum(s2) * (1.0f / D) + LN_EPS);
.LBB0_65:
	s_or_b64 exec, exec, s[8:9]
	v_add_f32_e32 v67, v62, v63
	v_add_f32_e32 v97, v64, v65
	v_add_f32_e32 v67, v67, v97
	v_add_f32_e32 v97, v58, v59
	v_add_f32_e32 v108, v60, v61
	v_add_f32_e32 v67, 0, v67
	v_add_f32_e32 v97, v97, v108
	v_add_f32_e32 v67, v97, v67
	v_add_f32_e32 v97, v54, v55
	v_add_f32_e32 v108, v56, v57
	v_add_f32_e32 v97, v97, v108
	v_add_f32_e32 v67, v97, v67
	v_add_f32_e32 v97, v50, v51
	v_add_f32_e32 v108, v52, v53
	v_add_f32_e32 v97, v97, v108
	v_add_f32_e32 v67, v97, v67
	v_add_f32_e32 v97, v46, v47
	v_add_f32_e32 v108, v48, v49
	v_add_f32_e32 v97, v97, v108
	v_add_f32_e32 v67, v97, v67
	v_add_f32_e32 v97, v42, v43
	v_add_f32_e32 v108, v44, v45
	v_add_f32_e32 v97, v97, v108
	v_add_f32_e32 v67, v97, v67
	v_add_f32_e32 v97, v38, v39
	v_add_f32_e32 v108, v40, v41
	v_add_f32_e32 v97, v97, v108
	v_add_f32_e32 v67, v97, v67
	v_add_f32_e32 v97, v34, v35
	v_add_f32_e32 v108, v36, v37
	v_add_f32_e32 v97, v97, v108
	v_add_f32_e32 v67, v97, v67
	s_nop 1
	v_mov_b32_dpp v97, v67 quad_perm:[1,0,3,2] row_mask:0xf bank_mask:0xf
	s_and_b64 s[6:7], exec, s[6:7]
	s_or_b64 s[14:15], s[6:7], s[14:15]
	s_waitcnt lgkmcnt(0)
	v_add_f32_e32 v67, v67, v97
	s_nop 1
	v_mov_b32_dpp v97, v67 quad_perm:[2,3,0,1] row_mask:0xf bank_mask:0xf
	s_waitcnt lgkmcnt(0)
	v_add_f32_e32 v67, v67, v97
	s_nop 1
	v_mov_b32_dpp v97, v67 row_half_mirror row_mask:0xf bank_mask:0xf
	s_waitcnt lgkmcnt(0)
	v_add_f32_e32 v67, v67, v97
	s_nop 1
	v_mov_b32_dpp v97, v67 row_mirror row_mask:0xf bank_mask:0xf
	s_waitcnt lgkmcnt(0)
	v_add_f32_e32 v67, v67, v97
	v_mov_b32_e32 v97, v67
	s_nop 1
	v_permlane16_swap_b32 v97, v67
	s_waitcnt lgkmcnt(0)
	v_add_f32_e32 v67, v67, v97
	v_mov_b32_e32 v97, v67
	s_nop 1
	v_permlane32_swap_b32 v97, v67
	s_waitcnt lgkmcnt(0)
	v_add_f32_e32 v67, v67, v97
	v_fmamk_f32 v63, v67, 0xba000000, v63
	v_fmamk_f32 v59, v67, 0xba000000, v59
	v_fmamk_f32 v65, v67, 0xba000000, v65
	v_fmac_f32_e32 v62, 0xba000000, v67
	v_fmamk_f32 v113, v67, 0xba000000, v61
	v_fmac_f32_e32 v58, 0xba000000, v67
	v_mov_b32_e32 v108, v63
	v_mov_b32_e32 v109, v59
	v_fmamk_f32 v64, v67, 0xba000000, v64
	v_fmamk_f32 v112, v67, 0xba000000, v60
	v_mov_b32_e32 v60, v62
	v_mov_b32_e32 v61, v58
	v_pk_mul_f32 v[108:109], v[108:109], v[108:109]
	v_mov_b32_e32 v110, v65
	v_mov_b32_e32 v111, v113
	v_pk_fma_f32 v[60:61], v[60:61], v[60:61], v[108:109]
	v_mov_b32_e32 v108, v64
	v_mov_b32_e32 v109, v112
	v_pk_mul_f32 v[110:111], v[110:111], v[110:111]
	v_fmamk_f32 v55, v67, 0xba000000, v55
	v_pk_fma_f32 v[108:109], v[108:109], v[108:109], v[110:111]
	v_fmamk_f32 v54, v67, 0xba000000, v54
	v_fmamk_f32 v57, v67, 0xba000000, v57
	v_fmac_f32_e32 v56, 0xba000000, v67
	v_pk_add_f32 v[60:61], v[60:61], v[108:109]
	v_pk_mul_f32 v[108:109], v[56:57], v[56:57]
	v_pk_mul_f32 v[110:111], v[54:55], v[54:55]
	v_fmac_f32_e32 v52, 0xba000000, v67
	v_pk_mov_b32 v[114:115], v[110:111], v[108:109] op_sel:[1,0]
	v_mov_b32_e32 v111, v109
	v_pk_add_f32 v[108:109], v[114:115], v[110:111]
	v_fmamk_f32 v114, v67, 0xba000000, v50
	v_fmamk_f32 v115, v67, 0xba000000, v51
	v_mul_f32_e32 v50, v114, v114
	v_pk_fma_f32 v[50:51], v[114:115], v[114:115], v[50:51] op_sel_hi:[1,1,0]
	v_fmamk_f32 v53, v67, 0xba000000, v53
	v_mul_f32_e32 v50, v52, v52
	v_pk_add_f32 v[60:61], v[60:61], v[60:61] op_sel_hi:[0,1]
	v_pk_add_f32 v[108:109], v[108:109], v[108:109] op_sel_hi:[0,1]
	v_pk_fma_f32 v[110:111], v[52:53], v[52:53], v[50:51] op_sel_hi:[1,1,0]
	v_fmamk_f32 v117, v67, 0xba000000, v49
	v_fmamk_f32 v116, v67, 0xba000000, v48
	v_fmamk_f32 v47, v67, 0xba000000, v47
	v_fmac_f32_e32 v46, 0xba000000, v67
	v_mul_f32_e32 v50, v46, v46
	v_mul_f32_e32 v110, v47, v47
	v_mul_f32_e32 v108, v116, v116
	v_mul_f32_e32 v60, v117, v117
	v_pk_add_f32 v[48:49], v[50:51], v[110:111]
	v_pk_add_f32 v[50:51], v[108:109], v[60:61]
	v_fmamk_f32 v119, v67, 0xba000000, v43
	v_fmamk_f32 v118, v67, 0xba000000, v42
	v_fmamk_f32 v45, v67, 0xba000000, v45
	v_fmac_f32_e32 v44, 0xba000000, v67
	v_fmamk_f32 v120, v67, 0xba000000, v38
	v_pk_add_f32 v[48:49], v[48:49], v[50:51]
	v_pk_mul_f32 v[42:43], v[44:45], v[44:45]
	v_pk_mul_f32 v[50:51], v[118:119], v[118:119]
	v_fmamk_f32 v121, v67, 0xba000000, v39
	v_mul_f32_e32 v38, v120, v120
	v_pk_mov_b32 v[60:61], v[50:51], v[42:43] op_sel:[1,0]
	v_mov_b32_e32 v51, v43
	v_fmac_f32_e32 v40, 0xba000000, v67
	v_pk_fma_f32 v[38:39], v[120:121], v[120:121], v[38:39] op_sel_hi:[1,1,0]
	v_pk_add_f32 v[42:43], v[60:61], v[50:51]
	v_fmamk_f32 v41, v67, 0xba000000, v41
	v_mul_f32_e32 v38, v40, v40
	v_pk_add_f32 v[48:49], v[48:49], v[48:49] op_sel_hi:[0,1]
	v_pk_add_f32 v[42:43], v[42:43], v[42:43] op_sel_hi:[0,1]
	v_pk_fma_f32 v[50:51], v[40:41], v[40:41], v[38:39] op_sel_hi:[1,1,0]
	v_fmamk_f32 v123, v67, 0xba000000, v37
	v_fmamk_f32 v122, v67, 0xba000000, v36
	v_fmamk_f32 v35, v67, 0xba000000, v35
	v_fmac_f32_e32 v34, 0xba000000, v67
	v_mul_f32_e32 v38, v34, v34
	v_mul_f32_e32 v50, v35, v35
	v_mul_f32_e32 v42, v122, v122
	v_mul_f32_e32 v48, v123, v123
	v_pk_add_f32 v[36:37], v[38:39], v[50:51]
	v_pk_add_f32 v[38:39], v[42:43], v[48:49]
	global_load_dwordx4 v[48:51], v[70:71], off
	global_load_dwordx4 v[108:111], v[72:73], off
	v_pk_add_f32 v[36:37], v[36:37], v[38:39]
	v_ashrrev_i32_e32 v67, 31, v66
	v_add_f32_e32 v36, v36, v37
	s_nop 1
	v_mov_b32_dpp v37, v36 quad_perm:[1,0,3,2] row_mask:0xf bank_mask:0xf
	v_mov_b32_e32 v97, 0
	s_waitcnt lgkmcnt(0)
	v_add_f32_e32 v36, v36, v37
	s_nop 1
	v_mov_b32_dpp v37, v36 quad_perm:[2,3,0,1] row_mask:0xf bank_mask:0xf
	s_waitcnt lgkmcnt(0)
; __device__ __forceinline__ unsigned pk2(float lo, float hi) { f32x2_t v = {lo, hi}; bf16x2_t b = __builtin_convertvector(v, bf16x2_t); return __builtin_bit_cast(unsigned, b); }
; __device__ __forceinline__ float wave_sum(float v) {
;     ...
;     for (int o = 1; o < 64; o <<= 1) v += __shfl_xor(v, o);
; template <bool GATES, bool WRITE_B, bool WRITE_F, bool SRC_BF16> ...
;     ...
;         const float mean = wave_sum(s) * (1.0f / D); float s2 = 0.f;
; #pragma unroll
;         for (int j = 0; j < 8; ++j) { v[j] = v[j] - mean; s2 += (v[j][0] * v[j][0] + v[j][1] * v[j][1]) + (v[j][2] * v[j][2] + v[j][3] * v[j][3]); }
;         const float rstd = 1.0f / sqrtf(wave_sum(s2) * (1.0f / D) + LN_EPS);
; #pragma unroll
;         for (int j = 0; j < 8; ++j) {
;             const f32x4 wvj = *(const f32x4*)(w + 256 * j + 4 * lane), bvj = *(const f32x4*)(b + 256 * j + 4 * lane);
;             v[j] = (v[j] * rstd) * wvj + bvj;
;             if (WRITE_F) *(f32x4*)(dstF + (size_t)row * D + 256 * j + 4 * lane) = v[j];
;             if (WRITE_B) { u32x2 o; o.x = pk2(v[j][0], v[j][1]); o.y = pk2(v[j][2], v[j][3]); *(u32x2*)(dstB + (size_t)row * D + 256 * j + 4 * lane) = o; }
;         }
	v_add_f32_e32 v36, v36, v37
	s_nop 1
	v_mov_b32_dpp v37, v36 row_half_mirror row_mask:0xf bank_mask:0xf
	s_waitcnt lgkmcnt(0)
	v_add_f32_e32 v36, v36, v37
	s_nop 1
	v_mov_b32_dpp v37, v36 row_mirror row_mask:0xf bank_mask:0xf
	s_waitcnt lgkmcnt(0)
	v_add_f32_e32 v36, v36, v37
	v_mov_b32_e32 v37, v36
	s_nop 1
	v_permlane16_swap_b32 v37, v36
	s_waitcnt lgkmcnt(0)
	v_add_f32_e32 v36, v36, v37
	v_mov_b32_e32 v37, v36
	s_nop 1
	v_permlane32_swap_b32 v37, v36
	s_waitcnt lgkmcnt(0)
	v_add_f32_e32 v36, v36, v37
	v_fmamk_f32 v36, v36, 0x3a000000, v106
	v_mul_f32_e32 v37, 0x4f800000, v36
	v_cmp_gt_f32_e32 vcc, s17, v36
	s_nop 1
	v_cndmask_b32_e32 v36, v36, v37, vcc
	v_sqrt_f32_e32 v37, v36
	s_nop 0
	v_add_u32_e32 v38, -1, v37
	v_fma_f32 v39, -v38, v37, v36
	v_cmp_ge_f32_e64 s[8:9], 0, v39
	v_add_u32_e32 v39, 1, v37
	s_nop 0
	v_cndmask_b32_e64 v38, v37, v38, s[8:9]
	v_fma_f32 v37, -v39, v37, v36
	v_cmp_lt_f32_e64 s[8:9], 0, v37
	s_nop 1
	v_cndmask_b32_e64 v37, v38, v39, s[8:9]
	v_mul_f32_e32 v38, 0x37800000, v37
	v_cndmask_b32_e32 v37, v37, v38, vcc
	v_cmp_class_f32_e32 vcc, v36, v107
	s_nop 1
	v_cndmask_b32_e32 v36, v37, v36, vcc
	v_div_scale_f32 v37, s[8:9], v36, v36, 1.0
	v_rcp_f32_e32 v38, v37
	s_mov_b32 s8, 0
	v_fma_f32 v39, -v37, v38, 1.0
	v_fmac_f32_e32 v38, v39, v38
	v_div_scale_f32 v39, vcc, 1.0, v36, 1.0
	v_mul_f32_e32 v42, v39, v38
	v_fma_f32 v43, -v37, v42, v39
	v_fmac_f32_e32 v42, v43, v38
	v_fma_f32 v37, -v37, v42, v39
	v_div_fmas_f32 v37, v37, v38, v42
	v_div_fixup_f32 v124, v37, v36, 1.0
	v_lshlrev_b64 v[36:37], 12, v[66:67]
	v_lshl_add_u64 v[126:127], v[74:75], 0, v[36:37]
	v_pk_mul_f32 v[38:39], v[62:63], v[124:125] op_sel_hi:[1,0]
	v_pk_mul_f32 v[36:37], v[64:65], v[124:125] op_sel_hi:[1,0]
	s_waitcnt vmcnt(0)
	v_pk_fma_f32 v[38:39], v[48:49], v[38:39], v[108:109]
	v_pk_fma_f32 v[36:37], v[50:51], v[36:37], v[110:111]
	v_cvt_pk_bf16_f32 v42, v38, v39
	v_cvt_pk_bf16_f32 v43, v36, v37
	global_store_dwordx2 v[126:127], v[42:43], off
	global_load_dwordx4 v[48:51], v[70:71], off offset:1024
	global_load_dwordx4 v[60:63], v[72:73], off offset:1024
	v_pk_mul_f32 v[58:59], v[58:59], v[124:125] op_sel_hi:[1,0]
	v_pk_mul_f32 v[42:43], v[112:113], v[124:125] op_sel_hi:[1,0]
	v_pk_mul_f32 v[54:55], v[54:55], v[124:125] op_sel_hi:[1,0]
	v_pk_mul_f32 v[52:53], v[52:53], v[124:125] op_sel_hi:[1,0]
	v_pk_mul_f32 v[108:109], v[46:47], v[124:125] op_sel_hi:[1,0]
	v_pk_mul_f32 v[46:47], v[116:117], v[124:125] op_sel_hi:[1,0]
	v_pk_mul_f32 v[44:45], v[44:45], v[124:125] op_sel_hi:[1,0]
	v_pk_mul_f32 v[112:113], v[120:121], v[124:125] op_sel_hi:[1,0]
	v_pk_mul_f32 v[40:41], v[40:41], v[124:125] op_sel_hi:[1,0]
	s_waitcnt vmcnt(0)
	v_pk_fma_f32 v[42:43], v[50:51], v[42:43], v[62:63]
	v_pk_fma_f32 v[48:49], v[48:49], v[58:59], v[60:61]
	v_cvt_pk_bf16_f32 v51, v42, v43
	v_cvt_pk_bf16_f32 v50, v48, v49
	global_store_dwordx2 v[126:127], v[50:51], off offset:512
	global_load_dwordx4 v[58:61], v[70:71], off offset:2048
	global_load_dwordx4 v[62:65], v[72:73], off offset:2048
	v_pk_mul_f32 v[50:51], v[56:57], v[124:125] op_sel_hi:[1,0]
	s_waitcnt vmcnt(0)
	v_pk_fma_f32 v[54:55], v[58:59], v[54:55], v[62:63]
	v_pk_fma_f32 v[50:51], v[60:61], v[50:51], v[64:65]
	v_cvt_pk_bf16_f32 v56, v54, v55
	v_cvt_pk_bf16_f32 v57, v50, v51
	global_store_dwordx2 v[126:127], v[56:57], off offset:1024
	global_load_dwordx4 v[56:59], v[70:71], off offset:3072
	s_nop 0
	global_load_dwordx4 v[60:63], v[72:73], off offset:3072
	v_pk_mul_f32 v[64:65], v[114:115], v[124:125] op_sel_hi:[1,0]
	s_waitcnt vmcnt(0)
	v_pk_fma_f32 v[52:53], v[58:59], v[52:53], v[62:63]
	v_pk_fma_f32 v[56:57], v[56:57], v[64:65], v[60:61]
	v_cvt_pk_bf16_f32 v59, v52, v53
	v_cvt_pk_bf16_f32 v58, v56, v57
	global_store_dwordx2 v[126:127], v[58:59], off offset:1536
	global_load_dwordx4 v[58:61], v[78:79], off
	s_nop 0
	global_load_dwordx4 v[62:65], v[80:81], off
	s_waitcnt vmcnt(0)
	v_pk_fma_f32 v[46:47], v[60:61], v[46:47], v[64:65]
	v_pk_fma_f32 v[58:59], v[58:59], v[108:109], v[62:63]
	v_cvt_pk_bf16_f32 v61, v46, v47
	v_cvt_pk_bf16_f32 v60, v58, v59
	global_store_dwordx2 v[126:127], v[60:61], off offset:2048
	global_load_dwordx4 v[60:63], v[82:83], off
	s_nop 0
	global_load_dwordx4 v[108:111], v[84:85], off
	v_pk_mul_f32 v[64:65], v[118:119], v[124:125] op_sel_hi:[1,0]
	s_waitcnt vmcnt(0)
	v_pk_fma_f32 v[44:45], v[62:63], v[44:45], v[110:111]
	v_pk_fma_f32 v[60:61], v[60:61], v[64:65], v[108:109]
	v_cvt_pk_bf16_f32 v63, v44, v45
	v_cvt_pk_bf16_f32 v62, v60, v61
	global_store_dwordx2 v[126:127], v[62:63], off offset:2560
	global_load_dwordx4 v[62:65], v[86:87], off
	s_nop 0
	global_load_dwordx4 v[108:111], v[88:89], off
	s_waitcnt vmcnt(0)
	v_pk_fma_f32 v[40:41], v[64:65], v[40:41], v[110:111]
	v_pk_fma_f32 v[62:63], v[62:63], v[112:113], v[108:109]
	v_cvt_pk_bf16_f32 v65, v40, v41
	v_cvt_pk_bf16_f32 v64, v62, v63
	global_store_dwordx2 v[126:127], v[64:65], off offset:3072
	global_load_dwordx4 v[108:111], v[90:91], off
	global_load_dwordx4 v[112:115], v[92:93], off
	v_pk_mul_f32 v[64:65], v[34:35], v[124:125] op_sel_hi:[1,0]
	v_pk_mul_f32 v[34:35], v[122:123], v[124:125] op_sel_hi:[1,0]
	s_waitcnt vmcnt(0)
	v_pk_fma_f32 v[64:65], v[108:109], v[64:65], v[112:113]
	v_pk_fma_f32 v[34:35], v[110:111], v[34:35], v[114:115]
	v_cvt_pk_bf16_f32 v108, v64, v65
	v_cvt_pk_bf16_f32 v109, v34, v35
	global_store_dwordx2 v[126:127], v[108:109], off offset:3584
	s_branch .LBB0_67

; #define LAS __attribute__((address_space(3)))
; #define gate_b KIN(7)
; __device__ __forceinline__ float wave_sum(float v) {
;     ...
;     for (int o = 1; o < 64; o <<= 1) v += __shfl_xor(v, o);
; template <bool GATES, bool WRITE_B, bool WRITE_F, bool SRC_BF16> ...
;     ...
;         if (GATES) {
;             float mine = 0.f;
; #pragma unroll 1
;             for (int g = 0; g < 8; ++g) {
;                 float p = 0.f;
; #pragma unroll
;                 for (int j = 0; j < 8; ++j) { const f32x4 q = *(const LAS f32x4*)(wg + g * D + 256 * j + 4 * lane); p += (v[j][0] * q[0] + v[j][1] * q[1]) + (v[j][2] * q[2] + v[j][3] * q[3]); }
;                 p = wave_sum(p);
;                 if (lane == g) mine = p + gate_b[g];
;             }
;             if (lane < 8) gif[(size_t)row * 8 + lane] = mine;
.LBB0_67:
	v_add_u32_e32 v116, s8, v104
	s_waitcnt lgkmcnt(0)
	ds_read_b128 v[108:111], v116
	ds_read_b128 v[112:115], v116 offset:1024
	v_cmp_eq_u32_e32 vcc, s8, v105
	s_waitcnt lgkmcnt(1)
	v_mul_f32_e32 v109, v39, v109
	v_mul_f32_e32 v111, v37, v111
	v_fmac_f32_e32 v109, v38, v108
	v_fmac_f32_e32 v111, v36, v110
	s_waitcnt lgkmcnt(0)
	v_mul_f32_e32 v113, v49, v113
	v_add_f32_e32 v108, v109, v111
	v_add_f32_e32 v117, 0, v108
	v_fmac_f32_e32 v113, v48, v112
	v_mul_f32_e32 v112, v43, v115
	ds_read_b128 v[108:111], v116 offset:2048
	v_fmac_f32_e32 v112, v42, v114
	v_add_f32_e32 v112, v113, v112
	v_add_f32_e32 v117, v117, v112
	ds_read_b128 v[112:115], v116 offset:3072
	s_waitcnt lgkmcnt(1)
	v_mul_f32_e32 v109, v55, v109
	v_fmac_f32_e32 v109, v54, v108
	v_mul_f32_e32 v108, v51, v111
	v_fmac_f32_e32 v108, v50, v110
	v_add_f32_e32 v108, v109, v108
	s_waitcnt lgkmcnt(0)
	v_mul_f32_e32 v113, v57, v113
	v_add_f32_e32 v117, v117, v108
	v_fmac_f32_e32 v113, v56, v112
	v_mul_f32_e32 v112, v53, v115
	ds_read_b128 v[108:111], v116 offset:4096
	v_fmac_f32_e32 v112, v52, v114
	v_add_f32_e32 v112, v113, v112
	v_add_f32_e32 v117, v117, v112
	ds_read_b128 v[112:115], v116 offset:5120
	s_waitcnt lgkmcnt(1)
	v_mul_f32_e32 v109, v59, v109
	v_fmac_f32_e32 v109, v58, v108
	v_mul_f32_e32 v108, v47, v111
	v_fmac_f32_e32 v108, v46, v110
	v_add_f32_e32 v108, v109, v108
	s_waitcnt lgkmcnt(0)
	v_mul_f32_e32 v113, v61, v113
	v_add_f32_e32 v117, v117, v108
	v_fmac_f32_e32 v113, v60, v112
	v_mul_f32_e32 v112, v45, v115
	ds_read_b128 v[108:111], v116 offset:6144
	v_fmac_f32_e32 v112, v44, v114
	v_add_f32_e32 v112, v113, v112
	v_add_f32_e32 v117, v117, v112
	ds_read_b128 v[112:115], v116 offset:7168
	s_waitcnt lgkmcnt(1)
	v_mul_f32_e32 v109, v63, v109
	v_fmac_f32_e32 v109, v62, v108
	v_mul_f32_e32 v108, v41, v111
	v_fmac_f32_e32 v108, v40, v110
	v_add_f32_e32 v108, v109, v108
	s_waitcnt lgkmcnt(0)
	v_mul_f32_e32 v109, v65, v113
	v_mul_f32_e32 v110, v35, v115
	v_fmac_f32_e32 v109, v64, v112
	v_fmac_f32_e32 v110, v34, v114
	v_add_f32_e32 v108, v117, v108
	v_add_f32_e32 v109, v109, v110
	v_add_f32_e32 v108, v108, v109
	s_nop 1
	v_mov_b32_dpp v109, v108 quad_perm:[1,0,3,2] row_mask:0xf bank_mask:0xf
	s_waitcnt lgkmcnt(0)
	v_add_f32_e32 v108, v108, v109
	s_nop 1
	v_mov_b32_dpp v109, v108 quad_perm:[2,3,0,1] row_mask:0xf bank_mask:0xf
	s_waitcnt lgkmcnt(0)
	v_add_f32_e32 v108, v108, v109
	s_nop 1
	v_mov_b32_dpp v109, v108 row_half_mirror row_mask:0xf bank_mask:0xf
	s_waitcnt lgkmcnt(0)
	v_add_f32_e32 v108, v108, v109
	s_nop 1
	v_mov_b32_dpp v109, v108 row_mirror row_mask:0xf bank_mask:0xf
	s_waitcnt lgkmcnt(0)
	v_add_f32_e32 v108, v108, v109
	v_mov_b32_e32 v109, v108
	s_nop 1
	v_permlane16_swap_b32 v109, v108
	s_waitcnt lgkmcnt(0)
	v_add_f32_e32 v108, v108, v109
	v_mov_b32_e32 v109, v108
	s_nop 1
	v_permlane32_swap_b32 v109, v108
	s_and_saveexec_b64 s[6:7], vcc
	s_cbranch_execz .LBB0_66
	global_load_dword v97, v[94:95], off
	s_waitcnt lgkmcnt(0)
	v_add_f32_e32 v108, v108, v109
	s_waitcnt vmcnt(0)
	v_add_f32_e32 v97, v108, v97
	s_branch .LBB0_66

;     __device__ __forceinline__ void run(const f32x4 (&v)[2][2][4][2], const Unit& u, int wr, int wc, int fr, int fq, LAS unsigned char* lds, int wid, int lane) const {
;     ...
;         for (int ai = 0; ai < 2; ++ai)
; #pragma unroll
;             for (int m = 0; m < 4; ++m) {
;                 float s = 0.f;
; #pragma unroll
;                 for (int bj = 0; bj < 2; ++bj)
; #pragma unroll
;                     for (int n = 0; n < 2; ++n) { const f32x4 x = v[ai][bj][m][n]; s += (x[0] + x[1]) + (x[2] + x[3]); }
;                 s += __shfl_xor(s, 16); s += __shfl_xor(s, 32);
;                 const float mw = s * (1.0f / 64.0f); float q = 0.f;
; #pragma unroll
;                 for (int bj = 0; bj < 2; ++bj)
; #pragma unroll
;                     for (int n = 0; n < 2; ++n) { const f32x4 d = v[ai][bj][m][n] - mw; q += (d[0] * d[0] + d[1] * d[1]) + (d[2] * d[2] + d[3] * d[3]); }
;                 q += __shfl_xor(q, 16); q += __shfl_xor(q, 32);
;     __device__ __forceinline__ void fused(f32x4 (&acc)[2][2][4][2], const Unit& u, int wr, int wc, int fr, int fq, LAS unsigned char* lds, int wid, int lane) const {
;     ...
;         const int col0 = u.pn * BM + wc * 32 + 8 * fq;
; #pragma unroll
;         for (int ai = 0; ai < 2; ++ai)
; #pragma unroll
;             for (int m = 0; m < 4; ++m) {
;                 const size_t ro = (size_t)(u.pm * BM + ai * HALF + wr * 64 + m * 16 + fr) * D + col0;
; #pragma unroll
;                 for (int bj = 0; bj < 2; ++bj) {
;                     const u32x4 hb = *(const u32x4*)(H + ro + bj * HALF);
;                     const f32x4 h0 = {bflo(hb.x), bfhi(hb.x), bflo(hb.y), bfhi(hb.y)}, h1 = {bflo(hb.z), bfhi(hb.z), bflo(hb.w), bfhi(hb.w)};
;                     acc[ai][bj][m][0] = h0 * ALPHA + acc[ai][bj][m][0]; acc[ai][bj][m][1] = h1 * ALPHA + acc[ai][bj][m][1];
.LBB0_781:
	s_add_u32 s40, s52, 0x17000000
	s_addc_u32 s41, s53, 0
	s_lshl_b32 s7, s36, 5
	s_lshl_b32 s8, s50, 8
	v_lshrrev_b32_e32 v2, 1, v193
	s_or_b32 s7, s8, s7
	v_and_or_b32 v2, v2, 24, s7
	s_lshl_b32 s7, s6, 8
	s_add_i32 s8, s7, s51
	v_or_b32_e32 v136, s8, v194
	v_ashrrev_i32_e32 v137, 31, v136
	v_ashrrev_i32_e32 v3, 31, v2
	v_lshlrev_b64 v[132:133], 12, v[136:137]
	v_lshl_add_u64 v[132:133], s[40:41], 0, v[132:133]
	v_lshlrev_b64 v[172:173], 1, v[2:3]
	v_lshl_add_u64 v[138:139], v[132:133], 0, v[172:173]
	s_waitcnt vmcnt(0)
	s_barrier
	global_load_dwordx4 v[132:135], v[138:139], off
	v_and_b32_e32 v191, 64, v217
	v_xor_b32_e32 v190, 16, v217
	v_add_u32_e32 v191, 64, v191
	v_cmp_lt_i32_e32 vcc, v190, v191
	v_and_b32_e32 v1, 63, v193
	s_lshl_b32 s8, s36, 3
	v_cndmask_b32_e32 v190, v217, v190, vcc
	v_lshlrev_b32_e32 v195, 2, v190
	v_xor_b32_e32 v190, 32, v217
	v_cmp_lt_i32_e32 vcc, v190, v191
	s_add_i32 s36, s8, 0
	s_waitcnt vmcnt(0)
	v_lshlrev_b32_e32 v142, 16, v134
	v_and_b32_e32 v143, 0xffff0000, v134
	v_lshlrev_b32_e32 v134, 16, v135
	v_and_b32_e32 v135, 0xffff0000, v135
	v_pk_fma_f32 v[182:183], v[142:143], s[24:25], v[124:125] op_sel_hi:[1,0,1]
	v_pk_fma_f32 v[184:185], v[134:135], s[24:25], v[126:127] op_sel_hi:[1,0,1]
	global_load_dwordx4 v[124:127], v[138:139], off offset:256
	v_lshlrev_b32_e32 v140, 16, v132
	v_and_b32_e32 v141, 0xffff0000, v132
	v_lshlrev_b32_e32 v132, 16, v133
	v_and_b32_e32 v133, 0xffff0000, v133
	v_pk_fma_f32 v[188:189], v[132:133], s[24:25], v[130:131] op_sel_hi:[1,0,1]
	v_pk_fma_f32 v[186:187], v[140:141], s[24:25], v[128:129] op_sel_hi:[1,0,1]
	v_cndmask_b32_e32 v190, v217, v190, vcc
	v_lshlrev_b32_e32 v210, 2, v190
	v_pk_mov_b32 v[190:191], v[186:187], v[188:189] op_sel:[1,0]
	v_mov_b32_e32 v196, v186
	v_mov_b32_e32 v197, v189
	v_pk_add_f32 v[190:191], v[190:191], v[196:197]
	v_pk_mov_b32 v[196:197], v[182:183], v[184:185] op_sel:[1,0]
	v_mov_b32_e32 v198, v182
	v_mov_b32_e32 v199, v185
	v_pk_add_f32 v[196:197], v[196:197], v[198:199]
	v_add_f32_e32 v190, v190, v191
	v_pk_add_f32 v[196:197], v[196:197], v[196:197] op_sel_hi:[0,1]
	v_add_f32_e32 v191, 0, v190
	v_cmp_gt_u32_e32 vcc, 16, v1
	s_waitcnt vmcnt(0)
	v_lshlrev_b32_e32 v130, 16, v126
	v_and_b32_e32 v131, 0xffff0000, v126
	v_pk_fma_f32 v[174:175], v[130:131], s[24:25], v[116:117] op_sel_hi:[1,0,1]
	v_or_b32_e32 v116, 16, v136
	v_ashrrev_i32_e32 v117, 31, v116
	v_lshlrev_b64 v[116:117], 12, v[116:117]
	v_lshl_add_u64 v[116:117], s[40:41], 0, v[116:117]
	v_lshl_add_u64 v[116:117], v[116:117], 0, v[172:173]
	global_load_dwordx4 v[168:171], v[116:117], off
	global_load_dwordx4 v[164:167], v[116:117], off offset:256
	v_or_b32_e32 v116, 32, v136
	v_ashrrev_i32_e32 v117, 31, v116
	v_lshlrev_b64 v[116:117], 12, v[116:117]
	v_lshl_add_u64 v[116:117], s[40:41], 0, v[116:117]
	v_lshl_add_u64 v[116:117], v[116:117], 0, v[172:173]
	global_load_dwordx4 v[160:163], v[116:117], off
	global_load_dwordx4 v[156:159], v[116:117], off offset:256
	v_or_b32_e32 v116, 48, v136
	v_ashrrev_i32_e32 v117, 31, v116
	v_lshlrev_b64 v[116:117], 12, v[116:117]
	v_lshl_add_u64 v[116:117], s[40:41], 0, v[116:117]
	v_lshl_add_u64 v[116:117], v[116:117], 0, v[172:173]
	global_load_dwordx4 v[152:155], v[116:117], off
	global_load_dwordx4 v[148:151], v[116:117], off offset:256
	v_add_u32_e32 v116, 0x80, v136
	v_ashrrev_i32_e32 v117, 31, v116
	v_lshlrev_b64 v[116:117], 12, v[116:117]
	v_lshl_add_u64 v[116:117], s[40:41], 0, v[116:117]
	v_lshl_add_u64 v[116:117], v[116:117], 0, v[172:173]
	global_load_dwordx4 v[144:147], v[116:117], off
	global_load_dwordx4 v[140:143], v[116:117], off offset:256
	v_add_u32_e32 v116, 0x90, v136
	v_ashrrev_i32_e32 v117, 31, v116
	v_lshlrev_b64 v[116:117], 12, v[116:117]
	v_lshl_add_u64 v[116:117], s[40:41], 0, v[116:117]
	v_lshlrev_b32_e32 v128, 16, v124
	v_and_b32_e32 v129, 0xffff0000, v124
	v_lshlrev_b32_e32 v124, 16, v125
	v_and_b32_e32 v125, 0xffff0000, v125
	v_lshlrev_b32_e32 v126, 16, v127
	v_and_b32_e32 v127, 0xffff0000, v127
	v_lshl_add_u64 v[116:117], v[116:117], 0, v[172:173]
	v_pk_fma_f32 v[178:179], v[128:129], s[24:25], v[120:121] op_sel_hi:[1,0,1]
	v_pk_fma_f32 v[180:181], v[124:125], s[24:25], v[122:123] op_sel_hi:[1,0,1]
	v_pk_fma_f32 v[176:177], v[126:127], s[24:25], v[118:119] op_sel_hi:[1,0,1]
	global_load_dwordx4 v[132:135], v[116:117], off
	global_load_dwordx4 v[124:127], v[116:117], off offset:256
	v_add_u32_e32 v116, 0xa0, v136
	v_add_u32_e32 v128, 0xb0, v136
	v_ashrrev_i32_e32 v117, 31, v116
	v_ashrrev_i32_e32 v129, 31, v128
	v_lshlrev_b64 v[116:117], 12, v[116:117]
	v_lshlrev_b64 v[128:129], 12, v[128:129]
	v_lshl_add_u64 v[116:117], s[40:41], 0, v[116:117]
	v_lshl_add_u64 v[128:129], s[40:41], 0, v[128:129]
	v_lshl_add_u64 v[116:117], v[116:117], 0, v[172:173]
	v_lshl_add_u64 v[128:129], v[128:129], 0, v[172:173]
	global_load_dwordx4 v[120:123], v[116:117], off
	s_nop 0
	global_load_dwordx4 v[116:119], v[116:117], off offset:256
	s_nop 0
	global_load_dwordx4 v[136:139], v[128:129], off
	s_nop 0
	global_load_dwordx4 v[128:131], v[128:129], off offset:256
	v_add_f32_e32 v199, v178, v179
	v_add_f32_e32 v201, v180, v181
	v_mov_b32_e32 v198, v174
	v_mov_b32_e32 v200, v175
	v_mov_b32_e32 v196, v176
	v_mov_b32_e32 v190, v177
	v_pk_add_f32 v[198:199], v[198:199], v[200:201]
	v_pk_add_f32 v[190:191], v[196:197], v[190:191]
	s_nop 0
	v_pk_add_f32 v[190:191], v[198:199], v[190:191]
	s_nop 0
	v_add_f32_e32 v190, v190, v191
	v_mov_b32_e32 v191, v190
	s_nop 1
	v_permlane16_swap_b32 v191, v190
	s_waitcnt lgkmcnt(0)
	v_add_f32_e32 v190, v190, v191
	v_mov_b32_e32 v191, v190
	s_nop 1
	v_permlane32_swap_b32 v191, v190
	s_waitcnt lgkmcnt(0)
;     __device__ __forceinline__ void run(const f32x4 (&v)[2][2][4][2], const Unit& u, int wr, int wc, int fr, int fq, LAS unsigned char* lds, int wid, int lane) const {
;     ...
;         for (int ai = 0; ai < 2; ++ai)
; #pragma unroll
;             for (int m = 0; m < 4; ++m) {
;                 float s = 0.f;
; #pragma unroll
;                 for (int bj = 0; bj < 2; ++bj)
; #pragma unroll
;                     for (int n = 0; n < 2; ++n) { const f32x4 x = v[ai][bj][m][n]; s += (x[0] + x[1]) + (x[2] + x[3]); }
;                 s += __shfl_xor(s, 16); s += __shfl_xor(s, 32);
;                 const float mw = s * (1.0f / 64.0f); float q = 0.f;
; #pragma unroll
;                 for (int bj = 0; bj < 2; ++bj)
; #pragma unroll
;                     for (int n = 0; n < 2; ++n) { const f32x4 d = v[ai][bj][m][n] - mw; q += (d[0] * d[0] + d[1] * d[1]) + (d[2] * d[2] + d[3] * d[3]); }
;                 q += __shfl_xor(q, 16); q += __shfl_xor(q, 32);
;                 if (fq == 0) Pt[(ai * HALF + wr * 64 + m * 16 + fr) * 4 + wc] = (f32x2v){mw, q};
;     __device__ __forceinline__ void fused(f32x4 (&acc)[2][2][4][2], const Unit& u, int wr, int wc, int fr, int fq, LAS unsigned char* lds, int wid, int lane) const {
;     ...
;                     const u32x4 hb = *(const u32x4*)(H + ro + bj * HALF);
;                     const f32x4 h0 = {bflo(hb.x), bfhi(hb.x), bflo(hb.y), bfhi(hb.y)}, h1 = {bflo(hb.z), bfhi(hb.z), bflo(hb.w), bfhi(hb.w)};
;                     acc[ai][bj][m][0] = h0 * ALPHA + acc[ai][bj][m][0]; acc[ai][bj][m][1] = h1 * ALPHA + acc[ai][bj][m][1];
	v_add_f32_e32 v190, v190, v191
	v_fmamk_f32 v196, v190, 0xbc800000, v189
	v_fmamk_f32 v198, v190, 0xbc800000, v187
	v_fmamk_f32 v191, v190, 0xbc800000, v188
	v_fmamk_f32 v197, v190, 0xbc800000, v186
	v_mul_f32_e32 v198, v198, v198
	v_mul_f32_e32 v196, v196, v196
	v_fmac_f32_e32 v198, v197, v197
	v_fmac_f32_e32 v196, v191, v191
	v_fmamk_f32 v197, v190, 0xbc800000, v185
	v_fmamk_f32 v199, v190, 0xbc800000, v183
	v_add_f32_e32 v191, v198, v196
	v_fmamk_f32 v196, v190, 0xbc800000, v184
	v_fmamk_f32 v198, v190, 0xbc800000, v182
	v_mul_f32_e32 v199, v199, v199
	v_mul_f32_e32 v197, v197, v197
	v_fmac_f32_e32 v199, v198, v198
	v_fmac_f32_e32 v197, v196, v196
	v_add_f32_e32 v196, v199, v197
	v_fmamk_f32 v197, v190, 0xbc800000, v181
	v_fmamk_f32 v199, v190, 0xbc800000, v179
	v_add_f32_e32 v191, v191, v196
	v_fmamk_f32 v196, v190, 0xbc800000, v180
	v_fmamk_f32 v198, v190, 0xbc800000, v178
	v_mul_f32_e32 v199, v199, v199
	v_mul_f32_e32 v197, v197, v197
	v_fmac_f32_e32 v199, v198, v198
	v_fmac_f32_e32 v197, v196, v196
	v_add_f32_e32 v196, v199, v197
	v_fmamk_f32 v197, v190, 0xbc800000, v177
	v_fmamk_f32 v199, v190, 0xbc800000, v175
	v_add_f32_e32 v191, v196, v191
	v_fmamk_f32 v196, v190, 0xbc800000, v176
	v_fmamk_f32 v198, v190, 0xbc800000, v174
	v_mul_f32_e32 v199, v199, v199
	v_mul_f32_e32 v197, v197, v197
	v_fmac_f32_e32 v199, v198, v198
	v_fmac_f32_e32 v197, v196, v196
	v_add_f32_e32 v196, v199, v197
	v_add_f32_e32 v191, v196, v191
	v_mov_b32_e32 v196, v191
	s_nop 1
	v_permlane16_swap_b32 v196, v191
	s_waitcnt lgkmcnt(0)
	v_add_f32_e32 v191, v191, v196
	v_mov_b32_e32 v211, v191
	s_nop 1
	v_permlane32_swap_b32 v211, v191
	s_and_saveexec_b64 s[40:41], vcc
	s_cbranch_execz .LBB0_783
	s_lshl_b32 s8, s5, 11
	s_add_i32 s8, s36, s8
	v_mul_f32_e32 v190, 0x3c800000, v190
	v_lshl_add_u32 v196, v194, 5, s8
	s_waitcnt lgkmcnt(0)
	v_add_f32_e32 v191, v191, v211
	ds_write_b64 v196, v[190:191]
.LBB0_783:
	s_or_b64 exec, exec, s[40:41]
	s_waitcnt vmcnt(13)
	v_lshlrev_b32_e32 v190, 16, v168
	v_and_b32_e32 v191, 0xffff0000, v168
	v_lshlrev_b32_e32 v196, 16, v169
	v_and_b32_e32 v197, 0xffff0000, v169
	v_lshlrev_b32_e32 v198, 16, v170
	v_and_b32_e32 v199, 0xffff0000, v170
	v_lshlrev_b32_e32 v200, 16, v171
	v_and_b32_e32 v201, 0xffff0000, v171
	v_pk_fma_f32 v[168:169], v[190:191], s[24:25], v[112:113] op_sel_hi:[1,0,1]
	v_pk_fma_f32 v[170:171], v[196:197], s[24:25], v[114:115] op_sel_hi:[1,0,1]
	v_pk_fma_f32 v[114:115], v[198:199], s[24:25], v[108:109] op_sel_hi:[1,0,1]
	v_pk_fma_f32 v[190:191], v[200:201], s[24:25], v[110:111] op_sel_hi:[1,0,1]
	s_waitcnt vmcnt(12)
	v_lshlrev_b32_e32 v108, 16, v164
	v_and_b32_e32 v109, 0xffff0000, v164
	v_lshlrev_b32_e32 v110, 16, v165
	v_and_b32_e32 v111, 0xffff0000, v165
	v_lshlrev_b32_e32 v112, 16, v166
	v_and_b32_e32 v113, 0xffff0000, v166
	v_pk_fma_f32 v[104:105], v[108:109], s[24:25], v[104:105] op_sel_hi:[1,0,1]
	v_pk_fma_f32 v[106:107], v[110:111], s[24:25], v[106:107] op_sel_hi:[1,0,1]
	v_pk_mov_b32 v[108:109], v[168:169], v[170:171] op_sel:[1,0]
	v_mov_b32_e32 v110, v168
	v_mov_b32_e32 v111, v171
	v_pk_fma_f32 v[100:101], v[112:113], s[24:25], v[100:101] op_sel_hi:[1,0,1]
	v_pk_add_f32 v[108:109], v[108:109], v[110:111]
	v_pk_mov_b32 v[110:111], v[114:115], v[190:191] op_sel:[1,0]
	v_mov_b32_e32 v112, v114
	v_mov_b32_e32 v113, v191
	v_lshlrev_b32_e32 v164, 16, v167
	v_and_b32_e32 v165, 0xffff0000, v167
	v_pk_add_f32 v[110:111], v[110:111], v[112:113]
	v_pk_fma_f32 v[102:103], v[164:165], s[24:25], v[102:103] op_sel_hi:[1,0,1]
	v_add_f32_e32 v108, v108, v109
	v_pk_add_f32 v[110:111], v[110:111], v[110:111] op_sel_hi:[0,1]
	v_add_f32_e32 v109, 0, v108
	v_add_f32_e32 v113, v104, v105
	v_add_f32_e32 v165, v106, v107
	v_mov_b32_e32 v112, v100
	v_mov_b32_e32 v164, v101
	v_mov_b32_e32 v110, v102
	v_mov_b32_e32 v108, v103
	v_pk_add_f32 v[112:113], v[112:113], v[164:165]
	v_pk_add_f32 v[108:109], v[110:111], v[108:109]
	s_nop 0
	v_pk_add_f32 v[108:109], v[112:113], v[108:109]
	s_nop 0
	v_add_f32_e32 v108, v108, v109
	v_mov_b32_e32 v109, v108
	s_nop 1
	v_permlane16_swap_b32 v109, v108
	s_waitcnt lgkmcnt(0)
	v_add_f32_e32 v108, v108, v109
	v_mov_b32_e32 v109, v108
	s_nop 1
	v_permlane32_swap_b32 v109, v108
	s_waitcnt lgkmcnt(0)
	v_add_f32_e32 v108, v108, v109
	v_fmamk_f32 v110, v108, 0xbc800000, v171
	v_fmamk_f32 v112, v108, 0xbc800000, v169
	v_fmamk_f32 v109, v108, 0xbc800000, v170
	v_fmamk_f32 v111, v108, 0xbc800000, v168
	v_mul_f32_e32 v112, v112, v112
	v_mul_f32_e32 v110, v110, v110
	v_fmac_f32_e32 v112, v111, v111
	v_fmac_f32_e32 v110, v109, v109
	v_fmamk_f32 v111, v108, 0xbc800000, v191
	v_fmamk_f32 v113, v108, 0xbc800000, v115
	v_add_f32_e32 v109, v112, v110
	v_fmamk_f32 v110, v108, 0xbc800000, v190
	v_fmamk_f32 v112, v108, 0xbc800000, v114
	v_mul_f32_e32 v113, v113, v113
	v_mul_f32_e32 v111, v111, v111
	v_fmac_f32_e32 v113, v112, v112
	v_fmac_f32_e32 v111, v110, v110
	v_add_f32_e32 v110, v113, v111
	v_fmamk_f32 v111, v108, 0xbc800000, v107
	v_fmamk_f32 v113, v108, 0xbc800000, v105
	v_add_f32_e32 v109, v109, v110
	v_fmamk_f32 v110, v108, 0xbc800000, v106
	v_fmamk_f32 v112, v108, 0xbc800000, v104
	v_mul_f32_e32 v113, v113, v113
	v_mul_f32_e32 v111, v111, v111
	v_fmac_f32_e32 v113, v112, v112
	v_fmac_f32_e32 v111, v110, v110
	v_add_f32_e32 v110, v113, v111
	v_fmamk_f32 v111, v108, 0xbc800000, v103
	v_fmamk_f32 v113, v108, 0xbc800000, v101
	v_add_f32_e32 v109, v110, v109
	v_fmamk_f32 v110, v108, 0xbc800000, v102
	v_fmamk_f32 v112, v108, 0xbc800000, v100
	v_mul_f32_e32 v113, v113, v113
	v_mul_f32_e32 v111, v111, v111
	v_fmac_f32_e32 v113, v112, v112
	v_fmac_f32_e32 v111, v110, v110
	v_add_f32_e32 v110, v113, v111
	v_add_f32_e32 v109, v110, v109
	v_mov_b32_e32 v110, v109
	s_nop 1
	v_permlane16_swap_b32 v110, v109
	s_waitcnt lgkmcnt(0)
	v_add_f32_e32 v109, v109, v110
	v_mov_b32_e32 v110, v109
	s_nop 1
	v_permlane32_swap_b32 v110, v109
	s_and_saveexec_b64 s[40:41], vcc
	v_readlane_b32 s88, v255, 26
	v_readlane_b32 s12, v255, 28
	v_readlane_b32 s14, v255, 30
	v_readlane_b32 s56, v255, 32
	v_readlane_b32 s84, v255, 34
	v_readlane_b32 s62, v255, 40
	v_readlane_b32 s86, v255, 24
	v_readlane_b32 s89, v255, 27
	v_readlane_b32 s13, v255, 29
	v_readlane_b32 s15, v255, 31
	v_readlane_b32 s57, v255, 33
	v_readlane_b32 s85, v255, 35
	v_readlane_b32 s63, v255, 41
	v_readlane_b32 s87, v255, 25
	s_cbranch_execz .LBB0_785
	s_lshl_b32 s8, s5, 11
	s_add_i32 s8, s36, s8
	v_mul_f32_e32 v108, 0x3c800000, v108
	v_lshl_add_u32 v111, v194, 5, s8
	s_waitcnt lgkmcnt(0)
	v_add_f32_e32 v109, v109, v110
	ds_write_b64 v111, v[108:109] offset:512
;     __device__ __forceinline__ void run(const f32x4 (&v)[2][2][4][2], const Unit& u, int wr, int wc, int fr, int fq, LAS unsigned char* lds, int wid, int lane) const {
;     ...
;         for (int ai = 0; ai < 2; ++ai)
; #pragma unroll
;             for (int m = 0; m < 4; ++m) {
;                 float s = 0.f;
; #pragma unroll
;                 for (int bj = 0; bj < 2; ++bj)
; #pragma unroll
;                     for (int n = 0; n < 2; ++n) { const f32x4 x = v[ai][bj][m][n]; s += (x[0] + x[1]) + (x[2] + x[3]); }
;                 s += __shfl_xor(s, 16); s += __shfl_xor(s, 32);
;                 const float mw = s * (1.0f / 64.0f); float q = 0.f;
; #pragma unroll
;                 for (int bj = 0; bj < 2; ++bj)
; #pragma unroll
;                     for (int n = 0; n < 2; ++n) { const f32x4 d = v[ai][bj][m][n] - mw; q += (d[0] * d[0] + d[1] * d[1]) + (d[2] * d[2] + d[3] * d[3]); }
;                 q += __shfl_xor(q, 16); q += __shfl_xor(q, 32);
;                 if (fq == 0) Pt[(ai * HALF + wr * 64 + m * 16 + fr) * 4 + wc] = (f32x2v){mw, q};
;     __device__ __forceinline__ void fused(f32x4 (&acc)[2][2][4][2], const Unit& u, int wr, int wc, int fr, int fq, LAS unsigned char* lds, int wid, int lane) const {
;     ...
;                     const u32x4 hb = *(const u32x4*)(H + ro + bj * HALF);
;                     const f32x4 h0 = {bflo(hb.x), bfhi(hb.x), bflo(hb.y), bfhi(hb.y)}, h1 = {bflo(hb.z), bfhi(hb.z), bflo(hb.w), bfhi(hb.w)};
;                     acc[ai][bj][m][0] = h0 * ALPHA + acc[ai][bj][m][0]; acc[ai][bj][m][1] = h1 * ALPHA + acc[ai][bj][m][1];
.LBB0_785:
	s_or_b64 exec, exec, s[40:41]
	s_waitcnt vmcnt(11)
	v_lshlrev_b32_e32 v108, 16, v160
	v_and_b32_e32 v109, 0xffff0000, v160
	s_waitcnt lgkmcnt(0)
	v_lshlrev_b32_e32 v110, 16, v161
	v_and_b32_e32 v111, 0xffff0000, v161
	v_lshlrev_b32_e32 v112, 16, v162
	v_and_b32_e32 v113, 0xffff0000, v162
	v_lshlrev_b32_e32 v160, 16, v163
	v_and_b32_e32 v161, 0xffff0000, v163
	v_pk_fma_f32 v[96:97], v[108:109], s[24:25], v[96:97] op_sel_hi:[1,0,1]
	v_pk_fma_f32 v[98:99], v[110:111], s[24:25], v[98:99] op_sel_hi:[1,0,1]
	s_waitcnt vmcnt(10)
	v_lshlrev_b32_e32 v108, 16, v156
	v_and_b32_e32 v109, 0xffff0000, v156
	v_lshlrev_b32_e32 v110, 16, v157
	v_and_b32_e32 v111, 0xffff0000, v157
	v_pk_fma_f32 v[92:93], v[112:113], s[24:25], v[92:93] op_sel_hi:[1,0,1]
	v_pk_fma_f32 v[94:95], v[160:161], s[24:25], v[94:95] op_sel_hi:[1,0,1]
	v_lshlrev_b32_e32 v112, 16, v158
	v_and_b32_e32 v113, 0xffff0000, v158
	v_pk_fma_f32 v[88:89], v[108:109], s[24:25], v[88:89] op_sel_hi:[1,0,1]
	v_pk_fma_f32 v[90:91], v[110:111], s[24:25], v[90:91] op_sel_hi:[1,0,1]
	v_pk_mov_b32 v[108:109], v[96:97], v[98:99] op_sel:[1,0]
	v_mov_b32_e32 v110, v96
	v_mov_b32_e32 v111, v99
	v_pk_fma_f32 v[84:85], v[112:113], s[24:25], v[84:85] op_sel_hi:[1,0,1]
	v_pk_add_f32 v[108:109], v[108:109], v[110:111]
	v_pk_mov_b32 v[110:111], v[92:93], v[94:95] op_sel:[1,0]
	v_mov_b32_e32 v112, v92
	v_mov_b32_e32 v113, v95
	v_lshlrev_b32_e32 v156, 16, v159
	v_and_b32_e32 v157, 0xffff0000, v159
	v_pk_add_f32 v[110:111], v[110:111], v[112:113]
	v_pk_fma_f32 v[86:87], v[156:157], s[24:25], v[86:87] op_sel_hi:[1,0,1]
	v_add_f32_e32 v108, v108, v109
	v_pk_add_f32 v[110:111], v[110:111], v[110:111] op_sel_hi:[0,1]
	v_add_f32_e32 v109, 0, v108
	v_add_f32_e32 v113, v88, v89
	v_add_f32_e32 v157, v90, v91
	v_mov_b32_e32 v112, v84
	v_mov_b32_e32 v156, v85
	v_mov_b32_e32 v110, v86
	v_mov_b32_e32 v108, v87
	v_pk_add_f32 v[112:113], v[112:113], v[156:157]
	v_pk_add_f32 v[108:109], v[110:111], v[108:109]
	s_nop 0
	v_pk_add_f32 v[108:109], v[112:113], v[108:109]
	s_nop 0
	v_add_f32_e32 v108, v108, v109
	v_mov_b32_e32 v109, v108
	s_nop 1
	v_permlane16_swap_b32 v109, v108
	s_waitcnt lgkmcnt(0)
	v_add_f32_e32 v108, v108, v109
	v_mov_b32_e32 v109, v108
	s_nop 1
	v_permlane32_swap_b32 v109, v108
	s_waitcnt lgkmcnt(0)
	v_add_f32_e32 v108, v108, v109
	v_fmamk_f32 v110, v108, 0xbc800000, v99
	v_fmamk_f32 v112, v108, 0xbc800000, v97
	v_fmamk_f32 v109, v108, 0xbc800000, v98
	v_fmamk_f32 v111, v108, 0xbc800000, v96
	v_mul_f32_e32 v112, v112, v112
	v_mul_f32_e32 v110, v110, v110
	v_fmac_f32_e32 v112, v111, v111
	v_fmac_f32_e32 v110, v109, v109
	v_fmamk_f32 v111, v108, 0xbc800000, v95
	v_fmamk_f32 v113, v108, 0xbc800000, v93
	v_add_f32_e32 v109, v112, v110
	v_fmamk_f32 v110, v108, 0xbc800000, v94
	v_fmamk_f32 v112, v108, 0xbc800000, v92
	v_mul_f32_e32 v113, v113, v113
	v_mul_f32_e32 v111, v111, v111
	v_fmac_f32_e32 v113, v112, v112
	v_fmac_f32_e32 v111, v110, v110
	v_add_f32_e32 v110, v113, v111
	v_fmamk_f32 v111, v108, 0xbc800000, v91
	v_fmamk_f32 v113, v108, 0xbc800000, v89
	v_add_f32_e32 v109, v109, v110
	v_fmamk_f32 v110, v108, 0xbc800000, v90
	v_fmamk_f32 v112, v108, 0xbc800000, v88
	v_mul_f32_e32 v113, v113, v113
	v_mul_f32_e32 v111, v111, v111
	v_fmac_f32_e32 v113, v112, v112
	v_fmac_f32_e32 v111, v110, v110
	v_add_f32_e32 v110, v113, v111
	v_fmamk_f32 v111, v108, 0xbc800000, v87
	v_fmamk_f32 v113, v108, 0xbc800000, v85
	v_add_f32_e32 v109, v110, v109
	v_fmamk_f32 v110, v108, 0xbc800000, v86
	v_fmamk_f32 v112, v108, 0xbc800000, v84
	v_mul_f32_e32 v113, v113, v113
	v_mul_f32_e32 v111, v111, v111
	v_fmac_f32_e32 v113, v112, v112
	v_fmac_f32_e32 v111, v110, v110
	v_add_f32_e32 v110, v113, v111
	v_add_f32_e32 v109, v110, v109
	v_mov_b32_e32 v110, v109
	s_nop 1
	v_permlane16_swap_b32 v110, v109
	s_waitcnt lgkmcnt(0)
	v_add_f32_e32 v109, v109, v110
	v_mov_b32_e32 v110, v109
	s_nop 1
	v_permlane32_swap_b32 v110, v109
	s_and_saveexec_b64 s[40:41], vcc
	s_cbranch_execz .LBB0_787
	s_lshl_b32 s8, s5, 11
	s_add_i32 s8, s36, s8
	v_mul_f32_e32 v108, 0x3c800000, v108
	v_lshl_add_u32 v111, v194, 5, s8
	s_waitcnt lgkmcnt(0)
	v_add_f32_e32 v109, v109, v110
	ds_write_b64 v111, v[108:109] offset:1024
.LBB0_787:
	s_or_b64 exec, exec, s[40:41]
	s_waitcnt vmcnt(9)
	v_lshlrev_b32_e32 v108, 16, v152
	v_and_b32_e32 v109, 0xffff0000, v152
	s_waitcnt lgkmcnt(0)
	v_lshlrev_b32_e32 v110, 16, v153
	v_and_b32_e32 v111, 0xffff0000, v153
	v_lshlrev_b32_e32 v112, 16, v154
	v_and_b32_e32 v113, 0xffff0000, v154
	v_lshlrev_b32_e32 v152, 16, v155
	v_and_b32_e32 v153, 0xffff0000, v155
	v_pk_fma_f32 v[80:81], v[108:109], s[24:25], v[80:81] op_sel_hi:[1,0,1]
	v_pk_fma_f32 v[82:83], v[110:111], s[24:25], v[82:83] op_sel_hi:[1,0,1]
	s_waitcnt vmcnt(8)
	v_lshlrev_b32_e32 v108, 16, v148
	v_and_b32_e32 v109, 0xffff0000, v148
	v_lshlrev_b32_e32 v110, 16, v149
	v_and_b32_e32 v111, 0xffff0000, v149
	v_pk_fma_f32 v[76:77], v[112:113], s[24:25], v[76:77] op_sel_hi:[1,0,1]
	v_pk_fma_f32 v[78:79], v[152:153], s[24:25], v[78:79] op_sel_hi:[1,0,1]
	v_lshlrev_b32_e32 v112, 16, v150
	v_and_b32_e32 v113, 0xffff0000, v150
	v_pk_fma_f32 v[72:73], v[108:109], s[24:25], v[72:73] op_sel_hi:[1,0,1]
	v_pk_fma_f32 v[74:75], v[110:111], s[24:25], v[74:75] op_sel_hi:[1,0,1]
	v_pk_mov_b32 v[108:109], v[80:81], v[82:83] op_sel:[1,0]
	v_mov_b32_e32 v110, v80
	v_mov_b32_e32 v111, v83
	v_pk_fma_f32 v[68:69], v[112:113], s[24:25], v[68:69] op_sel_hi:[1,0,1]
	v_pk_add_f32 v[108:109], v[108:109], v[110:111]
	v_pk_mov_b32 v[110:111], v[76:77], v[78:79] op_sel:[1,0]
	v_mov_b32_e32 v112, v76
	v_mov_b32_e32 v113, v79
	v_lshlrev_b32_e32 v148, 16, v151
	v_and_b32_e32 v149, 0xffff0000, v151
	v_pk_add_f32 v[110:111], v[110:111], v[112:113]
	v_pk_fma_f32 v[70:71], v[148:149], s[24:25], v[70:71] op_sel_hi:[1,0,1]
	v_add_f32_e32 v108, v108, v109
	v_pk_add_f32 v[110:111], v[110:111], v[110:111] op_sel_hi:[0,1]
	v_add_f32_e32 v109, 0, v108
	v_add_f32_e32 v113, v72, v73
	v_add_f32_e32 v149, v74, v75
	v_mov_b32_e32 v112, v68
	v_mov_b32_e32 v148, v69
	v_mov_b32_e32 v110, v70
	v_mov_b32_e32 v108, v71
	v_pk_add_f32 v[112:113], v[112:113], v[148:149]
	v_pk_add_f32 v[108:109], v[110:111], v[108:109]
	s_nop 0
	v_pk_add_f32 v[108:109], v[112:113], v[108:109]
	s_nop 0
	v_add_f32_e32 v108, v108, v109
	v_mov_b32_e32 v109, v108
	s_nop 1
	v_permlane16_swap_b32 v109, v108
	s_waitcnt lgkmcnt(0)
;     __device__ __forceinline__ void run(const f32x4 (&v)[2][2][4][2], const Unit& u, int wr, int wc, int fr, int fq, LAS unsigned char* lds, int wid, int lane) const {
;     ...
;         for (int ai = 0; ai < 2; ++ai)
; #pragma unroll
;             for (int m = 0; m < 4; ++m) {
;                 float s = 0.f;
; #pragma unroll
;                 for (int bj = 0; bj < 2; ++bj)
; #pragma unroll
;                     for (int n = 0; n < 2; ++n) { const f32x4 x = v[ai][bj][m][n]; s += (x[0] + x[1]) + (x[2] + x[3]); }
;                 s += __shfl_xor(s, 16); s += __shfl_xor(s, 32);
;                 const float mw = s * (1.0f / 64.0f); float q = 0.f;
; #pragma unroll
;                 for (int bj = 0; bj < 2; ++bj)
; #pragma unroll
;                     for (int n = 0; n < 2; ++n) { const f32x4 d = v[ai][bj][m][n] - mw; q += (d[0] * d[0] + d[1] * d[1]) + (d[2] * d[2] + d[3] * d[3]); }
;                 q += __shfl_xor(q, 16); q += __shfl_xor(q, 32);
;                 if (fq == 0) Pt[(ai * HALF + wr * 64 + m * 16 + fr) * 4 + wc] = (f32x2v){mw, q};
;     __device__ __forceinline__ void fused(f32x4 (&acc)[2][2][4][2], const Unit& u, int wr, int wc, int fr, int fq, LAS unsigned char* lds, int wid, int lane) const {
;     ...
;                     const u32x4 hb = *(const u32x4*)(H + ro + bj * HALF);
;                     const f32x4 h0 = {bflo(hb.x), bfhi(hb.x), bflo(hb.y), bfhi(hb.y)}, h1 = {bflo(hb.z), bfhi(hb.z), bflo(hb.w), bfhi(hb.w)};
;                     acc[ai][bj][m][0] = h0 * ALPHA + acc[ai][bj][m][0]; acc[ai][bj][m][1] = h1 * ALPHA + acc[ai][bj][m][1];
	v_add_f32_e32 v108, v108, v109
	v_mov_b32_e32 v109, v108
	s_nop 1
	v_permlane32_swap_b32 v109, v108
	s_waitcnt lgkmcnt(0)
	v_add_f32_e32 v108, v108, v109
	v_fmamk_f32 v110, v108, 0xbc800000, v83
	v_fmamk_f32 v112, v108, 0xbc800000, v81
	v_fmamk_f32 v109, v108, 0xbc800000, v82
	v_fmamk_f32 v111, v108, 0xbc800000, v80
	v_mul_f32_e32 v112, v112, v112
	v_mul_f32_e32 v110, v110, v110
	v_fmac_f32_e32 v112, v111, v111
	v_fmac_f32_e32 v110, v109, v109
	v_fmamk_f32 v111, v108, 0xbc800000, v79
	v_fmamk_f32 v113, v108, 0xbc800000, v77
	v_add_f32_e32 v109, v112, v110
	v_fmamk_f32 v110, v108, 0xbc800000, v78
	v_fmamk_f32 v112, v108, 0xbc800000, v76
	v_mul_f32_e32 v113, v113, v113
	v_mul_f32_e32 v111, v111, v111
	v_fmac_f32_e32 v113, v112, v112
	v_fmac_f32_e32 v111, v110, v110
	v_add_f32_e32 v110, v113, v111
	v_fmamk_f32 v111, v108, 0xbc800000, v75
	v_fmamk_f32 v113, v108, 0xbc800000, v73
	v_add_f32_e32 v109, v109, v110
	v_fmamk_f32 v110, v108, 0xbc800000, v74
	v_fmamk_f32 v112, v108, 0xbc800000, v72
	v_mul_f32_e32 v113, v113, v113
	v_mul_f32_e32 v111, v111, v111
	v_fmac_f32_e32 v113, v112, v112
	v_fmac_f32_e32 v111, v110, v110
	v_add_f32_e32 v110, v113, v111
	v_fmamk_f32 v111, v108, 0xbc800000, v71
	v_fmamk_f32 v113, v108, 0xbc800000, v69
	v_add_f32_e32 v109, v110, v109
	v_fmamk_f32 v110, v108, 0xbc800000, v70
	v_fmamk_f32 v112, v108, 0xbc800000, v68
	v_mul_f32_e32 v113, v113, v113
	v_mul_f32_e32 v111, v111, v111
	v_fmac_f32_e32 v113, v112, v112
	v_fmac_f32_e32 v111, v110, v110
	v_add_f32_e32 v110, v113, v111
	v_add_f32_e32 v109, v110, v109
	v_mov_b32_e32 v110, v109
	s_nop 1
	v_permlane16_swap_b32 v110, v109
	s_waitcnt lgkmcnt(0)
	v_add_f32_e32 v109, v109, v110
	v_mov_b32_e32 v110, v109
	s_nop 1
	v_permlane32_swap_b32 v110, v109
	s_and_saveexec_b64 s[40:41], vcc
	s_cbranch_execz .LBB0_789
	s_lshl_b32 s8, s5, 11
	s_add_i32 s8, s36, s8
	v_mul_f32_e32 v108, 0x3c800000, v108
	v_lshl_add_u32 v111, v194, 5, s8
	s_waitcnt lgkmcnt(0)
	v_add_f32_e32 v109, v109, v110
	ds_write_b64 v111, v[108:109] offset:1536
.LBB0_789:
	s_or_b64 exec, exec, s[40:41]
	s_waitcnt vmcnt(7)
	v_lshlrev_b32_e32 v108, 16, v144
	v_and_b32_e32 v109, 0xffff0000, v144
	s_waitcnt lgkmcnt(0)
	v_lshlrev_b32_e32 v110, 16, v145
	v_and_b32_e32 v111, 0xffff0000, v145
	v_lshlrev_b32_e32 v112, 16, v146
	v_and_b32_e32 v113, 0xffff0000, v146
	v_lshlrev_b32_e32 v144, 16, v147
	v_and_b32_e32 v145, 0xffff0000, v147
	v_pk_fma_f32 v[64:65], v[108:109], s[24:25], v[64:65] op_sel_hi:[1,0,1]
	v_pk_fma_f32 v[66:67], v[110:111], s[24:25], v[66:67] op_sel_hi:[1,0,1]
	s_waitcnt vmcnt(6)
	v_lshlrev_b32_e32 v108, 16, v140
	v_and_b32_e32 v109, 0xffff0000, v140
	v_lshlrev_b32_e32 v110, 16, v141
	v_and_b32_e32 v111, 0xffff0000, v141
	v_pk_fma_f32 v[60:61], v[112:113], s[24:25], v[60:61] op_sel_hi:[1,0,1]
	v_pk_fma_f32 v[62:63], v[144:145], s[24:25], v[62:63] op_sel_hi:[1,0,1]
	v_lshlrev_b32_e32 v112, 16, v142
	v_and_b32_e32 v113, 0xffff0000, v142
	v_pk_fma_f32 v[56:57], v[108:109], s[24:25], v[56:57] op_sel_hi:[1,0,1]
	v_pk_fma_f32 v[58:59], v[110:111], s[24:25], v[58:59] op_sel_hi:[1,0,1]
	v_pk_mov_b32 v[108:109], v[64:65], v[66:67] op_sel:[1,0]
	v_mov_b32_e32 v110, v64
	v_mov_b32_e32 v111, v67
	v_pk_fma_f32 v[52:53], v[112:113], s[24:25], v[52:53] op_sel_hi:[1,0,1]
	v_pk_add_f32 v[108:109], v[108:109], v[110:111]
	v_pk_mov_b32 v[110:111], v[60:61], v[62:63] op_sel:[1,0]
	v_mov_b32_e32 v112, v60
	v_mov_b32_e32 v113, v63
	v_lshlrev_b32_e32 v140, 16, v143
	v_and_b32_e32 v141, 0xffff0000, v143
	v_pk_add_f32 v[110:111], v[110:111], v[112:113]
	v_pk_fma_f32 v[54:55], v[140:141], s[24:25], v[54:55] op_sel_hi:[1,0,1]
	v_add_f32_e32 v108, v108, v109
	v_pk_add_f32 v[110:111], v[110:111], v[110:111] op_sel_hi:[0,1]
	v_add_f32_e32 v109, 0, v108
	v_add_f32_e32 v113, v56, v57
	v_add_f32_e32 v141, v58, v59
	v_mov_b32_e32 v112, v52
	v_mov_b32_e32 v140, v53
	v_mov_b32_e32 v110, v54
	v_mov_b32_e32 v108, v55
	v_pk_add_f32 v[112:113], v[112:113], v[140:141]
	v_pk_add_f32 v[108:109], v[110:111], v[108:109]
	s_nop 0
	v_pk_add_f32 v[108:109], v[112:113], v[108:109]
	s_nop 0
	v_add_f32_e32 v108, v108, v109
	v_mov_b32_e32 v109, v108
	s_nop 1
	v_permlane16_swap_b32 v109, v108
	s_waitcnt lgkmcnt(0)
	v_add_f32_e32 v108, v108, v109
	v_mov_b32_e32 v109, v108
	s_nop 1
	v_permlane32_swap_b32 v109, v108
	s_waitcnt lgkmcnt(0)
	v_add_f32_e32 v108, v108, v109
	v_fmamk_f32 v110, v108, 0xbc800000, v67
	v_fmamk_f32 v112, v108, 0xbc800000, v65
	v_fmamk_f32 v109, v108, 0xbc800000, v66
	v_fmamk_f32 v111, v108, 0xbc800000, v64
	v_mul_f32_e32 v112, v112, v112
	v_mul_f32_e32 v110, v110, v110
	v_fmac_f32_e32 v112, v111, v111
	v_fmac_f32_e32 v110, v109, v109
	v_fmamk_f32 v111, v108, 0xbc800000, v63
	v_fmamk_f32 v113, v108, 0xbc800000, v61
	v_add_f32_e32 v109, v112, v110
	v_fmamk_f32 v110, v108, 0xbc800000, v62
	v_fmamk_f32 v112, v108, 0xbc800000, v60
	v_mul_f32_e32 v113, v113, v113
	v_mul_f32_e32 v111, v111, v111
	v_fmac_f32_e32 v113, v112, v112
	v_fmac_f32_e32 v111, v110, v110
	v_add_f32_e32 v110, v113, v111
	v_fmamk_f32 v111, v108, 0xbc800000, v59
	v_fmamk_f32 v113, v108, 0xbc800000, v57
	v_add_f32_e32 v109, v109, v110
	v_fmamk_f32 v110, v108, 0xbc800000, v58
	v_fmamk_f32 v112, v108, 0xbc800000, v56
	v_mul_f32_e32 v113, v113, v113
	v_mul_f32_e32 v111, v111, v111
	v_fmac_f32_e32 v113, v112, v112
	v_fmac_f32_e32 v111, v110, v110
	v_add_f32_e32 v110, v113, v111
	v_fmamk_f32 v111, v108, 0xbc800000, v55
	v_fmamk_f32 v113, v108, 0xbc800000, v53
	v_add_f32_e32 v109, v110, v109
	v_fmamk_f32 v110, v108, 0xbc800000, v54
	v_fmamk_f32 v112, v108, 0xbc800000, v52
	v_mul_f32_e32 v113, v113, v113
	v_mul_f32_e32 v111, v111, v111
	v_fmac_f32_e32 v113, v112, v112
	v_fmac_f32_e32 v111, v110, v110
	v_add_f32_e32 v110, v113, v111
	v_add_f32_e32 v109, v110, v109
	v_mov_b32_e32 v110, v109
	s_nop 1
	v_permlane16_swap_b32 v110, v109
	s_waitcnt lgkmcnt(0)
	v_add_f32_e32 v109, v109, v110
	v_mov_b32_e32 v110, v109
	s_nop 1
	v_permlane32_swap_b32 v110, v109
	s_and_saveexec_b64 s[40:41], vcc
	s_cbranch_execz .LBB0_791
	s_lshl_b32 s8, s5, 11
	s_add_i32 s8, s36, s8
	v_mul_f32_e32 v108, 0x3c800000, v108
	v_lshl_add_u32 v111, v194, 5, s8
	s_waitcnt lgkmcnt(0)
	v_add_f32_e32 v109, v109, v110
	ds_write_b64 v111, v[108:109] offset:4096
;     __device__ __forceinline__ void run(const f32x4 (&v)[2][2][4][2], const Unit& u, int wr, int wc, int fr, int fq, LAS unsigned char* lds, int wid, int lane) const {
;     ...
;         for (int ai = 0; ai < 2; ++ai)
; #pragma unroll
;             for (int m = 0; m < 4; ++m) {
;                 float s = 0.f;
; #pragma unroll
;                 for (int bj = 0; bj < 2; ++bj)
; #pragma unroll
;                     for (int n = 0; n < 2; ++n) { const f32x4 x = v[ai][bj][m][n]; s += (x[0] + x[1]) + (x[2] + x[3]); }
;                 s += __shfl_xor(s, 16); s += __shfl_xor(s, 32);
;                 const float mw = s * (1.0f / 64.0f); float q = 0.f;
; #pragma unroll
;                 for (int bj = 0; bj < 2; ++bj)
; #pragma unroll
;                     for (int n = 0; n < 2; ++n) { const f32x4 d = v[ai][bj][m][n] - mw; q += (d[0] * d[0] + d[1] * d[1]) + (d[2] * d[2] + d[3] * d[3]); }
;                 q += __shfl_xor(q, 16); q += __shfl_xor(q, 32);
;                 if (fq == 0) Pt[(ai * HALF + wr * 64 + m * 16 + fr) * 4 + wc] = (f32x2v){mw, q};
;     __device__ __forceinline__ void fused(f32x4 (&acc)[2][2][4][2], const Unit& u, int wr, int wc, int fr, int fq, LAS unsigned char* lds, int wid, int lane) const {
;     ...
;                     const u32x4 hb = *(const u32x4*)(H + ro + bj * HALF);
;                     const f32x4 h0 = {bflo(hb.x), bfhi(hb.x), bflo(hb.y), bfhi(hb.y)}, h1 = {bflo(hb.z), bfhi(hb.z), bflo(hb.w), bfhi(hb.w)};
;                     acc[ai][bj][m][0] = h0 * ALPHA + acc[ai][bj][m][0]; acc[ai][bj][m][1] = h1 * ALPHA + acc[ai][bj][m][1];
.LBB0_791:
	s_or_b64 exec, exec, s[40:41]
	s_waitcnt vmcnt(5)
	v_lshlrev_b32_e32 v108, 16, v132
	v_and_b32_e32 v109, 0xffff0000, v132
	s_waitcnt lgkmcnt(0)
	v_lshlrev_b32_e32 v110, 16, v133
	v_and_b32_e32 v111, 0xffff0000, v133
	v_lshlrev_b32_e32 v112, 16, v134
	v_and_b32_e32 v113, 0xffff0000, v134
	v_lshlrev_b32_e32 v140, 16, v135
	v_and_b32_e32 v141, 0xffff0000, v135
	v_pk_fma_f32 v[134:135], v[108:109], s[24:25], v[48:49] op_sel_hi:[1,0,1]
	v_pk_fma_f32 v[142:143], v[110:111], s[24:25], v[50:51] op_sel_hi:[1,0,1]
	v_pk_fma_f32 v[132:133], v[112:113], s[24:25], v[44:45] op_sel_hi:[1,0,1]
	v_pk_fma_f32 v[140:141], v[140:141], s[24:25], v[46:47] op_sel_hi:[1,0,1]
	s_waitcnt vmcnt(4)
	v_lshlrev_b32_e32 v44, 16, v124
	v_and_b32_e32 v45, 0xffff0000, v124
	v_lshlrev_b32_e32 v46, 16, v125
	v_and_b32_e32 v47, 0xffff0000, v125
	v_lshlrev_b32_e32 v48, 16, v126
	v_and_b32_e32 v49, 0xffff0000, v126
	v_pk_fma_f32 v[40:41], v[44:45], s[24:25], v[40:41] op_sel_hi:[1,0,1]
	v_pk_fma_f32 v[42:43], v[46:47], s[24:25], v[42:43] op_sel_hi:[1,0,1]
	v_pk_mov_b32 v[44:45], v[134:135], v[142:143] op_sel:[1,0]
	v_mov_b32_e32 v46, v134
	v_mov_b32_e32 v47, v143
	v_pk_fma_f32 v[36:37], v[48:49], s[24:25], v[36:37] op_sel_hi:[1,0,1]
	v_pk_add_f32 v[44:45], v[44:45], v[46:47]
	v_pk_mov_b32 v[46:47], v[132:133], v[140:141] op_sel:[1,0]
	v_mov_b32_e32 v48, v132
	v_mov_b32_e32 v49, v141
	v_lshlrev_b32_e32 v50, 16, v127
	v_and_b32_e32 v51, 0xffff0000, v127
	v_pk_add_f32 v[46:47], v[46:47], v[48:49]
	v_pk_fma_f32 v[38:39], v[50:51], s[24:25], v[38:39] op_sel_hi:[1,0,1]
	v_add_f32_e32 v44, v44, v45
	v_pk_add_f32 v[46:47], v[46:47], v[46:47] op_sel_hi:[0,1]
	v_add_f32_e32 v45, 0, v44
	v_add_f32_e32 v49, v40, v41
	v_add_f32_e32 v51, v42, v43
	v_mov_b32_e32 v48, v36
	v_mov_b32_e32 v50, v37
	v_mov_b32_e32 v46, v38
	v_mov_b32_e32 v44, v39
	v_pk_add_f32 v[48:49], v[48:49], v[50:51]
	v_pk_add_f32 v[44:45], v[46:47], v[44:45]
	s_nop 0
	v_pk_add_f32 v[44:45], v[48:49], v[44:45]
	s_nop 0
	v_add_f32_e32 v44, v44, v45
	v_mov_b32_e32 v45, v44
	s_nop 1
	v_permlane16_swap_b32 v45, v44
	s_waitcnt lgkmcnt(0)
	v_add_f32_e32 v44, v44, v45
	v_mov_b32_e32 v45, v44
	s_nop 1
	v_permlane32_swap_b32 v45, v44
	s_waitcnt lgkmcnt(0)
	v_add_f32_e32 v44, v44, v45
	v_fmamk_f32 v46, v44, 0xbc800000, v143
	v_fmamk_f32 v48, v44, 0xbc800000, v135
	v_fmamk_f32 v45, v44, 0xbc800000, v142
	v_fmamk_f32 v47, v44, 0xbc800000, v134
	v_mul_f32_e32 v48, v48, v48
	v_mul_f32_e32 v46, v46, v46
	v_fmac_f32_e32 v48, v47, v47
	v_fmac_f32_e32 v46, v45, v45
	v_fmamk_f32 v47, v44, 0xbc800000, v141
	v_fmamk_f32 v49, v44, 0xbc800000, v133
	v_add_f32_e32 v45, v48, v46
	v_fmamk_f32 v46, v44, 0xbc800000, v140
	v_fmamk_f32 v48, v44, 0xbc800000, v132
	v_mul_f32_e32 v49, v49, v49
	v_mul_f32_e32 v47, v47, v47
	v_fmac_f32_e32 v49, v48, v48
	v_fmac_f32_e32 v47, v46, v46
	v_add_f32_e32 v46, v49, v47
	v_fmamk_f32 v47, v44, 0xbc800000, v43
	v_fmamk_f32 v49, v44, 0xbc800000, v41
	v_add_f32_e32 v45, v45, v46
	v_fmamk_f32 v46, v44, 0xbc800000, v42
	v_fmamk_f32 v48, v44, 0xbc800000, v40
	v_mul_f32_e32 v49, v49, v49
	v_mul_f32_e32 v47, v47, v47
	v_fmac_f32_e32 v49, v48, v48
	v_fmac_f32_e32 v47, v46, v46
	v_add_f32_e32 v46, v49, v47
	v_fmamk_f32 v47, v44, 0xbc800000, v39
	v_fmamk_f32 v49, v44, 0xbc800000, v37
	v_add_f32_e32 v45, v46, v45
	v_fmamk_f32 v46, v44, 0xbc800000, v38
	v_fmamk_f32 v48, v44, 0xbc800000, v36
	v_mul_f32_e32 v49, v49, v49
	v_mul_f32_e32 v47, v47, v47
	v_fmac_f32_e32 v49, v48, v48
	v_fmac_f32_e32 v47, v46, v46
	v_add_f32_e32 v46, v49, v47
	v_add_f32_e32 v45, v46, v45
	v_mov_b32_e32 v46, v45
	s_nop 1
	v_permlane16_swap_b32 v46, v45
	s_waitcnt lgkmcnt(0)
	v_add_f32_e32 v45, v45, v46
	v_mov_b32_e32 v46, v45
	s_nop 1
	v_permlane32_swap_b32 v46, v45
	s_and_saveexec_b64 s[40:41], vcc
	s_cbranch_execz .LBB0_793
	s_lshl_b32 s8, s5, 11
	s_add_i32 s8, s36, s8
	v_mul_f32_e32 v44, 0x3c800000, v44
	v_lshl_add_u32 v47, v194, 5, s8
	s_waitcnt lgkmcnt(0)
	v_add_f32_e32 v45, v45, v46
	ds_write_b64 v47, v[44:45] offset:4608
.LBB0_793:
	s_or_b64 exec, exec, s[40:41]
	s_waitcnt vmcnt(3)
	v_lshlrev_b32_e32 v44, 16, v120
	v_and_b32_e32 v45, 0xffff0000, v120
	s_waitcnt lgkmcnt(0)
	v_lshlrev_b32_e32 v46, 16, v121
	v_and_b32_e32 v47, 0xffff0000, v121
	v_lshlrev_b32_e32 v48, 16, v122
	v_and_b32_e32 v49, 0xffff0000, v122
	v_lshlrev_b32_e32 v50, 16, v123
	v_and_b32_e32 v51, 0xffff0000, v123
	v_pk_fma_f32 v[122:123], v[44:45], s[24:25], v[32:33] op_sel_hi:[1,0,1]
	v_pk_fma_f32 v[126:127], v[46:47], s[24:25], v[34:35] op_sel_hi:[1,0,1]
	s_waitcnt vmcnt(2)
	v_lshlrev_b32_e32 v32, 16, v118
	v_and_b32_e32 v33, 0xffff0000, v118
	v_lshlrev_b32_e32 v44, 16, v119
	v_and_b32_e32 v45, 0xffff0000, v119
	v_pk_fma_f32 v[120:121], v[48:49], s[24:25], v[28:29] op_sel_hi:[1,0,1]
	v_pk_fma_f32 v[124:125], v[50:51], s[24:25], v[30:31] op_sel_hi:[1,0,1]
	v_lshlrev_b32_e32 v28, 16, v116
	v_and_b32_e32 v29, 0xffff0000, v116
	v_pk_fma_f32 v[44:45], v[44:45], s[24:25], v[22:23] op_sel_hi:[1,0,1]
	v_pk_fma_f32 v[46:47], v[32:33], s[24:25], v[20:21] op_sel_hi:[1,0,1]
	v_pk_mov_b32 v[20:21], v[122:123], v[126:127] op_sel:[1,0]
	v_mov_b32_e32 v22, v122
	v_mov_b32_e32 v23, v127
	v_pk_fma_f32 v[34:35], v[28:29], s[24:25], v[24:25] op_sel_hi:[1,0,1]
	v_pk_add_f32 v[20:21], v[20:21], v[22:23]
	v_pk_mov_b32 v[22:23], v[120:121], v[124:125] op_sel:[1,0]
	v_mov_b32_e32 v24, v120
	v_mov_b32_e32 v25, v125
	v_lshlrev_b32_e32 v30, 16, v117
	v_and_b32_e32 v31, 0xffff0000, v117
	v_pk_add_f32 v[22:23], v[22:23], v[24:25]
	v_pk_fma_f32 v[48:49], v[30:31], s[24:25], v[26:27] op_sel_hi:[1,0,1]
	v_add_f32_e32 v20, v20, v21
	v_pk_add_f32 v[22:23], v[22:23], v[22:23] op_sel_hi:[0,1]
	v_add_f32_e32 v21, 0, v20
	v_add_f32_e32 v25, v34, v35
	v_add_f32_e32 v27, v48, v49
	v_mov_b32_e32 v24, v46
	v_mov_b32_e32 v26, v47
	v_mov_b32_e32 v22, v44
	v_mov_b32_e32 v20, v45
	v_pk_add_f32 v[24:25], v[24:25], v[26:27]
	v_pk_add_f32 v[20:21], v[22:23], v[20:21]
	s_nop 0
	v_pk_add_f32 v[20:21], v[24:25], v[20:21]
	s_nop 0
	v_add_f32_e32 v20, v20, v21
	v_mov_b32_e32 v21, v20
	s_nop 1
	v_permlane16_swap_b32 v21, v20
	s_waitcnt lgkmcnt(0)
;     __device__ __forceinline__ void run(const f32x4 (&v)[2][2][4][2], const Unit& u, int wr, int wc, int fr, int fq, LAS unsigned char* lds, int wid, int lane) const {
;     ...
;         for (int ai = 0; ai < 2; ++ai)
; #pragma unroll
;             for (int m = 0; m < 4; ++m) {
;                 float s = 0.f;
; #pragma unroll
;                 for (int bj = 0; bj < 2; ++bj)
; #pragma unroll
;                     for (int n = 0; n < 2; ++n) { const f32x4 x = v[ai][bj][m][n]; s += (x[0] + x[1]) + (x[2] + x[3]); }
;                 s += __shfl_xor(s, 16); s += __shfl_xor(s, 32);
;                 const float mw = s * (1.0f / 64.0f); float q = 0.f;
; #pragma unroll
;                 for (int bj = 0; bj < 2; ++bj)
; #pragma unroll
;                     for (int n = 0; n < 2; ++n) { const f32x4 d = v[ai][bj][m][n] - mw; q += (d[0] * d[0] + d[1] * d[1]) + (d[2] * d[2] + d[3] * d[3]); }
;                 q += __shfl_xor(q, 16); q += __shfl_xor(q, 32);
;                 if (fq == 0) Pt[(ai * HALF + wr * 64 + m * 16 + fr) * 4 + wc] = (f32x2v){mw, q};
;     __device__ __forceinline__ void fused(f32x4 (&acc)[2][2][4][2], const Unit& u, int wr, int wc, int fr, int fq, LAS unsigned char* lds, int wid, int lane) const {
;     ...
;                     const u32x4 hb = *(const u32x4*)(H + ro + bj * HALF);
;                     const f32x4 h0 = {bflo(hb.x), bfhi(hb.x), bflo(hb.y), bfhi(hb.y)}, h1 = {bflo(hb.z), bfhi(hb.z), bflo(hb.w), bfhi(hb.w)};
;                     acc[ai][bj][m][0] = h0 * ALPHA + acc[ai][bj][m][0]; acc[ai][bj][m][1] = h1 * ALPHA + acc[ai][bj][m][1];
	v_add_f32_e32 v20, v20, v21
	v_mov_b32_e32 v21, v20
	s_nop 1
	v_permlane32_swap_b32 v21, v20
	s_waitcnt lgkmcnt(0)
	v_add_f32_e32 v20, v20, v21
	v_fmamk_f32 v22, v20, 0xbc800000, v127
	v_fmamk_f32 v24, v20, 0xbc800000, v123
	v_fmamk_f32 v21, v20, 0xbc800000, v126
	v_fmamk_f32 v23, v20, 0xbc800000, v122
	v_mul_f32_e32 v24, v24, v24
	v_mul_f32_e32 v22, v22, v22
	v_fmac_f32_e32 v24, v23, v23
	v_fmac_f32_e32 v22, v21, v21
	v_fmamk_f32 v23, v20, 0xbc800000, v125
	v_fmamk_f32 v25, v20, 0xbc800000, v121
	v_add_f32_e32 v21, v24, v22
	v_fmamk_f32 v22, v20, 0xbc800000, v124
	v_fmamk_f32 v24, v20, 0xbc800000, v120
	v_mul_f32_e32 v25, v25, v25
	v_mul_f32_e32 v23, v23, v23
	v_fmac_f32_e32 v25, v24, v24
	v_fmac_f32_e32 v23, v22, v22
	v_add_f32_e32 v22, v25, v23
	v_fmamk_f32 v23, v20, 0xbc800000, v49
	v_fmamk_f32 v25, v20, 0xbc800000, v35
	v_add_f32_e32 v21, v21, v22
	v_fmamk_f32 v22, v20, 0xbc800000, v48
	v_fmamk_f32 v24, v20, 0xbc800000, v34
	v_mul_f32_e32 v25, v25, v25
	v_mul_f32_e32 v23, v23, v23
	v_fmac_f32_e32 v25, v24, v24
	v_fmac_f32_e32 v23, v22, v22
	v_add_f32_e32 v22, v25, v23
	v_fmamk_f32 v23, v20, 0xbc800000, v45
	v_fmamk_f32 v25, v20, 0xbc800000, v47
	v_add_f32_e32 v21, v22, v21
	v_fmamk_f32 v22, v20, 0xbc800000, v44
	v_fmamk_f32 v24, v20, 0xbc800000, v46
	v_mul_f32_e32 v25, v25, v25
	v_mul_f32_e32 v23, v23, v23
	v_fmac_f32_e32 v25, v24, v24
	v_fmac_f32_e32 v23, v22, v22
	v_add_f32_e32 v22, v25, v23
	v_add_f32_e32 v21, v22, v21
	v_mov_b32_e32 v22, v21
	s_nop 1
	v_permlane16_swap_b32 v22, v21
	s_waitcnt lgkmcnt(0)
	v_add_f32_e32 v21, v21, v22
	v_mov_b32_e32 v22, v21
	s_nop 1
	v_permlane32_swap_b32 v22, v21
	s_and_saveexec_b64 s[40:41], vcc
	s_cbranch_execz .LBB0_795
	s_lshl_b32 s8, s5, 11
	s_add_i32 s8, s36, s8
	v_mul_f32_e32 v20, 0x3c800000, v20
	v_lshl_add_u32 v23, v194, 5, s8
	s_waitcnt lgkmcnt(0)
	v_add_f32_e32 v21, v21, v22
	ds_write_b64 v23, v[20:21] offset:5120
.LBB0_795:
	s_or_b64 exec, exec, s[40:41]
	s_waitcnt vmcnt(1)
	v_lshlrev_b32_e32 v20, 16, v136
	v_and_b32_e32 v21, 0xffff0000, v136
	s_waitcnt lgkmcnt(0)
	v_lshlrev_b32_e32 v22, 16, v137
	v_and_b32_e32 v23, 0xffff0000, v137
	v_lshlrev_b32_e32 v24, 16, v138
	v_and_b32_e32 v25, 0xffff0000, v138
	v_lshlrev_b32_e32 v26, 16, v139
	v_and_b32_e32 v27, 0xffff0000, v139
	v_pk_fma_f32 v[118:119], v[20:21], s[24:25], v[16:17] op_sel_hi:[1,0,1]
	v_pk_fma_f32 v[138:139], v[22:23], s[24:25], v[18:19] op_sel_hi:[1,0,1]
	s_waitcnt vmcnt(0)
	v_lshlrev_b32_e32 v16, 16, v130
	v_and_b32_e32 v17, 0xffff0000, v130
	v_lshlrev_b32_e32 v18, 16, v131
	v_and_b32_e32 v19, 0xffff0000, v131
	v_pk_fma_f32 v[116:117], v[24:25], s[24:25], v[12:13] op_sel_hi:[1,0,1]
	v_pk_fma_f32 v[136:137], v[26:27], s[24:25], v[14:15] op_sel_hi:[1,0,1]
	v_lshlrev_b32_e32 v12, 16, v128
	v_and_b32_e32 v13, 0xffff0000, v128
	v_pk_fma_f32 v[108:109], v[18:19], s[24:25], v[6:7] op_sel_hi:[1,0,1]
	v_pk_fma_f32 v[110:111], v[16:17], s[24:25], v[4:5] op_sel_hi:[1,0,1]
	v_pk_mov_b32 v[4:5], v[118:119], v[138:139] op_sel:[1,0]
	v_mov_b32_e32 v6, v118
	v_mov_b32_e32 v7, v139
	v_pk_fma_f32 v[50:51], v[12:13], s[24:25], v[8:9] op_sel_hi:[1,0,1]
	v_pk_add_f32 v[4:5], v[4:5], v[6:7]
	v_pk_mov_b32 v[6:7], v[116:117], v[136:137] op_sel:[1,0]
	v_mov_b32_e32 v8, v116
	v_mov_b32_e32 v9, v137
	v_lshlrev_b32_e32 v14, 16, v129
	v_and_b32_e32 v15, 0xffff0000, v129
	v_pk_add_f32 v[6:7], v[6:7], v[8:9]
	v_pk_fma_f32 v[112:113], v[14:15], s[24:25], v[10:11] op_sel_hi:[1,0,1]
	v_add_f32_e32 v4, v4, v5
	v_pk_add_f32 v[6:7], v[6:7], v[6:7] op_sel_hi:[0,1]
	v_add_f32_e32 v5, 0, v4
	v_add_f32_e32 v9, v50, v51
	v_add_f32_e32 v11, v112, v113
	v_mov_b32_e32 v8, v110
	v_mov_b32_e32 v10, v111
	v_mov_b32_e32 v6, v108
	v_mov_b32_e32 v4, v109
	v_pk_add_f32 v[8:9], v[8:9], v[10:11]
	v_pk_add_f32 v[4:5], v[6:7], v[4:5]
	s_nop 0
	v_pk_add_f32 v[4:5], v[8:9], v[4:5]
	s_nop 0
	v_add_f32_e32 v4, v4, v5
	v_mov_b32_e32 v5, v4
	s_nop 1
	v_permlane16_swap_b32 v5, v4
	s_waitcnt lgkmcnt(0)
	v_add_f32_e32 v4, v4, v5
	v_mov_b32_e32 v5, v4
	s_nop 1
	v_permlane32_swap_b32 v5, v4
	s_waitcnt lgkmcnt(0)
	v_add_f32_e32 v4, v4, v5
	v_fmamk_f32 v6, v4, 0xbc800000, v139
	v_fmamk_f32 v8, v4, 0xbc800000, v119
	v_fmamk_f32 v5, v4, 0xbc800000, v138
	v_fmamk_f32 v7, v4, 0xbc800000, v118
	v_mul_f32_e32 v8, v8, v8
	v_mul_f32_e32 v6, v6, v6
	v_fmac_f32_e32 v8, v7, v7
	v_fmac_f32_e32 v6, v5, v5
	v_fmamk_f32 v7, v4, 0xbc800000, v137
	v_fmamk_f32 v9, v4, 0xbc800000, v117
	v_add_f32_e32 v5, v8, v6
	v_fmamk_f32 v6, v4, 0xbc800000, v136
	v_fmamk_f32 v8, v4, 0xbc800000, v116
	v_mul_f32_e32 v9, v9, v9
	v_mul_f32_e32 v7, v7, v7
	v_fmac_f32_e32 v9, v8, v8
	v_fmac_f32_e32 v7, v6, v6
	v_add_f32_e32 v6, v9, v7
	v_fmamk_f32 v7, v4, 0xbc800000, v113
	v_fmamk_f32 v9, v4, 0xbc800000, v51
	v_add_f32_e32 v5, v5, v6
	v_fmamk_f32 v6, v4, 0xbc800000, v112
	v_fmamk_f32 v8, v4, 0xbc800000, v50
	v_mul_f32_e32 v9, v9, v9
	v_mul_f32_e32 v7, v7, v7
	v_fmac_f32_e32 v9, v8, v8
	v_fmac_f32_e32 v7, v6, v6
	v_add_f32_e32 v6, v9, v7
	v_fmamk_f32 v7, v4, 0xbc800000, v109
	v_fmamk_f32 v9, v4, 0xbc800000, v111
	v_add_f32_e32 v5, v6, v5
	v_fmamk_f32 v6, v4, 0xbc800000, v108
	v_fmamk_f32 v8, v4, 0xbc800000, v110
	v_mul_f32_e32 v9, v9, v9
	v_mul_f32_e32 v7, v7, v7
	v_fmac_f32_e32 v9, v8, v8
	v_fmac_f32_e32 v7, v6, v6
	v_add_f32_e32 v6, v9, v7
	v_add_f32_e32 v5, v6, v5
	v_mov_b32_e32 v6, v5
	s_nop 1
	v_permlane16_swap_b32 v6, v5
	s_waitcnt lgkmcnt(0)
	v_add_f32_e32 v5, v5, v6
	v_mov_b32_e32 v6, v5
	s_nop 1
	v_permlane32_swap_b32 v6, v5
	s_and_saveexec_b64 s[40:41], vcc
	s_cbranch_execz .LBB0_797
	s_lshl_b32 s5, s5, 11
	s_add_i32 s36, s36, s5
	v_mul_f32_e32 v4, 0x3c800000, v4
	v_lshl_add_u32 v7, v194, 5, s36
	s_waitcnt lgkmcnt(0)
	v_add_f32_e32 v5, v5, v6
	ds_write_b64 v7, v[4:5] offset:5632

;     __device__ __forceinline__ void run(const f32x4 (&v)[2][2][4][2], const Unit& u, int wr, int wc, int fr, int fq, LAS unsigned char* lds, int wid, int lane) const {
;     ...
;         for (int ai = 0; ai < 2; ++ai)
; #pragma unroll
;             for (int m = 0; m < 4; ++m) {
;                 float s = 0.f;
; #pragma unroll
;                 for (int bj = 0; bj < 2; ++bj)
; #pragma unroll
;                     for (int n = 0; n < 2; ++n) { const f32x4 x = v[ai][bj][m][n]; s += (x[0] + x[1]) + (x[2] + x[3]); }
;                 s += __shfl_xor(s, 16); s += __shfl_xor(s, 32);
;                 const float mw = s * (1.0f / 64.0f); float q = 0.f;
; #pragma unroll
;                 for (int bj = 0; bj < 2; ++bj)
; #pragma unroll
;                     for (int n = 0; n < 2; ++n) { const f32x4 d = v[ai][bj][m][n] - mw; q += (d[0] * d[0] + d[1] * d[1]) + (d[2] * d[2] + d[3] * d[3]); }
;                 q += __shfl_xor(q, 16); q += __shfl_xor(q, 32);
;     __device__ __forceinline__ void fused(f32x4 (&acc)[2][2][4][2], const Unit& u, int wr, int wc, int fr, int fq, LAS unsigned char* lds, int wid, int lane) const {
;     ...
;         const int col0 = u.pn * BM + wc * 32 + 8 * fq;
; #pragma unroll
;         for (int ai = 0; ai < 2; ++ai)
; #pragma unroll
;             for (int m = 0; m < 4; ++m) {
;                 const size_t ro = (size_t)(u.pm * BM + ai * HALF + wr * 64 + m * 16 + fr) * D + col0;
; #pragma unroll
;                 for (int bj = 0; bj < 2; ++bj) {
;                     const u32x4 hb = *(const u32x4*)(H + ro + bj * HALF);
;                     const f32x4 h0 = {bflo(hb.x), bfhi(hb.x), bflo(hb.y), bfhi(hb.y)}, h1 = {bflo(hb.z), bfhi(hb.z), bflo(hb.w), bfhi(hb.w)};
;                     acc[ai][bj][m][0] = h0 * ALPHA + acc[ai][bj][m][0]; acc[ai][bj][m][1] = h1 * ALPHA + acc[ai][bj][m][1];
.LBB0_1036:
	s_add_u32 s44, s56, 0x17000000
	s_addc_u32 s45, s57, 0
	s_lshl_b32 s7, s55, 5
	s_lshl_b32 s8, s54, 8
	v_lshrrev_b32_e32 v2, 1, v189
	s_or_b32 s7, s8, s7
	v_and_or_b32 v2, v2, 24, s7
	s_lshl_b32 s7, s6, 8
	s_add_i32 s8, s7, s86
	v_or_b32_e32 v138, s8, v190
	v_ashrrev_i32_e32 v139, 31, v138
	v_ashrrev_i32_e32 v3, 31, v2
	v_lshlrev_b64 v[132:133], 12, v[138:139]
	v_lshl_add_u64 v[132:133], s[44:45], 0, v[132:133]
	v_lshlrev_b64 v[136:137], 1, v[2:3]
	v_lshl_add_u64 v[140:141], v[132:133], 0, v[136:137]
	s_waitcnt vmcnt(0)
	s_barrier
	global_load_dwordx4 v[132:135], v[140:141], off
	v_and_b32_e32 v192, 64, v217
	v_xor_b32_e32 v191, 16, v217
	v_add_u32_e32 v192, 64, v192
	v_cmp_lt_i32_e32 vcc, v191, v192
	v_xor_b32_e32 v193, 32, v217
	v_and_b32_e32 v1, 63, v189
	v_cndmask_b32_e32 v191, v217, v191, vcc
	v_cmp_lt_i32_e32 vcc, v193, v192
	v_lshlrev_b32_e32 v191, 2, v191
	s_lshl_b32 s8, s55, 3
	v_cndmask_b32_e32 v192, v217, v193, vcc
	v_lshlrev_b32_e32 v192, 2, v192
	v_cmp_gt_u32_e32 vcc, 16, v1
	s_add_i32 s46, s8, 0
	s_waitcnt vmcnt(0)
	v_lshlrev_b32_e32 v144, 16, v134
	v_and_b32_e32 v145, 0xffff0000, v134
	v_lshlrev_b32_e32 v134, 16, v135
	v_and_b32_e32 v135, 0xffff0000, v135
	v_pk_fma_f32 v[180:181], v[144:145], s[24:25], v[124:125] op_sel_hi:[1,0,1]
	v_pk_fma_f32 v[182:183], v[134:135], s[24:25], v[126:127] op_sel_hi:[1,0,1]
	global_load_dwordx4 v[124:127], v[140:141], off offset:256
	v_lshlrev_b32_e32 v142, 16, v132
	v_and_b32_e32 v143, 0xffff0000, v132
	v_lshlrev_b32_e32 v132, 16, v133
	v_and_b32_e32 v133, 0xffff0000, v133
	v_pk_fma_f32 v[186:187], v[132:133], s[24:25], v[130:131] op_sel_hi:[1,0,1]
	v_pk_fma_f32 v[184:185], v[142:143], s[24:25], v[128:129] op_sel_hi:[1,0,1]
	v_mov_b32_e32 v197, v187
	v_pk_mov_b32 v[194:195], v[184:185], v[186:187] op_sel:[1,0]
	v_mov_b32_e32 v196, v184
	v_pk_add_f32 v[194:195], v[194:195], v[196:197]
	v_pk_mov_b32 v[196:197], v[180:181], v[182:183] op_sel:[1,0]
	v_mov_b32_e32 v198, v180
	v_mov_b32_e32 v199, v183
	v_pk_add_f32 v[196:197], v[196:197], v[198:199]
	v_add_f32_e32 v193, v194, v195
	v_pk_add_f32 v[196:197], v[196:197], v[196:197] op_sel_hi:[0,1]
	v_add_f32_e32 v195, 0, v193
	s_waitcnt vmcnt(0)
	v_lshlrev_b32_e32 v130, 16, v126
	v_and_b32_e32 v131, 0xffff0000, v126
	v_pk_fma_f32 v[172:173], v[130:131], s[24:25], v[116:117] op_sel_hi:[1,0,1]
	v_or_b32_e32 v116, 16, v138
	v_ashrrev_i32_e32 v117, 31, v116
	v_lshlrev_b64 v[116:117], 12, v[116:117]
	v_lshl_add_u64 v[116:117], s[44:45], 0, v[116:117]
	v_lshl_add_u64 v[116:117], v[116:117], 0, v[136:137]
	global_load_dwordx4 v[168:171], v[116:117], off
	global_load_dwordx4 v[164:167], v[116:117], off offset:256
	v_or_b32_e32 v116, 32, v138
	v_ashrrev_i32_e32 v117, 31, v116
	v_lshlrev_b64 v[116:117], 12, v[116:117]
	v_lshl_add_u64 v[116:117], s[44:45], 0, v[116:117]
	v_lshl_add_u64 v[116:117], v[116:117], 0, v[136:137]
	global_load_dwordx4 v[160:163], v[116:117], off
	global_load_dwordx4 v[156:159], v[116:117], off offset:256
	v_or_b32_e32 v116, 48, v138
	v_ashrrev_i32_e32 v117, 31, v116
	v_lshlrev_b64 v[116:117], 12, v[116:117]
	v_lshl_add_u64 v[116:117], s[44:45], 0, v[116:117]
	v_lshl_add_u64 v[116:117], v[116:117], 0, v[136:137]
	global_load_dwordx4 v[152:155], v[116:117], off
	global_load_dwordx4 v[148:151], v[116:117], off offset:256
	v_add_u32_e32 v116, 0x80, v138
	v_ashrrev_i32_e32 v117, 31, v116
	v_lshlrev_b64 v[116:117], 12, v[116:117]
	v_lshl_add_u64 v[116:117], s[44:45], 0, v[116:117]
	v_lshl_add_u64 v[116:117], v[116:117], 0, v[136:137]
	global_load_dwordx4 v[144:147], v[116:117], off
	global_load_dwordx4 v[140:143], v[116:117], off offset:256
	v_add_u32_e32 v116, 0x90, v138
	v_ashrrev_i32_e32 v117, 31, v116
	v_lshlrev_b64 v[116:117], 12, v[116:117]
	v_lshl_add_u64 v[116:117], s[44:45], 0, v[116:117]
	v_lshlrev_b32_e32 v128, 16, v124
	v_and_b32_e32 v129, 0xffff0000, v124
	v_lshlrev_b32_e32 v124, 16, v125
	v_and_b32_e32 v125, 0xffff0000, v125
	v_lshlrev_b32_e32 v126, 16, v127
	v_and_b32_e32 v127, 0xffff0000, v127
	v_lshl_add_u64 v[116:117], v[116:117], 0, v[136:137]
	v_pk_fma_f32 v[176:177], v[128:129], s[24:25], v[120:121] op_sel_hi:[1,0,1]
	v_pk_fma_f32 v[178:179], v[124:125], s[24:25], v[122:123] op_sel_hi:[1,0,1]
	v_pk_fma_f32 v[174:175], v[126:127], s[24:25], v[118:119] op_sel_hi:[1,0,1]
	global_load_dwordx4 v[132:135], v[116:117], off
	global_load_dwordx4 v[124:127], v[116:117], off offset:256
	v_add_u32_e32 v116, 0xa0, v138
	v_add_u32_e32 v128, 0xb0, v138
	v_ashrrev_i32_e32 v117, 31, v116
	v_ashrrev_i32_e32 v129, 31, v128
	v_lshlrev_b64 v[116:117], 12, v[116:117]
	v_lshlrev_b64 v[128:129], 12, v[128:129]
	v_lshl_add_u64 v[116:117], s[44:45], 0, v[116:117]
	v_lshl_add_u64 v[128:129], s[44:45], 0, v[128:129]
	v_lshl_add_u64 v[116:117], v[116:117], 0, v[136:137]
	v_lshl_add_u64 v[128:129], v[128:129], 0, v[136:137]
	global_load_dwordx4 v[120:123], v[116:117], off
	s_nop 0
	global_load_dwordx4 v[116:119], v[116:117], off offset:256
	s_nop 0
	global_load_dwordx4 v[136:139], v[128:129], off
	s_nop 0
	global_load_dwordx4 v[128:131], v[128:129], off offset:256
	v_add_f32_e32 v199, v176, v177
	v_add_f32_e32 v201, v178, v179
	v_mov_b32_e32 v198, v172
	v_mov_b32_e32 v200, v173
	v_mov_b32_e32 v196, v174
	v_mov_b32_e32 v194, v175
	v_pk_add_f32 v[198:199], v[198:199], v[200:201]
	v_pk_add_f32 v[194:195], v[196:197], v[194:195]
	s_nop 0
	v_pk_add_f32 v[194:195], v[198:199], v[194:195]
	s_nop 0
	v_add_f32_e32 v193, v194, v195
	v_mov_b32_e32 v194, v193
	s_nop 1
	v_permlane16_swap_b32 v194, v193
	s_waitcnt lgkmcnt(0)
	v_add_f32_e32 v193, v193, v194
	v_mov_b32_e32 v194, v193
	s_nop 1
	v_permlane32_swap_b32 v194, v193
	s_waitcnt lgkmcnt(0)
;     __device__ __forceinline__ void run(const f32x4 (&v)[2][2][4][2], const Unit& u, int wr, int wc, int fr, int fq, LAS unsigned char* lds, int wid, int lane) const {
;     ...
;         for (int ai = 0; ai < 2; ++ai)
; #pragma unroll
;             for (int m = 0; m < 4; ++m) {
;                 float s = 0.f;
; #pragma unroll
;                 for (int bj = 0; bj < 2; ++bj)
; #pragma unroll
;                     for (int n = 0; n < 2; ++n) { const f32x4 x = v[ai][bj][m][n]; s += (x[0] + x[1]) + (x[2] + x[3]); }
;                 s += __shfl_xor(s, 16); s += __shfl_xor(s, 32);
;                 const float mw = s * (1.0f / 64.0f); float q = 0.f;
; #pragma unroll
;                 for (int bj = 0; bj < 2; ++bj)
; #pragma unroll
;                     for (int n = 0; n < 2; ++n) { const f32x4 d = v[ai][bj][m][n] - mw; q += (d[0] * d[0] + d[1] * d[1]) + (d[2] * d[2] + d[3] * d[3]); }
;                 q += __shfl_xor(q, 16); q += __shfl_xor(q, 32);
;                 if (fq == 0) Pt[(ai * HALF + wr * 64 + m * 16 + fr) * 4 + wc] = (f32x2v){mw, q};
;     __device__ __forceinline__ void fused(f32x4 (&acc)[2][2][4][2], const Unit& u, int wr, int wc, int fr, int fq, LAS unsigned char* lds, int wid, int lane) const {
;     ...
;                     const u32x4 hb = *(const u32x4*)(H + ro + bj * HALF);
;                     const f32x4 h0 = {bflo(hb.x), bfhi(hb.x), bflo(hb.y), bfhi(hb.y)}, h1 = {bflo(hb.z), bfhi(hb.z), bflo(hb.w), bfhi(hb.w)};
;                     acc[ai][bj][m][0] = h0 * ALPHA + acc[ai][bj][m][0]; acc[ai][bj][m][1] = h1 * ALPHA + acc[ai][bj][m][1];
	v_add_f32_e32 v193, v193, v194
	v_fmamk_f32 v195, v193, 0xbc800000, v187
	v_fmamk_f32 v197, v193, 0xbc800000, v185
	v_fmamk_f32 v194, v193, 0xbc800000, v186
	v_fmamk_f32 v196, v193, 0xbc800000, v184
	v_mul_f32_e32 v197, v197, v197
	v_mul_f32_e32 v195, v195, v195
	v_fmac_f32_e32 v197, v196, v196
	v_fmac_f32_e32 v195, v194, v194
	v_fmamk_f32 v196, v193, 0xbc800000, v183
	v_fmamk_f32 v198, v193, 0xbc800000, v181
	v_add_f32_e32 v194, v197, v195
	v_fmamk_f32 v195, v193, 0xbc800000, v182
	v_fmamk_f32 v197, v193, 0xbc800000, v180
	v_mul_f32_e32 v198, v198, v198
	v_mul_f32_e32 v196, v196, v196
	v_fmac_f32_e32 v198, v197, v197
	v_fmac_f32_e32 v196, v195, v195
	v_add_f32_e32 v195, v198, v196
	v_fmamk_f32 v196, v193, 0xbc800000, v179
	v_fmamk_f32 v198, v193, 0xbc800000, v177
	v_add_f32_e32 v194, v194, v195
	v_fmamk_f32 v195, v193, 0xbc800000, v178
	v_fmamk_f32 v197, v193, 0xbc800000, v176
	v_mul_f32_e32 v198, v198, v198
	v_mul_f32_e32 v196, v196, v196
	v_fmac_f32_e32 v198, v197, v197
	v_fmac_f32_e32 v196, v195, v195
	v_add_f32_e32 v195, v198, v196
	v_fmamk_f32 v196, v193, 0xbc800000, v175
	v_fmamk_f32 v198, v193, 0xbc800000, v173
	v_add_f32_e32 v194, v195, v194
	v_fmamk_f32 v195, v193, 0xbc800000, v174
	v_fmamk_f32 v197, v193, 0xbc800000, v172
	v_mul_f32_e32 v198, v198, v198
	v_mul_f32_e32 v196, v196, v196
	v_fmac_f32_e32 v198, v197, v197
	v_fmac_f32_e32 v196, v195, v195
	v_add_f32_e32 v195, v198, v196
	v_add_f32_e32 v194, v195, v194
	v_mov_b32_e32 v195, v194
	s_nop 1
	v_permlane16_swap_b32 v195, v194
	s_waitcnt lgkmcnt(0)
	v_add_f32_e32 v194, v194, v195
	v_mov_b32_e32 v195, v194
	s_nop 1
	v_permlane32_swap_b32 v195, v194
	s_and_saveexec_b64 s[44:45], vcc
	s_cbranch_execz .LBB0_1038
	s_lshl_b32 s8, s5, 11
	s_add_i32 s8, s46, s8
	v_mul_f32_e32 v196, 0x3c800000, v193
	v_lshl_add_u32 v193, v190, 5, s8
	s_waitcnt lgkmcnt(0)
	v_add_f32_e32 v197, v194, v195
	ds_write_b64 v193, v[196:197]
.LBB0_1038:
	s_or_b64 exec, exec, s[44:45]
	s_waitcnt vmcnt(13)
	v_lshlrev_b32_e32 v194, 16, v168
	s_waitcnt lgkmcnt(0)
	v_and_b32_e32 v195, 0xffff0000, v168
	v_lshlrev_b32_e32 v168, 16, v169
	v_and_b32_e32 v169, 0xffff0000, v169
	v_lshlrev_b32_e32 v196, 16, v170
	v_and_b32_e32 v197, 0xffff0000, v170
	v_lshlrev_b32_e32 v170, 16, v171
	v_and_b32_e32 v171, 0xffff0000, v171
	v_pk_fma_f32 v[112:113], v[194:195], s[24:25], v[112:113] op_sel_hi:[1,0,1]
	v_pk_fma_f32 v[114:115], v[168:169], s[24:25], v[114:115] op_sel_hi:[1,0,1]
	v_pk_fma_f32 v[110:111], v[170:171], s[24:25], v[110:111] op_sel_hi:[1,0,1]
	s_waitcnt vmcnt(12)
	v_lshlrev_b32_e32 v168, 16, v164
	v_and_b32_e32 v169, 0xffff0000, v164
	v_lshlrev_b32_e32 v164, 16, v165
	v_and_b32_e32 v165, 0xffff0000, v165
	v_lshlrev_b32_e32 v170, 16, v166
	v_and_b32_e32 v171, 0xffff0000, v166
	v_lshlrev_b32_e32 v166, 16, v167
	v_and_b32_e32 v167, 0xffff0000, v167
	v_pk_fma_f32 v[108:109], v[196:197], s[24:25], v[108:109] op_sel_hi:[1,0,1]
	v_pk_fma_f32 v[106:107], v[164:165], s[24:25], v[106:107] op_sel_hi:[1,0,1]
	v_pk_fma_f32 v[102:103], v[166:167], s[24:25], v[102:103] op_sel_hi:[1,0,1]
	v_pk_mov_b32 v[164:165], v[112:113], v[114:115] op_sel:[1,0]
	v_mov_b32_e32 v166, v112
	v_mov_b32_e32 v167, v115
	v_pk_fma_f32 v[104:105], v[168:169], s[24:25], v[104:105] op_sel_hi:[1,0,1]
	v_pk_add_f32 v[164:165], v[164:165], v[166:167]
	v_pk_mov_b32 v[166:167], v[108:109], v[110:111] op_sel:[1,0]
	v_mov_b32_e32 v168, v108
	v_mov_b32_e32 v169, v111
	v_pk_add_f32 v[166:167], v[166:167], v[168:169]
	v_pk_fma_f32 v[100:101], v[170:171], s[24:25], v[100:101] op_sel_hi:[1,0,1]
	v_add_f32_e32 v164, v164, v165
	v_pk_add_f32 v[166:167], v[166:167], v[166:167] op_sel_hi:[0,1]
	v_add_f32_e32 v165, 0, v164
	v_add_f32_e32 v169, v104, v105
	v_add_f32_e32 v171, v106, v107
	v_mov_b32_e32 v168, v100
	v_mov_b32_e32 v170, v101
	v_mov_b32_e32 v166, v102
	v_mov_b32_e32 v164, v103
	v_pk_add_f32 v[168:169], v[168:169], v[170:171]
	v_pk_add_f32 v[164:165], v[166:167], v[164:165]
	s_nop 0
	v_pk_add_f32 v[164:165], v[168:169], v[164:165]
	s_nop 0
	v_add_f32_e32 v164, v164, v165
	v_mov_b32_e32 v165, v164
	s_nop 1
	v_permlane16_swap_b32 v165, v164
	s_waitcnt lgkmcnt(0)
	v_add_f32_e32 v164, v164, v165
	v_mov_b32_e32 v165, v164
	s_nop 1
	v_permlane32_swap_b32 v165, v164
	s_waitcnt lgkmcnt(0)
	v_add_f32_e32 v164, v164, v165
	v_fmamk_f32 v166, v164, 0xbc800000, v115
	v_fmamk_f32 v168, v164, 0xbc800000, v113
	v_fmamk_f32 v165, v164, 0xbc800000, v114
	v_fmamk_f32 v167, v164, 0xbc800000, v112
	v_mul_f32_e32 v168, v168, v168
	v_mul_f32_e32 v166, v166, v166
	v_fmac_f32_e32 v168, v167, v167
	v_fmac_f32_e32 v166, v165, v165
	v_fmamk_f32 v167, v164, 0xbc800000, v111
	v_fmamk_f32 v169, v164, 0xbc800000, v109
	v_add_f32_e32 v165, v168, v166
	v_fmamk_f32 v166, v164, 0xbc800000, v110
	v_fmamk_f32 v168, v164, 0xbc800000, v108
	v_mul_f32_e32 v169, v169, v169
	v_mul_f32_e32 v167, v167, v167
	v_fmac_f32_e32 v169, v168, v168
	v_fmac_f32_e32 v167, v166, v166
	v_add_f32_e32 v166, v169, v167
	v_fmamk_f32 v167, v164, 0xbc800000, v107
	v_fmamk_f32 v169, v164, 0xbc800000, v105
	v_add_f32_e32 v165, v165, v166
	v_fmamk_f32 v166, v164, 0xbc800000, v106
	v_fmamk_f32 v168, v164, 0xbc800000, v104
	v_mul_f32_e32 v169, v169, v169
	v_mul_f32_e32 v167, v167, v167
	v_fmac_f32_e32 v169, v168, v168
	v_fmac_f32_e32 v167, v166, v166
	v_add_f32_e32 v166, v169, v167
	v_fmamk_f32 v167, v164, 0xbc800000, v103
	v_fmamk_f32 v169, v164, 0xbc800000, v101
	v_add_f32_e32 v165, v166, v165
	v_fmamk_f32 v166, v164, 0xbc800000, v102
	v_fmamk_f32 v168, v164, 0xbc800000, v100
	v_mul_f32_e32 v169, v169, v169
	v_mul_f32_e32 v167, v167, v167
	v_fmac_f32_e32 v169, v168, v168
	v_fmac_f32_e32 v167, v166, v166
	v_add_f32_e32 v166, v169, v167
	v_add_f32_e32 v165, v166, v165
	v_mov_b32_e32 v166, v165
	s_nop 1
	v_permlane16_swap_b32 v166, v165
	s_waitcnt lgkmcnt(0)
	v_add_f32_e32 v165, v165, v166
	v_mov_b32_e32 v166, v165
	s_nop 1
	v_permlane32_swap_b32 v166, v165
	s_and_saveexec_b64 s[44:45], vcc
	v_readlane_b32 s88, v255, 26
	v_readlane_b32 s12, v255, 28
	v_readlane_b32 s14, v255, 30
	v_readlane_b32 s56, v255, 32
	v_readlane_b32 s84, v255, 34
	v_readlane_b32 s62, v255, 40
	v_readlane_b32 s72, v255, 22
	v_readlane_b32 s86, v255, 24
	v_readlane_b32 s89, v255, 27
	v_readlane_b32 s13, v255, 29
	v_readlane_b32 s15, v255, 31
	v_readlane_b32 s57, v255, 33
	v_readlane_b32 s85, v255, 35
	s_mov_b32 s66, 0xf800000
	v_readlane_b32 s82, v255, 38
	v_readlane_b32 s63, v255, 41
	v_readlane_b32 s73, v255, 23
	v_readlane_b32 s87, v255, 25
	v_readlane_b32 s83, v255, 39
	s_cbranch_execz .LBB0_1040
	s_lshl_b32 s8, s5, 11
	s_add_i32 s8, s46, s8
	v_mul_f32_e32 v164, 0x3c800000, v164
	v_lshl_add_u32 v167, v190, 5, s8
	s_waitcnt lgkmcnt(0)
	v_add_f32_e32 v165, v165, v166
	ds_write_b64 v167, v[164:165] offset:512
;     __device__ __forceinline__ void run(const f32x4 (&v)[2][2][4][2], const Unit& u, int wr, int wc, int fr, int fq, LAS unsigned char* lds, int wid, int lane) const {
;     ...
;                 float s = 0.f;
; #pragma unroll
;                 for (int bj = 0; bj < 2; ++bj)
; #pragma unroll
;                     for (int n = 0; n < 2; ++n) { const f32x4 x = v[ai][bj][m][n]; s += (x[0] + x[1]) + (x[2] + x[3]); }
;                 s += __shfl_xor(s, 16); s += __shfl_xor(s, 32);
;                 const float mw = s * (1.0f / 64.0f); float q = 0.f;
; #pragma unroll
;                 for (int bj = 0; bj < 2; ++bj)
; #pragma unroll
;                     for (int n = 0; n < 2; ++n) { const f32x4 d = v[ai][bj][m][n] - mw; q += (d[0] * d[0] + d[1] * d[1]) + (d[2] * d[2] + d[3] * d[3]); }
;                 q += __shfl_xor(q, 16); q += __shfl_xor(q, 32);
;                 if (fq == 0) Pt[(ai * HALF + wr * 64 + m * 16 + fr) * 4 + wc] = (f32x2v){mw, q};
;             }
;     __device__ __forceinline__ void fused(f32x4 (&acc)[2][2][4][2], const Unit& u, int wr, int wc, int fr, int fq, LAS unsigned char* lds, int wid, int lane) const {
;     ...
;                     const u32x4 hb = *(const u32x4*)(H + ro + bj * HALF);
;                     const f32x4 h0 = {bflo(hb.x), bfhi(hb.x), bflo(hb.y), bfhi(hb.y)}, h1 = {bflo(hb.z), bfhi(hb.z), bflo(hb.w), bfhi(hb.w)};
;                     acc[ai][bj][m][0] = h0 * ALPHA + acc[ai][bj][m][0]; acc[ai][bj][m][1] = h1 * ALPHA + acc[ai][bj][m][1];
.LBB0_1040:
	s_or_b64 exec, exec, s[44:45]
	s_waitcnt vmcnt(11)
	v_lshlrev_b32_e32 v164, 16, v160
	v_and_b32_e32 v165, 0xffff0000, v160
	s_waitcnt lgkmcnt(0)
	v_lshlrev_b32_e32 v166, 16, v161
	v_and_b32_e32 v167, 0xffff0000, v161
	v_lshlrev_b32_e32 v168, 16, v162
	v_and_b32_e32 v169, 0xffff0000, v162
	v_lshlrev_b32_e32 v170, 16, v163
	v_and_b32_e32 v171, 0xffff0000, v163
	v_pk_fma_f32 v[160:161], v[164:165], s[24:25], v[96:97] op_sel_hi:[1,0,1]
	v_pk_fma_f32 v[164:165], v[166:167], s[24:25], v[98:99] op_sel_hi:[1,0,1]
	v_pk_fma_f32 v[162:163], v[168:169], s[24:25], v[92:93] op_sel_hi:[1,0,1]
	v_pk_fma_f32 v[166:167], v[170:171], s[24:25], v[94:95] op_sel_hi:[1,0,1]
	s_waitcnt vmcnt(10)
	v_lshlrev_b32_e32 v92, 16, v156
	v_and_b32_e32 v93, 0xffff0000, v156
	v_lshlrev_b32_e32 v94, 16, v157
	v_and_b32_e32 v95, 0xffff0000, v157
	v_lshlrev_b32_e32 v96, 16, v158
	v_and_b32_e32 v97, 0xffff0000, v158
	v_pk_fma_f32 v[88:89], v[92:93], s[24:25], v[88:89] op_sel_hi:[1,0,1]
	v_pk_fma_f32 v[90:91], v[94:95], s[24:25], v[90:91] op_sel_hi:[1,0,1]
	v_pk_mov_b32 v[92:93], v[160:161], v[164:165] op_sel:[1,0]
	v_mov_b32_e32 v94, v160
	v_mov_b32_e32 v95, v165
	v_pk_fma_f32 v[84:85], v[96:97], s[24:25], v[84:85] op_sel_hi:[1,0,1]
	v_pk_add_f32 v[92:93], v[92:93], v[94:95]
	v_pk_mov_b32 v[94:95], v[162:163], v[166:167] op_sel:[1,0]
	v_mov_b32_e32 v96, v162
	v_mov_b32_e32 v97, v167
	v_lshlrev_b32_e32 v98, 16, v159
	v_and_b32_e32 v99, 0xffff0000, v159
	v_pk_add_f32 v[94:95], v[94:95], v[96:97]
	v_pk_fma_f32 v[86:87], v[98:99], s[24:25], v[86:87] op_sel_hi:[1,0,1]
	v_add_f32_e32 v92, v92, v93
	v_pk_add_f32 v[94:95], v[94:95], v[94:95] op_sel_hi:[0,1]
	v_add_f32_e32 v93, 0, v92
	v_add_f32_e32 v97, v88, v89
	v_add_f32_e32 v99, v90, v91
	v_mov_b32_e32 v96, v84
	v_mov_b32_e32 v98, v85
	v_mov_b32_e32 v94, v86
	v_mov_b32_e32 v92, v87
	v_pk_add_f32 v[96:97], v[96:97], v[98:99]
	v_pk_add_f32 v[92:93], v[94:95], v[92:93]
	s_nop 0
	v_pk_add_f32 v[92:93], v[96:97], v[92:93]
	s_nop 0
	v_add_f32_e32 v92, v92, v93
	v_mov_b32_e32 v93, v92
	s_nop 1
	v_permlane16_swap_b32 v93, v92
	s_waitcnt lgkmcnt(0)
	v_add_f32_e32 v92, v92, v93
	v_mov_b32_e32 v93, v92
	s_nop 1
	v_permlane32_swap_b32 v93, v92
	s_waitcnt lgkmcnt(0)
	v_add_f32_e32 v92, v92, v93
	v_fmamk_f32 v94, v92, 0xbc800000, v165
	v_fmamk_f32 v96, v92, 0xbc800000, v161
	v_fmamk_f32 v93, v92, 0xbc800000, v164
	v_fmamk_f32 v95, v92, 0xbc800000, v160
	v_mul_f32_e32 v96, v96, v96
	v_mul_f32_e32 v94, v94, v94
	v_fmac_f32_e32 v96, v95, v95
	v_fmac_f32_e32 v94, v93, v93
	v_fmamk_f32 v95, v92, 0xbc800000, v167
	v_fmamk_f32 v97, v92, 0xbc800000, v163
	v_add_f32_e32 v93, v96, v94
	v_fmamk_f32 v94, v92, 0xbc800000, v166
	v_fmamk_f32 v96, v92, 0xbc800000, v162
	v_mul_f32_e32 v97, v97, v97
	v_mul_f32_e32 v95, v95, v95
	v_fmac_f32_e32 v97, v96, v96
	v_fmac_f32_e32 v95, v94, v94
	v_add_f32_e32 v94, v97, v95
	v_fmamk_f32 v95, v92, 0xbc800000, v91
	v_fmamk_f32 v97, v92, 0xbc800000, v89
	v_add_f32_e32 v93, v93, v94
	v_fmamk_f32 v94, v92, 0xbc800000, v90
	v_fmamk_f32 v96, v92, 0xbc800000, v88
	v_mul_f32_e32 v97, v97, v97
	v_mul_f32_e32 v95, v95, v95
	v_fmac_f32_e32 v97, v96, v96
	v_fmac_f32_e32 v95, v94, v94
	v_add_f32_e32 v94, v97, v95
	v_fmamk_f32 v95, v92, 0xbc800000, v87
	v_fmamk_f32 v97, v92, 0xbc800000, v85
	v_add_f32_e32 v93, v94, v93
	v_fmamk_f32 v94, v92, 0xbc800000, v86
	v_fmamk_f32 v96, v92, 0xbc800000, v84
	v_mul_f32_e32 v97, v97, v97
	v_mul_f32_e32 v95, v95, v95
	v_fmac_f32_e32 v97, v96, v96
	v_fmac_f32_e32 v95, v94, v94
	v_add_f32_e32 v94, v97, v95
	v_add_f32_e32 v93, v94, v93
	v_mov_b32_e32 v94, v93
	s_nop 1
	v_permlane16_swap_b32 v94, v93
	s_waitcnt lgkmcnt(0)
	v_add_f32_e32 v93, v93, v94
	v_mov_b32_e32 v94, v93
	s_nop 1
	v_permlane32_swap_b32 v94, v93
	s_and_saveexec_b64 s[44:45], vcc
	s_cbranch_execz .LBB0_1042
	s_lshl_b32 s8, s5, 11
	s_add_i32 s8, s46, s8
	v_mul_f32_e32 v92, 0x3c800000, v92
	v_lshl_add_u32 v95, v190, 5, s8
	s_waitcnt lgkmcnt(0)
	v_add_f32_e32 v93, v93, v94
	ds_write_b64 v95, v[92:93] offset:1024
.LBB0_1042:
	s_or_b64 exec, exec, s[44:45]
	s_waitcnt vmcnt(9)
	v_lshlrev_b32_e32 v92, 16, v152
	v_and_b32_e32 v93, 0xffff0000, v152
	s_waitcnt lgkmcnt(0)
	v_lshlrev_b32_e32 v94, 16, v153
	v_and_b32_e32 v95, 0xffff0000, v153
	v_lshlrev_b32_e32 v96, 16, v154
	v_and_b32_e32 v97, 0xffff0000, v154
	v_lshlrev_b32_e32 v98, 16, v155
	v_and_b32_e32 v99, 0xffff0000, v155
	v_pk_fma_f32 v[80:81], v[92:93], s[24:25], v[80:81] op_sel_hi:[1,0,1]
	v_pk_fma_f32 v[82:83], v[94:95], s[24:25], v[82:83] op_sel_hi:[1,0,1]
	s_waitcnt vmcnt(8)
	v_lshlrev_b32_e32 v92, 16, v148
	v_and_b32_e32 v93, 0xffff0000, v148
	v_lshlrev_b32_e32 v94, 16, v149
	v_and_b32_e32 v95, 0xffff0000, v149
	v_pk_fma_f32 v[76:77], v[96:97], s[24:25], v[76:77] op_sel_hi:[1,0,1]
	v_pk_fma_f32 v[78:79], v[98:99], s[24:25], v[78:79] op_sel_hi:[1,0,1]
	v_lshlrev_b32_e32 v96, 16, v150
	v_and_b32_e32 v97, 0xffff0000, v150
	v_pk_fma_f32 v[72:73], v[92:93], s[24:25], v[72:73] op_sel_hi:[1,0,1]
	v_pk_fma_f32 v[74:75], v[94:95], s[24:25], v[74:75] op_sel_hi:[1,0,1]
	v_pk_mov_b32 v[92:93], v[80:81], v[82:83] op_sel:[1,0]
	v_mov_b32_e32 v94, v80
	v_mov_b32_e32 v95, v83
	v_pk_fma_f32 v[68:69], v[96:97], s[24:25], v[68:69] op_sel_hi:[1,0,1]
	v_pk_add_f32 v[92:93], v[92:93], v[94:95]
	v_pk_mov_b32 v[94:95], v[76:77], v[78:79] op_sel:[1,0]
	v_mov_b32_e32 v96, v76
	v_mov_b32_e32 v97, v79
	v_lshlrev_b32_e32 v98, 16, v151
	v_and_b32_e32 v99, 0xffff0000, v151
	v_pk_add_f32 v[94:95], v[94:95], v[96:97]
	v_pk_fma_f32 v[70:71], v[98:99], s[24:25], v[70:71] op_sel_hi:[1,0,1]
	v_add_f32_e32 v92, v92, v93
	v_pk_add_f32 v[94:95], v[94:95], v[94:95] op_sel_hi:[0,1]
	v_add_f32_e32 v93, 0, v92
	v_add_f32_e32 v97, v72, v73
	v_add_f32_e32 v99, v74, v75
	v_mov_b32_e32 v96, v68
	v_mov_b32_e32 v98, v69
	v_mov_b32_e32 v94, v70
	v_mov_b32_e32 v92, v71
	v_pk_add_f32 v[96:97], v[96:97], v[98:99]
	v_pk_add_f32 v[92:93], v[94:95], v[92:93]
	s_nop 0
	v_pk_add_f32 v[92:93], v[96:97], v[92:93]
	s_nop 0
	v_add_f32_e32 v92, v92, v93
	v_mov_b32_e32 v93, v92
	s_nop 1
	v_permlane16_swap_b32 v93, v92
	s_waitcnt lgkmcnt(0)
;     __device__ __forceinline__ void run(const f32x4 (&v)[2][2][4][2], const Unit& u, int wr, int wc, int fr, int fq, LAS unsigned char* lds, int wid, int lane) const {
;     ...
;                 float s = 0.f;
; #pragma unroll
;                 for (int bj = 0; bj < 2; ++bj)
; #pragma unroll
;                     for (int n = 0; n < 2; ++n) { const f32x4 x = v[ai][bj][m][n]; s += (x[0] + x[1]) + (x[2] + x[3]); }
;                 s += __shfl_xor(s, 16); s += __shfl_xor(s, 32);
;                 const float mw = s * (1.0f / 64.0f); float q = 0.f;
; #pragma unroll
;                 for (int bj = 0; bj < 2; ++bj)
; #pragma unroll
;                     for (int n = 0; n < 2; ++n) { const f32x4 d = v[ai][bj][m][n] - mw; q += (d[0] * d[0] + d[1] * d[1]) + (d[2] * d[2] + d[3] * d[3]); }
;                 q += __shfl_xor(q, 16); q += __shfl_xor(q, 32);
;                 if (fq == 0) Pt[(ai * HALF + wr * 64 + m * 16 + fr) * 4 + wc] = (f32x2v){mw, q};
;             }
;     __device__ __forceinline__ void fused(f32x4 (&acc)[2][2][4][2], const Unit& u, int wr, int wc, int fr, int fq, LAS unsigned char* lds, int wid, int lane) const {
;     ...
;                     const u32x4 hb = *(const u32x4*)(H + ro + bj * HALF);
;                     const f32x4 h0 = {bflo(hb.x), bfhi(hb.x), bflo(hb.y), bfhi(hb.y)}, h1 = {bflo(hb.z), bfhi(hb.z), bflo(hb.w), bfhi(hb.w)};
;                     acc[ai][bj][m][0] = h0 * ALPHA + acc[ai][bj][m][0]; acc[ai][bj][m][1] = h1 * ALPHA + acc[ai][bj][m][1];
	v_add_f32_e32 v92, v92, v93
	v_mov_b32_e32 v93, v92
	s_nop 1
	v_permlane32_swap_b32 v93, v92
	s_waitcnt lgkmcnt(0)
	v_add_f32_e32 v92, v92, v93
	v_fmamk_f32 v94, v92, 0xbc800000, v83
	v_fmamk_f32 v96, v92, 0xbc800000, v81
	v_fmamk_f32 v93, v92, 0xbc800000, v82
	v_fmamk_f32 v95, v92, 0xbc800000, v80
	v_mul_f32_e32 v96, v96, v96
	v_mul_f32_e32 v94, v94, v94
	v_fmac_f32_e32 v96, v95, v95
	v_fmac_f32_e32 v94, v93, v93
	v_fmamk_f32 v95, v92, 0xbc800000, v79
	v_fmamk_f32 v97, v92, 0xbc800000, v77
	v_add_f32_e32 v93, v96, v94
	v_fmamk_f32 v94, v92, 0xbc800000, v78
	v_fmamk_f32 v96, v92, 0xbc800000, v76
	v_mul_f32_e32 v97, v97, v97
	v_mul_f32_e32 v95, v95, v95
	v_fmac_f32_e32 v97, v96, v96
	v_fmac_f32_e32 v95, v94, v94
	v_add_f32_e32 v94, v97, v95
	v_fmamk_f32 v95, v92, 0xbc800000, v75
	v_fmamk_f32 v97, v92, 0xbc800000, v73
	v_add_f32_e32 v93, v93, v94
	v_fmamk_f32 v94, v92, 0xbc800000, v74
	v_fmamk_f32 v96, v92, 0xbc800000, v72
	v_mul_f32_e32 v97, v97, v97
	v_mul_f32_e32 v95, v95, v95
	v_fmac_f32_e32 v97, v96, v96
	v_fmac_f32_e32 v95, v94, v94
	v_add_f32_e32 v94, v97, v95
	v_fmamk_f32 v95, v92, 0xbc800000, v71
	v_fmamk_f32 v97, v92, 0xbc800000, v69
	v_add_f32_e32 v93, v94, v93
	v_fmamk_f32 v94, v92, 0xbc800000, v70
	v_fmamk_f32 v96, v92, 0xbc800000, v68
	v_mul_f32_e32 v97, v97, v97
	v_mul_f32_e32 v95, v95, v95
	v_fmac_f32_e32 v97, v96, v96
	v_fmac_f32_e32 v95, v94, v94
	v_add_f32_e32 v94, v97, v95
	v_add_f32_e32 v93, v94, v93
	v_mov_b32_e32 v94, v93
	s_nop 1
	v_permlane16_swap_b32 v94, v93
	s_waitcnt lgkmcnt(0)
	v_add_f32_e32 v93, v93, v94
	v_mov_b32_e32 v94, v93
	s_nop 1
	v_permlane32_swap_b32 v94, v93
	s_and_saveexec_b64 s[44:45], vcc
	s_cbranch_execz .LBB0_1044
	s_lshl_b32 s8, s5, 11
	s_add_i32 s8, s46, s8
	v_mul_f32_e32 v92, 0x3c800000, v92
	v_lshl_add_u32 v95, v190, 5, s8
	s_waitcnt lgkmcnt(0)
	v_add_f32_e32 v93, v93, v94
	ds_write_b64 v95, v[92:93] offset:1536
.LBB0_1044:
	s_or_b64 exec, exec, s[44:45]
	s_waitcnt vmcnt(7)
	v_lshlrev_b32_e32 v92, 16, v144
	v_and_b32_e32 v93, 0xffff0000, v144
	s_waitcnt lgkmcnt(0)
	v_lshlrev_b32_e32 v94, 16, v145
	v_and_b32_e32 v95, 0xffff0000, v145
	v_lshlrev_b32_e32 v96, 16, v146
	v_and_b32_e32 v97, 0xffff0000, v146
	v_lshlrev_b32_e32 v98, 16, v147
	v_and_b32_e32 v99, 0xffff0000, v147
	v_pk_fma_f32 v[64:65], v[92:93], s[24:25], v[64:65] op_sel_hi:[1,0,1]
	v_pk_fma_f32 v[66:67], v[94:95], s[24:25], v[66:67] op_sel_hi:[1,0,1]
	s_waitcnt vmcnt(6)
	v_lshlrev_b32_e32 v92, 16, v140
	v_and_b32_e32 v93, 0xffff0000, v140
	v_lshlrev_b32_e32 v94, 16, v141
	v_and_b32_e32 v95, 0xffff0000, v141
	v_pk_fma_f32 v[60:61], v[96:97], s[24:25], v[60:61] op_sel_hi:[1,0,1]
	v_pk_fma_f32 v[62:63], v[98:99], s[24:25], v[62:63] op_sel_hi:[1,0,1]
	v_lshlrev_b32_e32 v96, 16, v142
	v_and_b32_e32 v97, 0xffff0000, v142
	v_pk_fma_f32 v[56:57], v[92:93], s[24:25], v[56:57] op_sel_hi:[1,0,1]
	v_pk_fma_f32 v[58:59], v[94:95], s[24:25], v[58:59] op_sel_hi:[1,0,1]
	v_pk_mov_b32 v[92:93], v[64:65], v[66:67] op_sel:[1,0]
	v_mov_b32_e32 v94, v64
	v_mov_b32_e32 v95, v67
	v_pk_fma_f32 v[52:53], v[96:97], s[24:25], v[52:53] op_sel_hi:[1,0,1]
	v_pk_add_f32 v[92:93], v[92:93], v[94:95]
	v_pk_mov_b32 v[94:95], v[60:61], v[62:63] op_sel:[1,0]
	v_mov_b32_e32 v96, v60
	v_mov_b32_e32 v97, v63
	v_lshlrev_b32_e32 v98, 16, v143
	v_and_b32_e32 v99, 0xffff0000, v143
	v_pk_add_f32 v[94:95], v[94:95], v[96:97]
	v_pk_fma_f32 v[54:55], v[98:99], s[24:25], v[54:55] op_sel_hi:[1,0,1]
	v_add_f32_e32 v92, v92, v93
	v_pk_add_f32 v[94:95], v[94:95], v[94:95] op_sel_hi:[0,1]
	v_add_f32_e32 v93, 0, v92
	v_add_f32_e32 v97, v56, v57
	v_add_f32_e32 v99, v58, v59
	v_mov_b32_e32 v96, v52
	v_mov_b32_e32 v98, v53
	v_mov_b32_e32 v94, v54
	v_mov_b32_e32 v92, v55
	v_pk_add_f32 v[96:97], v[96:97], v[98:99]
	v_pk_add_f32 v[92:93], v[94:95], v[92:93]
	s_nop 0
	v_pk_add_f32 v[92:93], v[96:97], v[92:93]
	s_nop 0
	v_add_f32_e32 v92, v92, v93
	v_mov_b32_e32 v93, v92
	s_nop 1
	v_permlane16_swap_b32 v93, v92
	s_waitcnt lgkmcnt(0)
	v_add_f32_e32 v92, v92, v93
	v_mov_b32_e32 v93, v92
	s_nop 1
	v_permlane32_swap_b32 v93, v92
	s_waitcnt lgkmcnt(0)
	v_add_f32_e32 v92, v92, v93
	v_fmamk_f32 v94, v92, 0xbc800000, v67
	v_fmamk_f32 v96, v92, 0xbc800000, v65
	v_fmamk_f32 v93, v92, 0xbc800000, v66
	v_fmamk_f32 v95, v92, 0xbc800000, v64
	v_mul_f32_e32 v96, v96, v96
	v_mul_f32_e32 v94, v94, v94
	v_fmac_f32_e32 v96, v95, v95
	v_fmac_f32_e32 v94, v93, v93
	v_fmamk_f32 v95, v92, 0xbc800000, v63
	v_fmamk_f32 v97, v92, 0xbc800000, v61
	v_add_f32_e32 v93, v96, v94
	v_fmamk_f32 v94, v92, 0xbc800000, v62
	v_fmamk_f32 v96, v92, 0xbc800000, v60
	v_mul_f32_e32 v97, v97, v97
	v_mul_f32_e32 v95, v95, v95
	v_fmac_f32_e32 v97, v96, v96
	v_fmac_f32_e32 v95, v94, v94
	v_add_f32_e32 v94, v97, v95
	v_fmamk_f32 v95, v92, 0xbc800000, v59
	v_fmamk_f32 v97, v92, 0xbc800000, v57
	v_add_f32_e32 v93, v93, v94
	v_fmamk_f32 v94, v92, 0xbc800000, v58
	v_fmamk_f32 v96, v92, 0xbc800000, v56
	v_mul_f32_e32 v97, v97, v97
	v_mul_f32_e32 v95, v95, v95
	v_fmac_f32_e32 v97, v96, v96
	v_fmac_f32_e32 v95, v94, v94
	v_add_f32_e32 v94, v97, v95
	v_fmamk_f32 v95, v92, 0xbc800000, v55
	v_fmamk_f32 v97, v92, 0xbc800000, v53
	v_add_f32_e32 v93, v94, v93
	v_fmamk_f32 v94, v92, 0xbc800000, v54
	v_fmamk_f32 v96, v92, 0xbc800000, v52
	v_mul_f32_e32 v97, v97, v97
	v_mul_f32_e32 v95, v95, v95
	v_fmac_f32_e32 v97, v96, v96
	v_fmac_f32_e32 v95, v94, v94
	v_add_f32_e32 v94, v97, v95
	v_add_f32_e32 v93, v94, v93
	v_mov_b32_e32 v94, v93
	s_nop 1
	v_permlane16_swap_b32 v94, v93
	s_waitcnt lgkmcnt(0)
	v_add_f32_e32 v93, v93, v94
	v_mov_b32_e32 v94, v93
	s_nop 1
	v_permlane32_swap_b32 v94, v93
	s_and_saveexec_b64 s[44:45], vcc
	s_cbranch_execz .LBB0_1046
	s_lshl_b32 s8, s5, 11
	s_add_i32 s8, s46, s8
	v_mul_f32_e32 v92, 0x3c800000, v92
	v_lshl_add_u32 v95, v190, 5, s8
	s_waitcnt lgkmcnt(0)
	v_add_f32_e32 v93, v93, v94
	ds_write_b64 v95, v[92:93] offset:4096
;     __device__ __forceinline__ void run(const f32x4 (&v)[2][2][4][2], const Unit& u, int wr, int wc, int fr, int fq, LAS unsigned char* lds, int wid, int lane) const {
;     ...
;                 float s = 0.f;
; #pragma unroll
;                 for (int bj = 0; bj < 2; ++bj)
; #pragma unroll
;                     for (int n = 0; n < 2; ++n) { const f32x4 x = v[ai][bj][m][n]; s += (x[0] + x[1]) + (x[2] + x[3]); }
;                 s += __shfl_xor(s, 16); s += __shfl_xor(s, 32);
;                 const float mw = s * (1.0f / 64.0f); float q = 0.f;
; #pragma unroll
;                 for (int bj = 0; bj < 2; ++bj)
; #pragma unroll
;                     for (int n = 0; n < 2; ++n) { const f32x4 d = v[ai][bj][m][n] - mw; q += (d[0] * d[0] + d[1] * d[1]) + (d[2] * d[2] + d[3] * d[3]); }
;                 q += __shfl_xor(q, 16); q += __shfl_xor(q, 32);
;                 if (fq == 0) Pt[(ai * HALF + wr * 64 + m * 16 + fr) * 4 + wc] = (f32x2v){mw, q};
;             }
;     __device__ __forceinline__ void fused(f32x4 (&acc)[2][2][4][2], const Unit& u, int wr, int wc, int fr, int fq, LAS unsigned char* lds, int wid, int lane) const {
;     ...
;                     const u32x4 hb = *(const u32x4*)(H + ro + bj * HALF);
;                     const f32x4 h0 = {bflo(hb.x), bfhi(hb.x), bflo(hb.y), bfhi(hb.y)}, h1 = {bflo(hb.z), bfhi(hb.z), bflo(hb.w), bfhi(hb.w)};
;                     acc[ai][bj][m][0] = h0 * ALPHA + acc[ai][bj][m][0]; acc[ai][bj][m][1] = h1 * ALPHA + acc[ai][bj][m][1];
.LBB0_1046:
	s_or_b64 exec, exec, s[44:45]
	s_waitcnt vmcnt(5)
	v_lshlrev_b32_e32 v92, 16, v132
	v_and_b32_e32 v93, 0xffff0000, v132
	s_waitcnt lgkmcnt(0)
	v_lshlrev_b32_e32 v94, 16, v133
	v_and_b32_e32 v95, 0xffff0000, v133
	v_lshlrev_b32_e32 v96, 16, v134
	v_and_b32_e32 v97, 0xffff0000, v134
	v_lshlrev_b32_e32 v134, 16, v135
	v_and_b32_e32 v135, 0xffff0000, v135
	v_pk_fma_f32 v[132:133], v[92:93], s[24:25], v[48:49] op_sel_hi:[1,0,1]
	v_pk_fma_f32 v[140:141], v[94:95], s[24:25], v[50:51] op_sel_hi:[1,0,1]
	v_pk_fma_f32 v[98:99], v[96:97], s[24:25], v[44:45] op_sel_hi:[1,0,1]
	v_pk_fma_f32 v[134:135], v[134:135], s[24:25], v[46:47] op_sel_hi:[1,0,1]
	s_waitcnt vmcnt(4)
	v_lshlrev_b32_e32 v44, 16, v124
	v_and_b32_e32 v45, 0xffff0000, v124
	v_lshlrev_b32_e32 v46, 16, v125
	v_and_b32_e32 v47, 0xffff0000, v125
	v_lshlrev_b32_e32 v48, 16, v126
	v_and_b32_e32 v49, 0xffff0000, v126
	v_pk_fma_f32 v[40:41], v[44:45], s[24:25], v[40:41] op_sel_hi:[1,0,1]
	v_pk_fma_f32 v[42:43], v[46:47], s[24:25], v[42:43] op_sel_hi:[1,0,1]
	v_pk_mov_b32 v[44:45], v[132:133], v[140:141] op_sel:[1,0]
	v_mov_b32_e32 v46, v132
	v_mov_b32_e32 v47, v141
	v_pk_fma_f32 v[36:37], v[48:49], s[24:25], v[36:37] op_sel_hi:[1,0,1]
	v_pk_add_f32 v[44:45], v[44:45], v[46:47]
	v_pk_mov_b32 v[46:47], v[98:99], v[134:135] op_sel:[1,0]
	v_mov_b32_e32 v48, v98
	v_mov_b32_e32 v49, v135
	v_lshlrev_b32_e32 v50, 16, v127
	v_and_b32_e32 v51, 0xffff0000, v127
	v_pk_add_f32 v[46:47], v[46:47], v[48:49]
	v_pk_fma_f32 v[38:39], v[50:51], s[24:25], v[38:39] op_sel_hi:[1,0,1]
	v_add_f32_e32 v44, v44, v45
	v_pk_add_f32 v[46:47], v[46:47], v[46:47] op_sel_hi:[0,1]
	v_add_f32_e32 v45, 0, v44
	v_add_f32_e32 v49, v40, v41
	v_add_f32_e32 v51, v42, v43
	v_mov_b32_e32 v48, v36
	v_mov_b32_e32 v50, v37
	v_mov_b32_e32 v46, v38
	v_mov_b32_e32 v44, v39
	v_pk_add_f32 v[48:49], v[48:49], v[50:51]
	v_pk_add_f32 v[44:45], v[46:47], v[44:45]
	s_nop 0
	v_pk_add_f32 v[44:45], v[48:49], v[44:45]
	s_nop 0
	v_add_f32_e32 v44, v44, v45
	v_mov_b32_e32 v45, v44
	s_nop 1
	v_permlane16_swap_b32 v45, v44
	s_waitcnt lgkmcnt(0)
	v_add_f32_e32 v44, v44, v45
	v_mov_b32_e32 v45, v44
	s_nop 1
	v_permlane32_swap_b32 v45, v44
	s_waitcnt lgkmcnt(0)
	v_add_f32_e32 v44, v44, v45
	v_fmamk_f32 v46, v44, 0xbc800000, v141
	v_fmamk_f32 v48, v44, 0xbc800000, v133
	v_fmamk_f32 v45, v44, 0xbc800000, v140
	v_fmamk_f32 v47, v44, 0xbc800000, v132
	v_mul_f32_e32 v48, v48, v48
	v_mul_f32_e32 v46, v46, v46
	v_fmac_f32_e32 v48, v47, v47
	v_fmac_f32_e32 v46, v45, v45
	v_fmamk_f32 v47, v44, 0xbc800000, v135
	v_fmamk_f32 v49, v44, 0xbc800000, v99
	v_add_f32_e32 v45, v48, v46
	v_fmamk_f32 v46, v44, 0xbc800000, v134
	v_fmamk_f32 v48, v44, 0xbc800000, v98
	v_mul_f32_e32 v49, v49, v49
	v_mul_f32_e32 v47, v47, v47
	v_fmac_f32_e32 v49, v48, v48
	v_fmac_f32_e32 v47, v46, v46
	v_add_f32_e32 v46, v49, v47
	v_fmamk_f32 v47, v44, 0xbc800000, v43
	v_fmamk_f32 v49, v44, 0xbc800000, v41
	v_add_f32_e32 v45, v45, v46
	v_fmamk_f32 v46, v44, 0xbc800000, v42
	v_fmamk_f32 v48, v44, 0xbc800000, v40
	v_mul_f32_e32 v49, v49, v49
	v_mul_f32_e32 v47, v47, v47
	v_fmac_f32_e32 v49, v48, v48
	v_fmac_f32_e32 v47, v46, v46
	v_add_f32_e32 v46, v49, v47
	v_fmamk_f32 v47, v44, 0xbc800000, v39
	v_fmamk_f32 v49, v44, 0xbc800000, v37
	v_add_f32_e32 v45, v46, v45
	v_fmamk_f32 v46, v44, 0xbc800000, v38
	v_fmamk_f32 v48, v44, 0xbc800000, v36
	v_mul_f32_e32 v49, v49, v49
	v_mul_f32_e32 v47, v47, v47
	v_fmac_f32_e32 v49, v48, v48
	v_fmac_f32_e32 v47, v46, v46
	v_add_f32_e32 v46, v49, v47
	v_add_f32_e32 v45, v46, v45
	v_mov_b32_e32 v46, v45
	s_nop 1
	v_permlane16_swap_b32 v46, v45
	s_waitcnt lgkmcnt(0)
	v_add_f32_e32 v45, v45, v46
	v_mov_b32_e32 v46, v45
	s_nop 1
	v_permlane32_swap_b32 v46, v45
	s_and_saveexec_b64 s[44:45], vcc
	s_cbranch_execz .LBB0_1048
	s_lshl_b32 s8, s5, 11
	s_add_i32 s8, s46, s8
	v_mul_f32_e32 v44, 0x3c800000, v44
	v_lshl_add_u32 v47, v190, 5, s8
	s_waitcnt lgkmcnt(0)
	v_add_f32_e32 v45, v45, v46
	ds_write_b64 v47, v[44:45] offset:4608
.LBB0_1048:
	s_or_b64 exec, exec, s[44:45]
	s_waitcnt vmcnt(3)
	v_lshlrev_b32_e32 v44, 16, v120
	v_and_b32_e32 v45, 0xffff0000, v120
	s_waitcnt lgkmcnt(0)
	v_lshlrev_b32_e32 v46, 16, v121
	v_and_b32_e32 v47, 0xffff0000, v121
	v_lshlrev_b32_e32 v48, 16, v122
	v_and_b32_e32 v49, 0xffff0000, v122
	v_lshlrev_b32_e32 v50, 16, v123
	v_and_b32_e32 v51, 0xffff0000, v123
	v_pk_fma_f32 v[122:123], v[44:45], s[24:25], v[32:33] op_sel_hi:[1,0,1]
	v_pk_fma_f32 v[126:127], v[46:47], s[24:25], v[34:35] op_sel_hi:[1,0,1]
	s_waitcnt vmcnt(2)
	v_lshlrev_b32_e32 v32, 16, v118
	v_and_b32_e32 v33, 0xffff0000, v118
	v_lshlrev_b32_e32 v44, 16, v119
	v_and_b32_e32 v45, 0xffff0000, v119
	v_pk_fma_f32 v[120:121], v[48:49], s[24:25], v[28:29] op_sel_hi:[1,0,1]
	v_pk_fma_f32 v[124:125], v[50:51], s[24:25], v[30:31] op_sel_hi:[1,0,1]
	v_lshlrev_b32_e32 v28, 16, v116
	v_and_b32_e32 v29, 0xffff0000, v116
	v_pk_fma_f32 v[44:45], v[44:45], s[24:25], v[22:23] op_sel_hi:[1,0,1]
	v_pk_fma_f32 v[46:47], v[32:33], s[24:25], v[20:21] op_sel_hi:[1,0,1]
	v_pk_mov_b32 v[20:21], v[122:123], v[126:127] op_sel:[1,0]
	v_mov_b32_e32 v22, v122
	v_mov_b32_e32 v23, v127
	v_pk_fma_f32 v[34:35], v[28:29], s[24:25], v[24:25] op_sel_hi:[1,0,1]
	v_pk_add_f32 v[20:21], v[20:21], v[22:23]
	v_pk_mov_b32 v[22:23], v[120:121], v[124:125] op_sel:[1,0]
	v_mov_b32_e32 v24, v120
	v_mov_b32_e32 v25, v125
	v_lshlrev_b32_e32 v30, 16, v117
	v_and_b32_e32 v31, 0xffff0000, v117
	v_pk_add_f32 v[22:23], v[22:23], v[24:25]
	v_pk_fma_f32 v[48:49], v[30:31], s[24:25], v[26:27] op_sel_hi:[1,0,1]
	v_add_f32_e32 v20, v20, v21
	v_pk_add_f32 v[22:23], v[22:23], v[22:23] op_sel_hi:[0,1]
	v_add_f32_e32 v21, 0, v20
	v_add_f32_e32 v25, v34, v35
	v_add_f32_e32 v27, v48, v49
	v_mov_b32_e32 v24, v46
	v_mov_b32_e32 v26, v47
	v_mov_b32_e32 v22, v44
	v_mov_b32_e32 v20, v45
	v_pk_add_f32 v[24:25], v[24:25], v[26:27]
	v_pk_add_f32 v[20:21], v[22:23], v[20:21]
	s_nop 0
	v_pk_add_f32 v[20:21], v[24:25], v[20:21]
	s_nop 0
	v_add_f32_e32 v20, v20, v21
	v_mov_b32_e32 v21, v20
	s_nop 1
	v_permlane16_swap_b32 v21, v20
	s_waitcnt lgkmcnt(0)
;     __device__ __forceinline__ void run(const f32x4 (&v)[2][2][4][2], const Unit& u, int wr, int wc, int fr, int fq, LAS unsigned char* lds, int wid, int lane) const {
;     ...
;                 float s = 0.f;
; #pragma unroll
;                 for (int bj = 0; bj < 2; ++bj)
; #pragma unroll
;                     for (int n = 0; n < 2; ++n) { const f32x4 x = v[ai][bj][m][n]; s += (x[0] + x[1]) + (x[2] + x[3]); }
;                 s += __shfl_xor(s, 16); s += __shfl_xor(s, 32);
;                 const float mw = s * (1.0f / 64.0f); float q = 0.f;
; #pragma unroll
;                 for (int bj = 0; bj < 2; ++bj)
; #pragma unroll
;                     for (int n = 0; n < 2; ++n) { const f32x4 d = v[ai][bj][m][n] - mw; q += (d[0] * d[0] + d[1] * d[1]) + (d[2] * d[2] + d[3] * d[3]); }
;                 q += __shfl_xor(q, 16); q += __shfl_xor(q, 32);
;                 if (fq == 0) Pt[(ai * HALF + wr * 64 + m * 16 + fr) * 4 + wc] = (f32x2v){mw, q};
;             }
;     __device__ __forceinline__ void fused(f32x4 (&acc)[2][2][4][2], const Unit& u, int wr, int wc, int fr, int fq, LAS unsigned char* lds, int wid, int lane) const {
;     ...
;                     const u32x4 hb = *(const u32x4*)(H + ro + bj * HALF);
;                     const f32x4 h0 = {bflo(hb.x), bfhi(hb.x), bflo(hb.y), bfhi(hb.y)}, h1 = {bflo(hb.z), bfhi(hb.z), bflo(hb.w), bfhi(hb.w)};
;                     acc[ai][bj][m][0] = h0 * ALPHA + acc[ai][bj][m][0]; acc[ai][bj][m][1] = h1 * ALPHA + acc[ai][bj][m][1];
	v_add_f32_e32 v20, v20, v21
	v_mov_b32_e32 v21, v20
	s_nop 1
	v_permlane32_swap_b32 v21, v20
	s_waitcnt lgkmcnt(0)
	v_add_f32_e32 v20, v20, v21
	v_fmamk_f32 v22, v20, 0xbc800000, v127
	v_fmamk_f32 v24, v20, 0xbc800000, v123
	v_fmamk_f32 v21, v20, 0xbc800000, v126
	v_fmamk_f32 v23, v20, 0xbc800000, v122
	v_mul_f32_e32 v24, v24, v24
	v_mul_f32_e32 v22, v22, v22
	v_fmac_f32_e32 v24, v23, v23
	v_fmac_f32_e32 v22, v21, v21
	v_fmamk_f32 v23, v20, 0xbc800000, v125
	v_fmamk_f32 v25, v20, 0xbc800000, v121
	v_add_f32_e32 v21, v24, v22
	v_fmamk_f32 v22, v20, 0xbc800000, v124
	v_fmamk_f32 v24, v20, 0xbc800000, v120
	v_mul_f32_e32 v25, v25, v25
	v_mul_f32_e32 v23, v23, v23
	v_fmac_f32_e32 v25, v24, v24
	v_fmac_f32_e32 v23, v22, v22
	v_add_f32_e32 v22, v25, v23
	v_fmamk_f32 v23, v20, 0xbc800000, v49
	v_fmamk_f32 v25, v20, 0xbc800000, v35
	v_add_f32_e32 v21, v21, v22
	v_fmamk_f32 v22, v20, 0xbc800000, v48
	v_fmamk_f32 v24, v20, 0xbc800000, v34
	v_mul_f32_e32 v25, v25, v25
	v_mul_f32_e32 v23, v23, v23
	v_fmac_f32_e32 v25, v24, v24
	v_fmac_f32_e32 v23, v22, v22
	v_add_f32_e32 v22, v25, v23
	v_fmamk_f32 v23, v20, 0xbc800000, v45
	v_fmamk_f32 v25, v20, 0xbc800000, v47
	v_add_f32_e32 v21, v22, v21
	v_fmamk_f32 v22, v20, 0xbc800000, v44
	v_fmamk_f32 v24, v20, 0xbc800000, v46
	v_mul_f32_e32 v25, v25, v25
	v_mul_f32_e32 v23, v23, v23
	v_fmac_f32_e32 v25, v24, v24
	v_fmac_f32_e32 v23, v22, v22
	v_add_f32_e32 v22, v25, v23
	v_add_f32_e32 v21, v22, v21
	v_mov_b32_e32 v22, v21
	s_nop 1
	v_permlane16_swap_b32 v22, v21
	s_waitcnt lgkmcnt(0)
	v_add_f32_e32 v21, v21, v22
	v_mov_b32_e32 v22, v21
	s_nop 1
	v_permlane32_swap_b32 v22, v21
	s_and_saveexec_b64 s[44:45], vcc
	s_cbranch_execz .LBB0_1050
	s_lshl_b32 s8, s5, 11
	s_add_i32 s8, s46, s8
	v_mul_f32_e32 v20, 0x3c800000, v20
	v_lshl_add_u32 v23, v190, 5, s8
	s_waitcnt lgkmcnt(0)
	v_add_f32_e32 v21, v21, v22
	ds_write_b64 v23, v[20:21] offset:5120
.LBB0_1050:
	s_or_b64 exec, exec, s[44:45]
	s_waitcnt vmcnt(1)
	v_lshlrev_b32_e32 v20, 16, v136
	v_and_b32_e32 v21, 0xffff0000, v136
	s_waitcnt lgkmcnt(0)
	v_lshlrev_b32_e32 v22, 16, v137
	v_and_b32_e32 v23, 0xffff0000, v137
	v_lshlrev_b32_e32 v24, 16, v138
	v_and_b32_e32 v25, 0xffff0000, v138
	v_lshlrev_b32_e32 v26, 16, v139
	v_and_b32_e32 v27, 0xffff0000, v139
	v_pk_fma_f32 v[118:119], v[20:21], s[24:25], v[16:17] op_sel_hi:[1,0,1]
	v_pk_fma_f32 v[138:139], v[22:23], s[24:25], v[18:19] op_sel_hi:[1,0,1]
	s_waitcnt vmcnt(0)
	v_lshlrev_b32_e32 v16, 16, v130
	v_and_b32_e32 v17, 0xffff0000, v130
	v_lshlrev_b32_e32 v18, 16, v131
	v_and_b32_e32 v19, 0xffff0000, v131
	v_pk_fma_f32 v[116:117], v[24:25], s[24:25], v[12:13] op_sel_hi:[1,0,1]
	v_pk_fma_f32 v[136:137], v[26:27], s[24:25], v[14:15] op_sel_hi:[1,0,1]
	v_lshlrev_b32_e32 v12, 16, v128
	v_and_b32_e32 v13, 0xffff0000, v128
	v_pk_fma_f32 v[92:93], v[18:19], s[24:25], v[6:7] op_sel_hi:[1,0,1]
	v_pk_fma_f32 v[94:95], v[16:17], s[24:25], v[4:5] op_sel_hi:[1,0,1]
	v_pk_mov_b32 v[4:5], v[118:119], v[138:139] op_sel:[1,0]
	v_mov_b32_e32 v6, v118
	v_mov_b32_e32 v7, v139
	v_pk_fma_f32 v[50:51], v[12:13], s[24:25], v[8:9] op_sel_hi:[1,0,1]
	v_pk_add_f32 v[4:5], v[4:5], v[6:7]
	v_pk_mov_b32 v[6:7], v[116:117], v[136:137] op_sel:[1,0]
	v_mov_b32_e32 v8, v116
	v_mov_b32_e32 v9, v137
	v_lshlrev_b32_e32 v14, 16, v129
	v_and_b32_e32 v15, 0xffff0000, v129
	v_pk_add_f32 v[6:7], v[6:7], v[8:9]
	v_pk_fma_f32 v[96:97], v[14:15], s[24:25], v[10:11] op_sel_hi:[1,0,1]
	v_add_f32_e32 v4, v4, v5
	v_pk_add_f32 v[6:7], v[6:7], v[6:7] op_sel_hi:[0,1]
	v_add_f32_e32 v5, 0, v4
	v_add_f32_e32 v9, v50, v51
	v_add_f32_e32 v11, v96, v97
	v_mov_b32_e32 v8, v94
	v_mov_b32_e32 v10, v95
	v_mov_b32_e32 v6, v92
	v_mov_b32_e32 v4, v93
	v_pk_add_f32 v[8:9], v[8:9], v[10:11]
	v_pk_add_f32 v[4:5], v[6:7], v[4:5]
	s_nop 0
	v_pk_add_f32 v[4:5], v[8:9], v[4:5]
	s_nop 0
	v_add_f32_e32 v4, v4, v5
	v_mov_b32_e32 v5, v4
	s_nop 1
	v_permlane16_swap_b32 v5, v4
	s_waitcnt lgkmcnt(0)
	v_add_f32_e32 v4, v4, v5
	v_mov_b32_e32 v5, v4
	s_nop 1
	v_permlane32_swap_b32 v5, v4
	s_waitcnt lgkmcnt(0)
	v_add_f32_e32 v4, v4, v5
	v_fmamk_f32 v6, v4, 0xbc800000, v139
	v_fmamk_f32 v8, v4, 0xbc800000, v119
	v_fmamk_f32 v5, v4, 0xbc800000, v138
	v_fmamk_f32 v7, v4, 0xbc800000, v118
	v_mul_f32_e32 v8, v8, v8
	v_mul_f32_e32 v6, v6, v6
	v_fmac_f32_e32 v8, v7, v7
	v_fmac_f32_e32 v6, v5, v5
	v_fmamk_f32 v7, v4, 0xbc800000, v137
	v_fmamk_f32 v9, v4, 0xbc800000, v117
	v_add_f32_e32 v5, v8, v6
	v_fmamk_f32 v6, v4, 0xbc800000, v136
	v_fmamk_f32 v8, v4, 0xbc800000, v116
	v_mul_f32_e32 v9, v9, v9
	v_mul_f32_e32 v7, v7, v7
	v_fmac_f32_e32 v9, v8, v8
	v_fmac_f32_e32 v7, v6, v6
	v_add_f32_e32 v6, v9, v7
	v_fmamk_f32 v7, v4, 0xbc800000, v97
	v_fmamk_f32 v9, v4, 0xbc800000, v51
	v_add_f32_e32 v5, v5, v6
	v_fmamk_f32 v6, v4, 0xbc800000, v96
	v_fmamk_f32 v8, v4, 0xbc800000, v50
	v_mul_f32_e32 v9, v9, v9
	v_mul_f32_e32 v7, v7, v7
	v_fmac_f32_e32 v9, v8, v8
	v_fmac_f32_e32 v7, v6, v6
	v_add_f32_e32 v6, v9, v7
	v_fmamk_f32 v7, v4, 0xbc800000, v93
	v_fmamk_f32 v9, v4, 0xbc800000, v95
	v_add_f32_e32 v5, v6, v5
	v_fmamk_f32 v6, v4, 0xbc800000, v92
	v_fmamk_f32 v8, v4, 0xbc800000, v94
	v_mul_f32_e32 v9, v9, v9
	v_mul_f32_e32 v7, v7, v7
	v_fmac_f32_e32 v9, v8, v8
	v_fmac_f32_e32 v7, v6, v6
	v_add_f32_e32 v6, v9, v7
	v_add_f32_e32 v5, v6, v5
	v_mov_b32_e32 v6, v5
	s_nop 1
	v_permlane16_swap_b32 v6, v5
	s_waitcnt lgkmcnt(0)
	v_add_f32_e32 v5, v5, v6
	v_mov_b32_e32 v6, v5
	s_nop 1
	v_permlane32_swap_b32 v6, v5
	s_and_saveexec_b64 s[44:45], vcc
	s_cbranch_execz .LBB0_1052
	s_lshl_b32 s5, s5, 11
	s_add_i32 s46, s46, s5
	v_mul_f32_e32 v4, 0x3c800000, v4
	v_lshl_add_u32 v7, v190, 5, s46
	s_waitcnt lgkmcnt(0)
	v_add_f32_e32 v5, v5, v6
	ds_write_b64 v7, v[4:5] offset:5632

;     __device__ __forceinline__ void run(const f32x4 (&v)[2][2][4][2], const Unit& u, int wr, int wc, int fr, int fq, LAS unsigned char* lds, int wid, int lane) const {
;     ...
;                 float s = 0.f;
; #pragma unroll
;                 for (int bj = 0; bj < 2; ++bj)
; #pragma unroll
;                     for (int n = 0; n < 2; ++n) { const f32x4 x = v[ai][bj][m][n]; s += (x[0] + x[1]) + (x[2] + x[3]); }
;                 s += __shfl_xor(s, 16); s += __shfl_xor(s, 32);
;                 const float mw = s * (1.0f / 64.0f); float q = 0.f;
; #pragma unroll
;                 for (int bj = 0; bj < 2; ++bj)
; #pragma unroll
;                     for (int n = 0; n < 2; ++n) { const f32x4 d = v[ai][bj][m][n] - mw; q += (d[0] * d[0] + d[1] * d[1]) + (d[2] * d[2] + d[3] * d[3]); }
;                 q += __shfl_xor(q, 16); q += __shfl_xor(q, 32);
;                 if (fq == 0) Pt[(ai * HALF + wr * 64 + m * 16 + fr) * 4 + wc] = (f32x2v){mw, q};
;             }
;     __device__ __forceinline__ void fused(f32x4 (&acc)[2][2][4][2], const Unit& u, int wr, int wc, int fr, int fq, LAS unsigned char* lds, int wid, int lane) const {
;     ...
;                     const u32x4 hb = *(const u32x4*)(H + ro + bj * HALF);
;                     const f32x4 h0 = {bflo(hb.x), bfhi(hb.x), bflo(hb.y), bfhi(hb.y)}, h1 = {bflo(hb.z), bfhi(hb.z), bflo(hb.w), bfhi(hb.w)};
;                     acc[ai][bj][m][0] = h0 * ALPHA + acc[ai][bj][m][0]; acc[ai][bj][m][1] = h1 * ALPHA + acc[ai][bj][m][1];
.LBB0_1089:
	s_or_b64 exec, exec, s[44:45]
	s_waitcnt vmcnt(0)
	v_lshlrev_b32_e32 v196, 16, v192
	v_and_b32_e32 v197, 0xffff0000, v192
	v_lshlrev_b32_e32 v192, 16, v193
	v_and_b32_e32 v193, 0xffff0000, v193
	v_lshlrev_b32_e32 v198, 16, v194
	v_and_b32_e32 v199, 0xffff0000, v194
	v_lshlrev_b32_e32 v194, 16, v195
	v_and_b32_e32 v195, 0xffff0000, v195
	v_pk_fma_f32 v[128:129], v[196:197], s[24:25], v[128:129] op_sel_hi:[1,0,1]
	v_pk_fma_f32 v[130:131], v[192:193], s[24:25], v[130:131] op_sel_hi:[1,0,1]
	v_pk_fma_f32 v[126:127], v[194:195], s[24:25], v[126:127] op_sel_hi:[1,0,1]
	v_lshlrev_b32_e32 v192, 16, v188
	v_and_b32_e32 v193, 0xffff0000, v188
	v_lshlrev_b32_e32 v194, 16, v190
	v_and_b32_e32 v195, 0xffff0000, v190
	v_lshlrev_b32_e32 v190, 16, v191
	v_and_b32_e32 v191, 0xffff0000, v191
	v_pk_fma_f32 v[124:125], v[198:199], s[24:25], v[124:125] op_sel_hi:[1,0,1]
	v_pk_fma_f32 v[120:121], v[192:193], s[24:25], v[120:121] op_sel_hi:[1,0,1]
	v_pk_fma_f32 v[118:119], v[190:191], s[24:25], v[118:119] op_sel_hi:[1,0,1]
	v_pk_mov_b32 v[190:191], v[128:129], v[130:131] op_sel:[1,0]
	v_mov_b32_e32 v192, v128
	v_mov_b32_e32 v193, v131
	v_pk_fma_f32 v[116:117], v[194:195], s[24:25], v[116:117] op_sel_hi:[1,0,1]
	v_pk_add_f32 v[190:191], v[190:191], v[192:193]
	v_pk_mov_b32 v[192:193], v[124:125], v[126:127] op_sel:[1,0]
	v_mov_b32_e32 v194, v124
	v_mov_b32_e32 v195, v127
	v_lshlrev_b32_e32 v188, 16, v189
	v_and_b32_e32 v189, 0xffff0000, v189
	v_pk_add_f32 v[192:193], v[192:193], v[194:195]
	v_pk_fma_f32 v[122:123], v[188:189], s[24:25], v[122:123] op_sel_hi:[1,0,1]
	v_and_b32_e32 v189, 64, v217
	v_add_f32_e32 v190, v190, v191
	v_pk_add_f32 v[192:193], v[192:193], v[192:193] op_sel_hi:[0,1]
	v_xor_b32_e32 v188, 16, v217
	v_add_u32_e32 v189, 64, v189
	v_add_f32_e32 v191, 0, v190
	v_add_f32_e32 v195, v120, v121
	v_add_f32_e32 v197, v122, v123
	v_mov_b32_e32 v194, v116
	v_mov_b32_e32 v196, v117
	v_mov_b32_e32 v192, v118
	v_mov_b32_e32 v190, v119
	v_cmp_lt_i32_e32 vcc, v188, v189
	v_pk_add_f32 v[194:195], v[194:195], v[196:197]
	v_pk_add_f32 v[190:191], v[192:193], v[190:191]
	v_cndmask_b32_e32 v188, v217, v188, vcc
	v_pk_add_f32 v[190:191], v[194:195], v[190:191]
	v_lshlrev_b32_e32 v188, 2, v188
	v_add_f32_e32 v190, v190, v191
	v_mov_b32_e32 v191, v190
	s_nop 1
	v_permlane16_swap_b32 v191, v190
	v_xor_b32_e32 v192, 32, v217
	v_cmp_lt_i32_e32 vcc, v192, v189
	s_lshl_b32 s8, s82, 3
	s_add_i32 s36, s8, 0
	v_cndmask_b32_e32 v189, v217, v192, vcc
	v_lshlrev_b32_e32 v189, 2, v189
	s_waitcnt lgkmcnt(0)
	v_add_f32_e32 v190, v190, v191
	v_mov_b32_e32 v191, v190
	s_nop 1
	v_permlane32_swap_b32 v191, v190
	s_waitcnt lgkmcnt(0)
	v_add_f32_e32 v191, v190, v191
	v_fmamk_f32 v192, v191, 0xbc800000, v131
	v_fmamk_f32 v194, v191, 0xbc800000, v129
	v_fmamk_f32 v190, v191, 0xbc800000, v130
	v_fmamk_f32 v193, v191, 0xbc800000, v128
	v_mul_f32_e32 v194, v194, v194
	v_mul_f32_e32 v192, v192, v192
	v_fmac_f32_e32 v194, v193, v193
	v_fmac_f32_e32 v192, v190, v190
	v_fmamk_f32 v193, v191, 0xbc800000, v127
	v_fmamk_f32 v195, v191, 0xbc800000, v125
	v_add_f32_e32 v190, v194, v192
	v_fmamk_f32 v192, v191, 0xbc800000, v126
	v_fmamk_f32 v194, v191, 0xbc800000, v124
	v_mul_f32_e32 v195, v195, v195
	v_mul_f32_e32 v193, v193, v193
	v_fmac_f32_e32 v195, v194, v194
	v_fmac_f32_e32 v193, v192, v192
	v_add_f32_e32 v192, v195, v193
	v_fmamk_f32 v193, v191, 0xbc800000, v123
	v_fmamk_f32 v195, v191, 0xbc800000, v121
	v_add_f32_e32 v190, v190, v192
	v_fmamk_f32 v192, v191, 0xbc800000, v122
	v_fmamk_f32 v194, v191, 0xbc800000, v120
	v_mul_f32_e32 v195, v195, v195
	v_mul_f32_e32 v193, v193, v193
	v_fmac_f32_e32 v195, v194, v194
	v_fmac_f32_e32 v193, v192, v192
	v_add_f32_e32 v192, v195, v193
	v_fmamk_f32 v193, v191, 0xbc800000, v119
	v_fmamk_f32 v195, v191, 0xbc800000, v117
	v_add_f32_e32 v190, v192, v190
	v_fmamk_f32 v192, v191, 0xbc800000, v118
	v_fmamk_f32 v194, v191, 0xbc800000, v116
	v_mul_f32_e32 v195, v195, v195
	v_mul_f32_e32 v193, v193, v193
	v_fmac_f32_e32 v195, v194, v194
	v_fmac_f32_e32 v193, v192, v192
	v_add_f32_e32 v192, v195, v193
	v_add_f32_e32 v190, v192, v190
	v_mov_b32_e32 v192, v190
	s_nop 1
	v_permlane16_swap_b32 v192, v190
	s_waitcnt lgkmcnt(0)
	v_add_f32_e32 v192, v190, v192
	v_mov_b32_e32 v193, v192
	s_nop 1
	v_permlane32_swap_b32 v193, v192
	v_and_b32_e32 v190, 63, v227
	v_cmp_gt_u32_e64 s[44:45], 16, v190
	s_and_saveexec_b64 s[46:47], s[44:45]
	v_readlane_b32 s84, v255, 34
	v_readlane_b32 s62, v255, 40
	v_readlane_b32 s72, v255, 22
	v_readlane_b32 s85, v255, 35
	s_mov_b32 s66, 0xf800000
	v_readlane_b32 s63, v255, 41
	v_readlane_b32 s73, v255, 23
	s_cbranch_execz .LBB0_1091
	s_lshl_b32 s8, s83, 11
	s_add_i32 s8, s36, s8
	v_mul_f32_e32 v194, 0x3c800000, v191
	v_lshl_add_u32 v191, v228, 5, s8
	s_waitcnt lgkmcnt(0)
	v_add_f32_e32 v195, v192, v193
	ds_write_b64 v191, v[194:195]
;     __device__ __forceinline__ void run(const f32x4 (&v)[2][2][4][2], const Unit& u, int wr, int wc, int fr, int fq, LAS unsigned char* lds, int wid, int lane) const {
;     ...
;                 float s = 0.f;
; #pragma unroll
;                 for (int bj = 0; bj < 2; ++bj)
; #pragma unroll
;                     for (int n = 0; n < 2; ++n) { const f32x4 x = v[ai][bj][m][n]; s += (x[0] + x[1]) + (x[2] + x[3]); }
;                 s += __shfl_xor(s, 16); s += __shfl_xor(s, 32);
;                 const float mw = s * (1.0f / 64.0f); float q = 0.f;
; #pragma unroll
;                 for (int bj = 0; bj < 2; ++bj)
; #pragma unroll
;                     for (int n = 0; n < 2; ++n) { const f32x4 d = v[ai][bj][m][n] - mw; q += (d[0] * d[0] + d[1] * d[1]) + (d[2] * d[2] + d[3] * d[3]); }
;                 q += __shfl_xor(q, 16); q += __shfl_xor(q, 32);
;                 if (fq == 0) Pt[(ai * HALF + wr * 64 + m * 16 + fr) * 4 + wc] = (f32x2v){mw, q};
;             }
;     __device__ __forceinline__ void fused(f32x4 (&acc)[2][2][4][2], const Unit& u, int wr, int wc, int fr, int fq, LAS unsigned char* lds, int wid, int lane) const {
;     ...
;                     const u32x4 hb = *(const u32x4*)(H + ro + bj * HALF);
;                     const f32x4 h0 = {bflo(hb.x), bfhi(hb.x), bflo(hb.y), bfhi(hb.y)}, h1 = {bflo(hb.z), bfhi(hb.z), bflo(hb.w), bfhi(hb.w)};
;                     acc[ai][bj][m][0] = h0 * ALPHA + acc[ai][bj][m][0]; acc[ai][bj][m][1] = h1 * ALPHA + acc[ai][bj][m][1];
.LBB0_1091:
	s_or_b64 exec, exec, s[46:47]
	v_lshlrev_b32_e32 v192, 16, v184
	s_waitcnt lgkmcnt(0)
	v_and_b32_e32 v193, 0xffff0000, v184
	v_lshlrev_b32_e32 v184, 16, v185
	v_and_b32_e32 v185, 0xffff0000, v185
	v_lshlrev_b32_e32 v194, 16, v186
	v_and_b32_e32 v195, 0xffff0000, v186
	v_lshlrev_b32_e32 v186, 16, v187
	v_and_b32_e32 v187, 0xffff0000, v187
	v_pk_fma_f32 v[112:113], v[192:193], s[24:25], v[112:113] op_sel_hi:[1,0,1]
	v_pk_fma_f32 v[114:115], v[184:185], s[24:25], v[114:115] op_sel_hi:[1,0,1]
	v_pk_fma_f32 v[110:111], v[186:187], s[24:25], v[110:111] op_sel_hi:[1,0,1]
	v_lshlrev_b32_e32 v184, 16, v180
	v_and_b32_e32 v185, 0xffff0000, v180
	v_lshlrev_b32_e32 v180, 16, v181
	v_and_b32_e32 v181, 0xffff0000, v181
	v_lshlrev_b32_e32 v186, 16, v182
	v_and_b32_e32 v187, 0xffff0000, v182
	v_lshlrev_b32_e32 v182, 16, v183
	v_and_b32_e32 v183, 0xffff0000, v183
	v_pk_fma_f32 v[108:109], v[194:195], s[24:25], v[108:109] op_sel_hi:[1,0,1]
	v_pk_fma_f32 v[106:107], v[180:181], s[24:25], v[106:107] op_sel_hi:[1,0,1]
	v_pk_fma_f32 v[102:103], v[182:183], s[24:25], v[102:103] op_sel_hi:[1,0,1]
	v_pk_mov_b32 v[180:181], v[112:113], v[114:115] op_sel:[1,0]
	v_mov_b32_e32 v182, v112
	v_mov_b32_e32 v183, v115
	v_pk_fma_f32 v[104:105], v[184:185], s[24:25], v[104:105] op_sel_hi:[1,0,1]
	v_pk_add_f32 v[180:181], v[180:181], v[182:183]
	v_pk_mov_b32 v[182:183], v[108:109], v[110:111] op_sel:[1,0]
	v_mov_b32_e32 v184, v108
	v_mov_b32_e32 v185, v111
	v_pk_add_f32 v[182:183], v[182:183], v[184:185]
	v_pk_fma_f32 v[100:101], v[186:187], s[24:25], v[100:101] op_sel_hi:[1,0,1]
	v_add_f32_e32 v180, v180, v181
	v_pk_add_f32 v[182:183], v[182:183], v[182:183] op_sel_hi:[0,1]
	v_add_f32_e32 v181, 0, v180
	v_add_f32_e32 v185, v104, v105
	v_add_f32_e32 v187, v106, v107
	v_mov_b32_e32 v184, v100
	v_mov_b32_e32 v186, v101
	v_mov_b32_e32 v182, v102
	v_mov_b32_e32 v180, v103
	v_pk_add_f32 v[184:185], v[184:185], v[186:187]
	v_pk_add_f32 v[180:181], v[182:183], v[180:181]
	s_nop 0
	v_pk_add_f32 v[180:181], v[184:185], v[180:181]
	s_nop 0
	v_add_f32_e32 v180, v180, v181
	v_mov_b32_e32 v181, v180
	s_nop 1
	v_permlane16_swap_b32 v181, v180
	s_waitcnt lgkmcnt(0)
	v_add_f32_e32 v180, v180, v181
	v_mov_b32_e32 v181, v180
	s_nop 1
	v_permlane32_swap_b32 v181, v180
	s_waitcnt lgkmcnt(0)
	v_add_f32_e32 v180, v180, v181
	v_fmamk_f32 v182, v180, 0xbc800000, v115
	v_fmamk_f32 v184, v180, 0xbc800000, v113
	v_fmamk_f32 v181, v180, 0xbc800000, v114
	v_fmamk_f32 v183, v180, 0xbc800000, v112
	v_mul_f32_e32 v184, v184, v184
	v_mul_f32_e32 v182, v182, v182
	v_fmac_f32_e32 v184, v183, v183
	v_fmac_f32_e32 v182, v181, v181
	v_fmamk_f32 v183, v180, 0xbc800000, v111
	v_fmamk_f32 v185, v180, 0xbc800000, v109
	v_add_f32_e32 v181, v184, v182
	v_fmamk_f32 v182, v180, 0xbc800000, v110
	v_fmamk_f32 v184, v180, 0xbc800000, v108
	v_mul_f32_e32 v185, v185, v185
	v_mul_f32_e32 v183, v183, v183
	v_fmac_f32_e32 v185, v184, v184
	v_fmac_f32_e32 v183, v182, v182
	v_add_f32_e32 v182, v185, v183
	v_fmamk_f32 v183, v180, 0xbc800000, v107
	v_fmamk_f32 v185, v180, 0xbc800000, v105
	v_add_f32_e32 v181, v181, v182
	v_fmamk_f32 v182, v180, 0xbc800000, v106
	v_fmamk_f32 v184, v180, 0xbc800000, v104
	v_mul_f32_e32 v185, v185, v185
	v_mul_f32_e32 v183, v183, v183
	v_fmac_f32_e32 v185, v184, v184
	v_fmac_f32_e32 v183, v182, v182
	v_add_f32_e32 v182, v185, v183
	v_fmamk_f32 v183, v180, 0xbc800000, v103
	v_fmamk_f32 v185, v180, 0xbc800000, v101
	v_add_f32_e32 v181, v182, v181
	v_fmamk_f32 v182, v180, 0xbc800000, v102
	v_fmamk_f32 v184, v180, 0xbc800000, v100
	v_mul_f32_e32 v185, v185, v185
	v_mul_f32_e32 v183, v183, v183
	v_fmac_f32_e32 v185, v184, v184
	v_fmac_f32_e32 v183, v182, v182
	v_add_f32_e32 v182, v185, v183
	v_add_f32_e32 v181, v182, v181
	v_mov_b32_e32 v182, v181
	s_nop 1
	v_permlane16_swap_b32 v182, v181
	s_waitcnt lgkmcnt(0)
	v_add_f32_e32 v181, v181, v182
	v_mov_b32_e32 v182, v181
	s_nop 1
	v_permlane32_swap_b32 v182, v181
	s_and_saveexec_b64 s[46:47], s[44:45]
	s_cbranch_execz .LBB0_1093
	s_lshl_b32 s8, s83, 11
	s_add_i32 s8, s36, s8
	v_mul_f32_e32 v180, 0x3c800000, v180
	v_lshl_add_u32 v183, v228, 5, s8
	s_waitcnt lgkmcnt(0)
	v_add_f32_e32 v181, v181, v182
	ds_write_b64 v183, v[180:181] offset:512
.LBB0_1093:
	s_or_b64 exec, exec, s[46:47]
	v_lshlrev_b32_e32 v180, 16, v176
	v_and_b32_e32 v181, 0xffff0000, v176
	v_lshlrev_b32_e32 v176, 16, v177
	v_and_b32_e32 v177, 0xffff0000, v177
	s_waitcnt lgkmcnt(0)
	v_lshlrev_b32_e32 v182, 16, v178
	v_and_b32_e32 v183, 0xffff0000, v178
	v_lshlrev_b32_e32 v178, 16, v179
	v_and_b32_e32 v179, 0xffff0000, v179
	v_pk_fma_f32 v[96:97], v[180:181], s[24:25], v[96:97] op_sel_hi:[1,0,1]
	v_pk_fma_f32 v[98:99], v[176:177], s[24:25], v[98:99] op_sel_hi:[1,0,1]
	v_pk_fma_f32 v[94:95], v[178:179], s[24:25], v[94:95] op_sel_hi:[1,0,1]
	v_lshlrev_b32_e32 v176, 16, v172
	v_and_b32_e32 v177, 0xffff0000, v172
	v_lshlrev_b32_e32 v172, 16, v173
	v_and_b32_e32 v173, 0xffff0000, v173
	v_lshlrev_b32_e32 v178, 16, v174
	v_and_b32_e32 v179, 0xffff0000, v174
	v_lshlrev_b32_e32 v174, 16, v175
	v_and_b32_e32 v175, 0xffff0000, v175
	v_pk_fma_f32 v[92:93], v[182:183], s[24:25], v[92:93] op_sel_hi:[1,0,1]
	v_pk_fma_f32 v[90:91], v[172:173], s[24:25], v[90:91] op_sel_hi:[1,0,1]
	v_pk_fma_f32 v[86:87], v[174:175], s[24:25], v[86:87] op_sel_hi:[1,0,1]
	v_pk_mov_b32 v[172:173], v[96:97], v[98:99] op_sel:[1,0]
	v_mov_b32_e32 v174, v96
	v_mov_b32_e32 v175, v99
	v_pk_fma_f32 v[88:89], v[176:177], s[24:25], v[88:89] op_sel_hi:[1,0,1]
	v_pk_add_f32 v[172:173], v[172:173], v[174:175]
	v_pk_mov_b32 v[174:175], v[92:93], v[94:95] op_sel:[1,0]
	v_mov_b32_e32 v176, v92
	v_mov_b32_e32 v177, v95
	v_pk_add_f32 v[174:175], v[174:175], v[176:177]
	v_pk_fma_f32 v[84:85], v[178:179], s[24:25], v[84:85] op_sel_hi:[1,0,1]
	v_add_f32_e32 v172, v172, v173
	v_pk_add_f32 v[174:175], v[174:175], v[174:175] op_sel_hi:[0,1]
	v_add_f32_e32 v173, 0, v172
	v_add_f32_e32 v177, v88, v89
	v_add_f32_e32 v179, v90, v91
	v_mov_b32_e32 v176, v84
	v_mov_b32_e32 v178, v85
	v_mov_b32_e32 v174, v86
	v_mov_b32_e32 v172, v87
	v_pk_add_f32 v[176:177], v[176:177], v[178:179]
	v_pk_add_f32 v[172:173], v[174:175], v[172:173]
	s_nop 0
	v_pk_add_f32 v[172:173], v[176:177], v[172:173]
	s_nop 0
	v_add_f32_e32 v172, v172, v173
	v_mov_b32_e32 v173, v172
	s_nop 1
	v_permlane16_swap_b32 v173, v172
	s_waitcnt lgkmcnt(0)
;     __device__ __forceinline__ void run(const f32x4 (&v)[2][2][4][2], const Unit& u, int wr, int wc, int fr, int fq, LAS unsigned char* lds, int wid, int lane) const {
;     ...
;                 float s = 0.f;
; #pragma unroll
;                 for (int bj = 0; bj < 2; ++bj)
; #pragma unroll
;                     for (int n = 0; n < 2; ++n) { const f32x4 x = v[ai][bj][m][n]; s += (x[0] + x[1]) + (x[2] + x[3]); }
;                 s += __shfl_xor(s, 16); s += __shfl_xor(s, 32);
;                 const float mw = s * (1.0f / 64.0f); float q = 0.f;
; #pragma unroll
;                 for (int bj = 0; bj < 2; ++bj)
; #pragma unroll
;                     for (int n = 0; n < 2; ++n) { const f32x4 d = v[ai][bj][m][n] - mw; q += (d[0] * d[0] + d[1] * d[1]) + (d[2] * d[2] + d[3] * d[3]); }
;                 q += __shfl_xor(q, 16); q += __shfl_xor(q, 32);
;                 if (fq == 0) Pt[(ai * HALF + wr * 64 + m * 16 + fr) * 4 + wc] = (f32x2v){mw, q};
;             }
;     __device__ __forceinline__ void fused(f32x4 (&acc)[2][2][4][2], const Unit& u, int wr, int wc, int fr, int fq, LAS unsigned char* lds, int wid, int lane) const {
;     ...
;                     const u32x4 hb = *(const u32x4*)(H + ro + bj * HALF);
;                     const f32x4 h0 = {bflo(hb.x), bfhi(hb.x), bflo(hb.y), bfhi(hb.y)}, h1 = {bflo(hb.z), bfhi(hb.z), bflo(hb.w), bfhi(hb.w)};
;                     acc[ai][bj][m][0] = h0 * ALPHA + acc[ai][bj][m][0]; acc[ai][bj][m][1] = h1 * ALPHA + acc[ai][bj][m][1];
	v_add_f32_e32 v172, v172, v173
	v_mov_b32_e32 v173, v172
	s_nop 1
	v_permlane32_swap_b32 v173, v172
	s_waitcnt lgkmcnt(0)
	v_add_f32_e32 v172, v172, v173
	v_fmamk_f32 v174, v172, 0xbc800000, v99
	v_fmamk_f32 v176, v172, 0xbc800000, v97
	v_fmamk_f32 v173, v172, 0xbc800000, v98
	v_fmamk_f32 v175, v172, 0xbc800000, v96
	v_mul_f32_e32 v176, v176, v176
	v_mul_f32_e32 v174, v174, v174
	v_fmac_f32_e32 v176, v175, v175
	v_fmac_f32_e32 v174, v173, v173
	v_fmamk_f32 v175, v172, 0xbc800000, v95
	v_fmamk_f32 v177, v172, 0xbc800000, v93
	v_add_f32_e32 v173, v176, v174
	v_fmamk_f32 v174, v172, 0xbc800000, v94
	v_fmamk_f32 v176, v172, 0xbc800000, v92
	v_mul_f32_e32 v177, v177, v177
	v_mul_f32_e32 v175, v175, v175
	v_fmac_f32_e32 v177, v176, v176
	v_fmac_f32_e32 v175, v174, v174
	v_add_f32_e32 v174, v177, v175
	v_fmamk_f32 v175, v172, 0xbc800000, v91
	v_fmamk_f32 v177, v172, 0xbc800000, v89
	v_add_f32_e32 v173, v173, v174
	v_fmamk_f32 v174, v172, 0xbc800000, v90
	v_fmamk_f32 v176, v172, 0xbc800000, v88
	v_mul_f32_e32 v177, v177, v177
	v_mul_f32_e32 v175, v175, v175
	v_fmac_f32_e32 v177, v176, v176
	v_fmac_f32_e32 v175, v174, v174
	v_add_f32_e32 v174, v177, v175
	v_fmamk_f32 v175, v172, 0xbc800000, v87
	v_fmamk_f32 v177, v172, 0xbc800000, v85
	v_add_f32_e32 v173, v174, v173
	v_fmamk_f32 v174, v172, 0xbc800000, v86
	v_fmamk_f32 v176, v172, 0xbc800000, v84
	v_mul_f32_e32 v177, v177, v177
	v_mul_f32_e32 v175, v175, v175
	v_fmac_f32_e32 v177, v176, v176
	v_fmac_f32_e32 v175, v174, v174
	v_add_f32_e32 v174, v177, v175
	v_add_f32_e32 v173, v174, v173
	v_mov_b32_e32 v174, v173
	s_nop 1
	v_permlane16_swap_b32 v174, v173
	s_waitcnt lgkmcnt(0)
	v_add_f32_e32 v173, v173, v174
	v_mov_b32_e32 v174, v173
	s_nop 1
	v_permlane32_swap_b32 v174, v173
	s_and_saveexec_b64 s[46:47], s[44:45]
	s_cbranch_execz .LBB0_1095
	s_lshl_b32 s8, s83, 11
	s_add_i32 s8, s36, s8
	v_mul_f32_e32 v172, 0x3c800000, v172
	v_lshl_add_u32 v175, v228, 5, s8
	s_waitcnt lgkmcnt(0)
	v_add_f32_e32 v173, v173, v174
	ds_write_b64 v175, v[172:173] offset:1024
.LBB0_1095:
	s_or_b64 exec, exec, s[46:47]
	v_lshlrev_b32_e32 v172, 16, v168
	v_and_b32_e32 v173, 0xffff0000, v168
	v_lshlrev_b32_e32 v168, 16, v169
	v_and_b32_e32 v169, 0xffff0000, v169
	s_waitcnt lgkmcnt(0)
	v_lshlrev_b32_e32 v174, 16, v170
	v_and_b32_e32 v175, 0xffff0000, v170
	v_lshlrev_b32_e32 v170, 16, v171
	v_and_b32_e32 v171, 0xffff0000, v171
	v_pk_fma_f32 v[80:81], v[172:173], s[24:25], v[80:81] op_sel_hi:[1,0,1]
	v_pk_fma_f32 v[82:83], v[168:169], s[24:25], v[82:83] op_sel_hi:[1,0,1]
	v_pk_fma_f32 v[78:79], v[170:171], s[24:25], v[78:79] op_sel_hi:[1,0,1]
	v_lshlrev_b32_e32 v168, 16, v164
	v_and_b32_e32 v169, 0xffff0000, v164
	v_lshlrev_b32_e32 v164, 16, v165
	v_and_b32_e32 v165, 0xffff0000, v165
	v_lshlrev_b32_e32 v170, 16, v166
	v_and_b32_e32 v171, 0xffff0000, v166
	v_lshlrev_b32_e32 v166, 16, v167
	v_and_b32_e32 v167, 0xffff0000, v167
	v_pk_fma_f32 v[76:77], v[174:175], s[24:25], v[76:77] op_sel_hi:[1,0,1]
	v_pk_fma_f32 v[74:75], v[164:165], s[24:25], v[74:75] op_sel_hi:[1,0,1]
	v_pk_fma_f32 v[70:71], v[166:167], s[24:25], v[70:71] op_sel_hi:[1,0,1]
	v_pk_mov_b32 v[164:165], v[80:81], v[82:83] op_sel:[1,0]
	v_mov_b32_e32 v166, v80
	v_mov_b32_e32 v167, v83
	v_pk_fma_f32 v[72:73], v[168:169], s[24:25], v[72:73] op_sel_hi:[1,0,1]
	v_pk_add_f32 v[164:165], v[164:165], v[166:167]
	v_pk_mov_b32 v[166:167], v[76:77], v[78:79] op_sel:[1,0]
	v_mov_b32_e32 v168, v76
	v_mov_b32_e32 v169, v79
	v_pk_add_f32 v[166:167], v[166:167], v[168:169]
	v_pk_fma_f32 v[68:69], v[170:171], s[24:25], v[68:69] op_sel_hi:[1,0,1]
	v_add_f32_e32 v164, v164, v165
	v_pk_add_f32 v[166:167], v[166:167], v[166:167] op_sel_hi:[0,1]
	v_add_f32_e32 v165, 0, v164
	v_add_f32_e32 v169, v72, v73
	v_add_f32_e32 v171, v74, v75
	v_mov_b32_e32 v168, v68
	v_mov_b32_e32 v170, v69
	v_mov_b32_e32 v166, v70
	v_mov_b32_e32 v164, v71
	v_pk_add_f32 v[168:169], v[168:169], v[170:171]
	v_pk_add_f32 v[164:165], v[166:167], v[164:165]
	s_nop 0
	v_pk_add_f32 v[164:165], v[168:169], v[164:165]
	s_nop 0
	v_add_f32_e32 v164, v164, v165
	v_mov_b32_e32 v165, v164
	s_nop 1
	v_permlane16_swap_b32 v165, v164
	s_waitcnt lgkmcnt(0)
	v_add_f32_e32 v164, v164, v165
	v_mov_b32_e32 v165, v164
	s_nop 1
	v_permlane32_swap_b32 v165, v164
	s_waitcnt lgkmcnt(0)
	v_add_f32_e32 v164, v164, v165
	v_fmamk_f32 v166, v164, 0xbc800000, v83
	v_fmamk_f32 v168, v164, 0xbc800000, v81
	v_fmamk_f32 v165, v164, 0xbc800000, v82
	v_fmamk_f32 v167, v164, 0xbc800000, v80
	v_mul_f32_e32 v168, v168, v168
	v_mul_f32_e32 v166, v166, v166
	v_fmac_f32_e32 v168, v167, v167
	v_fmac_f32_e32 v166, v165, v165
	v_fmamk_f32 v167, v164, 0xbc800000, v79
	v_fmamk_f32 v169, v164, 0xbc800000, v77
	v_add_f32_e32 v165, v168, v166
	v_fmamk_f32 v166, v164, 0xbc800000, v78
	v_fmamk_f32 v168, v164, 0xbc800000, v76
	v_mul_f32_e32 v169, v169, v169
	v_mul_f32_e32 v167, v167, v167
	v_fmac_f32_e32 v169, v168, v168
	v_fmac_f32_e32 v167, v166, v166
	v_add_f32_e32 v166, v169, v167
	v_fmamk_f32 v167, v164, 0xbc800000, v75
	v_fmamk_f32 v169, v164, 0xbc800000, v73
	v_add_f32_e32 v165, v165, v166
	v_fmamk_f32 v166, v164, 0xbc800000, v74
	v_fmamk_f32 v168, v164, 0xbc800000, v72
	v_mul_f32_e32 v169, v169, v169
	v_mul_f32_e32 v167, v167, v167
	v_fmac_f32_e32 v169, v168, v168
	v_fmac_f32_e32 v167, v166, v166
	v_add_f32_e32 v166, v169, v167
	v_fmamk_f32 v167, v164, 0xbc800000, v71
	v_fmamk_f32 v169, v164, 0xbc800000, v69
	v_add_f32_e32 v165, v166, v165
	v_fmamk_f32 v166, v164, 0xbc800000, v70
	v_fmamk_f32 v168, v164, 0xbc800000, v68
	v_mul_f32_e32 v169, v169, v169
	v_mul_f32_e32 v167, v167, v167
	v_fmac_f32_e32 v169, v168, v168
	v_fmac_f32_e32 v167, v166, v166
	v_add_f32_e32 v166, v169, v167
	v_add_f32_e32 v165, v166, v165
	v_mov_b32_e32 v166, v165
	s_nop 1
	v_permlane16_swap_b32 v166, v165
	s_waitcnt lgkmcnt(0)
	v_add_f32_e32 v165, v165, v166
	v_mov_b32_e32 v166, v165
	s_nop 1
	v_permlane32_swap_b32 v166, v165
	s_and_saveexec_b64 s[46:47], s[44:45]
	s_cbranch_execz .LBB0_1097
	s_lshl_b32 s8, s83, 11
	s_add_i32 s8, s36, s8
	v_mul_f32_e32 v164, 0x3c800000, v164
	v_lshl_add_u32 v167, v228, 5, s8
	s_waitcnt lgkmcnt(0)
	v_add_f32_e32 v165, v165, v166
	ds_write_b64 v167, v[164:165] offset:1536
;     __device__ __forceinline__ void run(const f32x4 (&v)[2][2][4][2], const Unit& u, int wr, int wc, int fr, int fq, LAS unsigned char* lds, int wid, int lane) const {
;     ...
;                 float s = 0.f;
; #pragma unroll
;                 for (int bj = 0; bj < 2; ++bj)
; #pragma unroll
;                     for (int n = 0; n < 2; ++n) { const f32x4 x = v[ai][bj][m][n]; s += (x[0] + x[1]) + (x[2] + x[3]); }
;                 s += __shfl_xor(s, 16); s += __shfl_xor(s, 32);
;                 const float mw = s * (1.0f / 64.0f); float q = 0.f;
; #pragma unroll
;                 for (int bj = 0; bj < 2; ++bj)
; #pragma unroll
;                     for (int n = 0; n < 2; ++n) { const f32x4 d = v[ai][bj][m][n] - mw; q += (d[0] * d[0] + d[1] * d[1]) + (d[2] * d[2] + d[3] * d[3]); }
;                 q += __shfl_xor(q, 16); q += __shfl_xor(q, 32);
;                 if (fq == 0) Pt[(ai * HALF + wr * 64 + m * 16 + fr) * 4 + wc] = (f32x2v){mw, q};
;             }
;     __device__ __forceinline__ void fused(f32x4 (&acc)[2][2][4][2], const Unit& u, int wr, int wc, int fr, int fq, LAS unsigned char* lds, int wid, int lane) const {
;     ...
;                     const u32x4 hb = *(const u32x4*)(H + ro + bj * HALF);
;                     const f32x4 h0 = {bflo(hb.x), bfhi(hb.x), bflo(hb.y), bfhi(hb.y)}, h1 = {bflo(hb.z), bfhi(hb.z), bflo(hb.w), bfhi(hb.w)};
;                     acc[ai][bj][m][0] = h0 * ALPHA + acc[ai][bj][m][0]; acc[ai][bj][m][1] = h1 * ALPHA + acc[ai][bj][m][1];
.LBB0_1097:
	s_or_b64 exec, exec, s[46:47]
	v_lshlrev_b32_e32 v164, 16, v160
	v_and_b32_e32 v165, 0xffff0000, v160
	v_lshlrev_b32_e32 v160, 16, v161
	v_and_b32_e32 v161, 0xffff0000, v161
	s_waitcnt lgkmcnt(0)
	v_lshlrev_b32_e32 v166, 16, v162
	v_and_b32_e32 v167, 0xffff0000, v162
	v_lshlrev_b32_e32 v168, 16, v163
	v_and_b32_e32 v169, 0xffff0000, v163
	v_pk_fma_f32 v[162:163], v[164:165], s[24:25], v[64:65] op_sel_hi:[1,0,1]
	v_pk_fma_f32 v[164:165], v[160:161], s[24:25], v[66:67] op_sel_hi:[1,0,1]
	v_pk_fma_f32 v[66:67], v[166:167], s[24:25], v[60:61] op_sel_hi:[1,0,1]
	v_pk_fma_f32 v[160:161], v[168:169], s[24:25], v[62:63] op_sel_hi:[1,0,1]
	v_lshlrev_b32_e32 v60, 16, v156
	v_and_b32_e32 v61, 0xffff0000, v156
	v_lshlrev_b32_e32 v62, 16, v157
	v_and_b32_e32 v63, 0xffff0000, v157
	v_lshlrev_b32_e32 v64, 16, v158
	v_and_b32_e32 v65, 0xffff0000, v158
	v_pk_fma_f32 v[56:57], v[60:61], s[24:25], v[56:57] op_sel_hi:[1,0,1]
	v_pk_fma_f32 v[58:59], v[62:63], s[24:25], v[58:59] op_sel_hi:[1,0,1]
	v_pk_mov_b32 v[60:61], v[162:163], v[164:165] op_sel:[1,0]
	v_mov_b32_e32 v62, v162
	v_mov_b32_e32 v63, v165
	v_pk_fma_f32 v[52:53], v[64:65], s[24:25], v[52:53] op_sel_hi:[1,0,1]
	v_pk_add_f32 v[60:61], v[60:61], v[62:63]
	v_pk_mov_b32 v[62:63], v[66:67], v[160:161] op_sel:[1,0]
	v_mov_b32_e32 v64, v66
	v_mov_b32_e32 v65, v161
	v_lshlrev_b32_e32 v156, 16, v159
	v_and_b32_e32 v157, 0xffff0000, v159
	v_pk_add_f32 v[62:63], v[62:63], v[64:65]
	v_pk_fma_f32 v[54:55], v[156:157], s[24:25], v[54:55] op_sel_hi:[1,0,1]
	v_add_f32_e32 v60, v60, v61
	v_pk_add_f32 v[62:63], v[62:63], v[62:63] op_sel_hi:[0,1]
	v_add_f32_e32 v61, 0, v60
	v_add_f32_e32 v65, v56, v57
	v_add_f32_e32 v157, v58, v59
	v_mov_b32_e32 v64, v52
	v_mov_b32_e32 v156, v53
	v_mov_b32_e32 v62, v54
	v_mov_b32_e32 v60, v55
	v_pk_add_f32 v[64:65], v[64:65], v[156:157]
	v_pk_add_f32 v[60:61], v[62:63], v[60:61]
	s_nop 0
	v_pk_add_f32 v[60:61], v[64:65], v[60:61]
	s_nop 0
	v_add_f32_e32 v60, v60, v61
	v_mov_b32_e32 v61, v60
	s_nop 1
	v_permlane16_swap_b32 v61, v60
	s_waitcnt lgkmcnt(0)
	v_add_f32_e32 v60, v60, v61
	v_mov_b32_e32 v61, v60
	s_nop 1
	v_permlane32_swap_b32 v61, v60
	s_waitcnt lgkmcnt(0)
	v_add_f32_e32 v60, v60, v61
	v_fmamk_f32 v62, v60, 0xbc800000, v165
	v_fmamk_f32 v64, v60, 0xbc800000, v163
	v_fmamk_f32 v61, v60, 0xbc800000, v164
	v_fmamk_f32 v63, v60, 0xbc800000, v162
	v_mul_f32_e32 v64, v64, v64
	v_mul_f32_e32 v62, v62, v62
	v_fmac_f32_e32 v64, v63, v63
	v_fmac_f32_e32 v62, v61, v61
	v_fmamk_f32 v63, v60, 0xbc800000, v161
	v_fmamk_f32 v65, v60, 0xbc800000, v67
	v_add_f32_e32 v61, v64, v62
	v_fmamk_f32 v62, v60, 0xbc800000, v160
	v_fmamk_f32 v64, v60, 0xbc800000, v66
	v_mul_f32_e32 v65, v65, v65
	v_mul_f32_e32 v63, v63, v63
	v_fmac_f32_e32 v65, v64, v64
	v_fmac_f32_e32 v63, v62, v62
	v_add_f32_e32 v62, v65, v63
	v_fmamk_f32 v63, v60, 0xbc800000, v59
	v_fmamk_f32 v65, v60, 0xbc800000, v57
	v_add_f32_e32 v61, v61, v62
	v_fmamk_f32 v62, v60, 0xbc800000, v58
	v_fmamk_f32 v64, v60, 0xbc800000, v56
	v_mul_f32_e32 v65, v65, v65
	v_mul_f32_e32 v63, v63, v63
	v_fmac_f32_e32 v65, v64, v64
	v_fmac_f32_e32 v63, v62, v62
	v_add_f32_e32 v62, v65, v63
	v_fmamk_f32 v63, v60, 0xbc800000, v55
	v_fmamk_f32 v65, v60, 0xbc800000, v53
	v_add_f32_e32 v61, v62, v61
	v_fmamk_f32 v62, v60, 0xbc800000, v54
	v_fmamk_f32 v64, v60, 0xbc800000, v52
	v_mul_f32_e32 v65, v65, v65
	v_mul_f32_e32 v63, v63, v63
	v_fmac_f32_e32 v65, v64, v64
	v_fmac_f32_e32 v63, v62, v62
	v_add_f32_e32 v62, v65, v63
	v_add_f32_e32 v61, v62, v61
	v_mov_b32_e32 v62, v61
	s_nop 1
	v_permlane16_swap_b32 v62, v61
	s_waitcnt lgkmcnt(0)
	v_add_f32_e32 v61, v61, v62
	v_mov_b32_e32 v62, v61
	s_nop 1
	v_permlane32_swap_b32 v62, v61
	s_and_saveexec_b64 s[46:47], s[44:45]
	s_cbranch_execz .LBB0_1099
	s_lshl_b32 s8, s83, 11
	s_add_i32 s8, s36, s8
	v_mul_f32_e32 v60, 0x3c800000, v60
	v_lshl_add_u32 v63, v228, 5, s8
	s_waitcnt lgkmcnt(0)
	v_add_f32_e32 v61, v61, v62
	ds_write_b64 v63, v[60:61] offset:4096
.LBB0_1099:
	s_or_b64 exec, exec, s[46:47]
	v_lshlrev_b32_e32 v60, 16, v152
	v_and_b32_e32 v61, 0xffff0000, v152
	s_waitcnt lgkmcnt(0)
	v_lshlrev_b32_e32 v62, 16, v153
	v_and_b32_e32 v63, 0xffff0000, v153
	v_lshlrev_b32_e32 v64, 16, v154
	v_and_b32_e32 v65, 0xffff0000, v154
	v_lshlrev_b32_e32 v154, 16, v155
	v_and_b32_e32 v155, 0xffff0000, v155
	v_pk_fma_f32 v[156:157], v[60:61], s[24:25], v[48:49] op_sel_hi:[1,0,1]
	v_pk_fma_f32 v[158:159], v[62:63], s[24:25], v[50:51] op_sel_hi:[1,0,1]
	v_pk_fma_f32 v[152:153], v[64:65], s[24:25], v[44:45] op_sel_hi:[1,0,1]
	v_pk_fma_f32 v[154:155], v[154:155], s[24:25], v[46:47] op_sel_hi:[1,0,1]
	v_lshlrev_b32_e32 v44, 16, v148
	v_and_b32_e32 v45, 0xffff0000, v148
	v_lshlrev_b32_e32 v46, 16, v149
	v_and_b32_e32 v47, 0xffff0000, v149
	v_lshlrev_b32_e32 v48, 16, v150
	v_and_b32_e32 v49, 0xffff0000, v150
	v_pk_fma_f32 v[40:41], v[44:45], s[24:25], v[40:41] op_sel_hi:[1,0,1]
	v_pk_fma_f32 v[42:43], v[46:47], s[24:25], v[42:43] op_sel_hi:[1,0,1]
	v_pk_mov_b32 v[44:45], v[156:157], v[158:159] op_sel:[1,0]
	v_mov_b32_e32 v46, v156
	v_mov_b32_e32 v47, v159
	v_pk_fma_f32 v[36:37], v[48:49], s[24:25], v[36:37] op_sel_hi:[1,0,1]
	v_pk_add_f32 v[44:45], v[44:45], v[46:47]
	v_pk_mov_b32 v[46:47], v[152:153], v[154:155] op_sel:[1,0]
	v_mov_b32_e32 v48, v152
	v_mov_b32_e32 v49, v155
	v_lshlrev_b32_e32 v50, 16, v151
	v_and_b32_e32 v51, 0xffff0000, v151
	v_pk_add_f32 v[46:47], v[46:47], v[48:49]
	v_pk_fma_f32 v[38:39], v[50:51], s[24:25], v[38:39] op_sel_hi:[1,0,1]
	v_add_f32_e32 v44, v44, v45
	v_pk_add_f32 v[46:47], v[46:47], v[46:47] op_sel_hi:[0,1]
	v_add_f32_e32 v45, 0, v44
	v_add_f32_e32 v49, v40, v41
	v_add_f32_e32 v51, v42, v43
	v_mov_b32_e32 v48, v36
	v_mov_b32_e32 v50, v37
	v_mov_b32_e32 v46, v38
	v_mov_b32_e32 v44, v39
	v_pk_add_f32 v[48:49], v[48:49], v[50:51]
	v_pk_add_f32 v[44:45], v[46:47], v[44:45]
	s_nop 0
	v_pk_add_f32 v[44:45], v[48:49], v[44:45]
	s_nop 0
	v_add_f32_e32 v44, v44, v45
	v_mov_b32_e32 v45, v44
	s_nop 1
	v_permlane16_swap_b32 v45, v44
	s_waitcnt lgkmcnt(0)
;     __device__ __forceinline__ void run(const f32x4 (&v)[2][2][4][2], const Unit& u, int wr, int wc, int fr, int fq, LAS unsigned char* lds, int wid, int lane) const {
;     ...
;                 float s = 0.f;
; #pragma unroll
;                 for (int bj = 0; bj < 2; ++bj)
; #pragma unroll
;                     for (int n = 0; n < 2; ++n) { const f32x4 x = v[ai][bj][m][n]; s += (x[0] + x[1]) + (x[2] + x[3]); }
;                 s += __shfl_xor(s, 16); s += __shfl_xor(s, 32);
;                 const float mw = s * (1.0f / 64.0f); float q = 0.f;
; #pragma unroll
;                 for (int bj = 0; bj < 2; ++bj)
; #pragma unroll
;                     for (int n = 0; n < 2; ++n) { const f32x4 d = v[ai][bj][m][n] - mw; q += (d[0] * d[0] + d[1] * d[1]) + (d[2] * d[2] + d[3] * d[3]); }
;                 q += __shfl_xor(q, 16); q += __shfl_xor(q, 32);
;                 if (fq == 0) Pt[(ai * HALF + wr * 64 + m * 16 + fr) * 4 + wc] = (f32x2v){mw, q};
;             }
;     __device__ __forceinline__ void fused(f32x4 (&acc)[2][2][4][2], const Unit& u, int wr, int wc, int fr, int fq, LAS unsigned char* lds, int wid, int lane) const {
;     ...
;                     const u32x4 hb = *(const u32x4*)(H + ro + bj * HALF);
;                     const f32x4 h0 = {bflo(hb.x), bfhi(hb.x), bflo(hb.y), bfhi(hb.y)}, h1 = {bflo(hb.z), bfhi(hb.z), bflo(hb.w), bfhi(hb.w)};
;                     acc[ai][bj][m][0] = h0 * ALPHA + acc[ai][bj][m][0]; acc[ai][bj][m][1] = h1 * ALPHA + acc[ai][bj][m][1];
	v_add_f32_e32 v44, v44, v45
	v_mov_b32_e32 v45, v44
	s_nop 1
	v_permlane32_swap_b32 v45, v44
	s_waitcnt lgkmcnt(0)
	v_add_f32_e32 v44, v44, v45
	v_fmamk_f32 v46, v44, 0xbc800000, v159
	v_fmamk_f32 v48, v44, 0xbc800000, v157
	v_fmamk_f32 v45, v44, 0xbc800000, v158
	v_fmamk_f32 v47, v44, 0xbc800000, v156
	v_mul_f32_e32 v48, v48, v48
	v_mul_f32_e32 v46, v46, v46
	v_fmac_f32_e32 v48, v47, v47
	v_fmac_f32_e32 v46, v45, v45
	v_fmamk_f32 v47, v44, 0xbc800000, v155
	v_fmamk_f32 v49, v44, 0xbc800000, v153
	v_add_f32_e32 v45, v48, v46
	v_fmamk_f32 v46, v44, 0xbc800000, v154
	v_fmamk_f32 v48, v44, 0xbc800000, v152
	v_mul_f32_e32 v49, v49, v49
	v_mul_f32_e32 v47, v47, v47
	v_fmac_f32_e32 v49, v48, v48
	v_fmac_f32_e32 v47, v46, v46
	v_add_f32_e32 v46, v49, v47
	v_fmamk_f32 v47, v44, 0xbc800000, v43
	v_fmamk_f32 v49, v44, 0xbc800000, v41
	v_add_f32_e32 v45, v45, v46
	v_fmamk_f32 v46, v44, 0xbc800000, v42
	v_fmamk_f32 v48, v44, 0xbc800000, v40
	v_mul_f32_e32 v49, v49, v49
	v_mul_f32_e32 v47, v47, v47
	v_fmac_f32_e32 v49, v48, v48
	v_fmac_f32_e32 v47, v46, v46
	v_add_f32_e32 v46, v49, v47
	v_fmamk_f32 v47, v44, 0xbc800000, v39
	v_fmamk_f32 v49, v44, 0xbc800000, v37
	v_add_f32_e32 v45, v46, v45
	v_fmamk_f32 v46, v44, 0xbc800000, v38
	v_fmamk_f32 v48, v44, 0xbc800000, v36
	v_mul_f32_e32 v49, v49, v49
	v_mul_f32_e32 v47, v47, v47
	v_fmac_f32_e32 v49, v48, v48
	v_fmac_f32_e32 v47, v46, v46
	v_add_f32_e32 v46, v49, v47
	v_add_f32_e32 v45, v46, v45
	v_mov_b32_e32 v46, v45
	s_nop 1
	v_permlane16_swap_b32 v46, v45
	s_waitcnt lgkmcnt(0)
	v_add_f32_e32 v45, v45, v46
	v_mov_b32_e32 v46, v45
	s_nop 1
	v_permlane32_swap_b32 v46, v45
	s_and_saveexec_b64 s[46:47], s[44:45]
	s_cbranch_execz .LBB0_1101
	s_lshl_b32 s8, s83, 11
	s_add_i32 s8, s36, s8
	v_mul_f32_e32 v44, 0x3c800000, v44
	v_lshl_add_u32 v47, v228, 5, s8
	s_waitcnt lgkmcnt(0)
	v_add_f32_e32 v45, v45, v46
	ds_write_b64 v47, v[44:45] offset:4608
.LBB0_1101:
	s_or_b64 exec, exec, s[46:47]
	v_lshlrev_b32_e32 v44, 16, v144
	v_and_b32_e32 v45, 0xffff0000, v144
	s_waitcnt lgkmcnt(0)
	v_lshlrev_b32_e32 v46, 16, v145
	v_and_b32_e32 v47, 0xffff0000, v145
	v_lshlrev_b32_e32 v48, 16, v146
	v_and_b32_e32 v49, 0xffff0000, v146
	v_lshlrev_b32_e32 v50, 16, v147
	v_and_b32_e32 v51, 0xffff0000, v147
	v_pk_fma_f32 v[148:149], v[44:45], s[24:25], v[32:33] op_sel_hi:[1,0,1]
	v_pk_fma_f32 v[150:151], v[46:47], s[24:25], v[34:35] op_sel_hi:[1,0,1]
	v_lshlrev_b32_e32 v32, 16, v142
	v_and_b32_e32 v33, 0xffff0000, v142
	v_lshlrev_b32_e32 v34, 16, v143
	v_and_b32_e32 v35, 0xffff0000, v143
	v_pk_fma_f32 v[144:145], v[48:49], s[24:25], v[28:29] op_sel_hi:[1,0,1]
	v_pk_fma_f32 v[146:147], v[50:51], s[24:25], v[30:31] op_sel_hi:[1,0,1]
	v_lshlrev_b32_e32 v28, 16, v140
	v_and_b32_e32 v29, 0xffff0000, v140
	v_pk_fma_f32 v[34:35], v[34:35], s[24:25], v[22:23] op_sel_hi:[1,0,1]
	v_pk_fma_f32 v[44:45], v[32:33], s[24:25], v[20:21] op_sel_hi:[1,0,1]
	v_pk_mov_b32 v[20:21], v[148:149], v[150:151] op_sel:[1,0]
	v_mov_b32_e32 v22, v148
	v_mov_b32_e32 v23, v151
	v_pk_fma_f32 v[46:47], v[28:29], s[24:25], v[24:25] op_sel_hi:[1,0,1]
	v_pk_add_f32 v[20:21], v[20:21], v[22:23]
	v_pk_mov_b32 v[22:23], v[144:145], v[146:147] op_sel:[1,0]
	v_mov_b32_e32 v24, v144
	v_mov_b32_e32 v25, v147
	v_lshlrev_b32_e32 v30, 16, v141
	v_and_b32_e32 v31, 0xffff0000, v141
	v_pk_add_f32 v[22:23], v[22:23], v[24:25]
	v_pk_fma_f32 v[48:49], v[30:31], s[24:25], v[26:27] op_sel_hi:[1,0,1]
	v_add_f32_e32 v20, v20, v21
	v_pk_add_f32 v[22:23], v[22:23], v[22:23] op_sel_hi:[0,1]
	v_add_f32_e32 v21, 0, v20
	v_add_f32_e32 v25, v46, v47
	v_add_f32_e32 v27, v48, v49
	v_mov_b32_e32 v24, v44
	v_mov_b32_e32 v26, v45
	v_mov_b32_e32 v22, v34
	v_mov_b32_e32 v20, v35
	v_pk_add_f32 v[24:25], v[24:25], v[26:27]
	v_pk_add_f32 v[20:21], v[22:23], v[20:21]
	s_nop 0
	v_pk_add_f32 v[20:21], v[24:25], v[20:21]
	s_nop 0
	v_add_f32_e32 v20, v20, v21
	v_mov_b32_e32 v21, v20
	s_nop 1
	v_permlane16_swap_b32 v21, v20
	s_waitcnt lgkmcnt(0)
	v_add_f32_e32 v20, v20, v21
	v_mov_b32_e32 v21, v20
	s_nop 1
	v_permlane32_swap_b32 v21, v20
	s_waitcnt lgkmcnt(0)
	v_add_f32_e32 v20, v20, v21
	v_fmamk_f32 v22, v20, 0xbc800000, v151
	v_fmamk_f32 v24, v20, 0xbc800000, v149
	v_fmamk_f32 v21, v20, 0xbc800000, v150
	v_fmamk_f32 v23, v20, 0xbc800000, v148
	v_mul_f32_e32 v24, v24, v24
	v_mul_f32_e32 v22, v22, v22
	v_fmac_f32_e32 v24, v23, v23
	v_fmac_f32_e32 v22, v21, v21
	v_fmamk_f32 v23, v20, 0xbc800000, v147
	v_fmamk_f32 v25, v20, 0xbc800000, v145
	v_add_f32_e32 v21, v24, v22
	v_fmamk_f32 v22, v20, 0xbc800000, v146
	v_fmamk_f32 v24, v20, 0xbc800000, v144
	v_mul_f32_e32 v25, v25, v25
	v_mul_f32_e32 v23, v23, v23
	v_fmac_f32_e32 v25, v24, v24
	v_fmac_f32_e32 v23, v22, v22
	v_add_f32_e32 v22, v25, v23
	v_fmamk_f32 v23, v20, 0xbc800000, v49
	v_fmamk_f32 v25, v20, 0xbc800000, v47
	v_add_f32_e32 v21, v21, v22
	v_fmamk_f32 v22, v20, 0xbc800000, v48
	v_fmamk_f32 v24, v20, 0xbc800000, v46
	v_mul_f32_e32 v25, v25, v25
	v_mul_f32_e32 v23, v23, v23
	v_fmac_f32_e32 v25, v24, v24
	v_fmac_f32_e32 v23, v22, v22
	v_add_f32_e32 v22, v25, v23
	v_fmamk_f32 v23, v20, 0xbc800000, v35
	v_fmamk_f32 v25, v20, 0xbc800000, v45
	v_add_f32_e32 v21, v22, v21
	v_fmamk_f32 v22, v20, 0xbc800000, v34
	v_fmamk_f32 v24, v20, 0xbc800000, v44
	v_mul_f32_e32 v25, v25, v25
	v_mul_f32_e32 v23, v23, v23
	v_fmac_f32_e32 v25, v24, v24
	v_fmac_f32_e32 v23, v22, v22
	v_add_f32_e32 v22, v25, v23
	v_add_f32_e32 v21, v22, v21
	v_mov_b32_e32 v22, v21
	s_nop 1
	v_permlane16_swap_b32 v22, v21
	s_waitcnt lgkmcnt(0)
	v_add_f32_e32 v21, v21, v22
	v_mov_b32_e32 v22, v21
	s_nop 1
	v_permlane32_swap_b32 v22, v21
	s_and_saveexec_b64 s[46:47], s[44:45]
	s_cbranch_execz .LBB0_1103
	s_lshl_b32 s8, s83, 11
	s_add_i32 s8, s36, s8
	v_mul_f32_e32 v20, 0x3c800000, v20
	v_lshl_add_u32 v23, v228, 5, s8
	s_waitcnt lgkmcnt(0)
	v_add_f32_e32 v21, v21, v22
	ds_write_b64 v23, v[20:21] offset:5120
;     __device__ __forceinline__ void run(const f32x4 (&v)[2][2][4][2], const Unit& u, int wr, int wc, int fr, int fq, LAS unsigned char* lds, int wid, int lane) const {
;     ...
;                 float s = 0.f;
; #pragma unroll
;                 for (int bj = 0; bj < 2; ++bj)
; #pragma unroll
;                     for (int n = 0; n < 2; ++n) { const f32x4 x = v[ai][bj][m][n]; s += (x[0] + x[1]) + (x[2] + x[3]); }
;                 s += __shfl_xor(s, 16); s += __shfl_xor(s, 32);
;                 const float mw = s * (1.0f / 64.0f); float q = 0.f;
; #pragma unroll
;                 for (int bj = 0; bj < 2; ++bj)
; #pragma unroll
;                     for (int n = 0; n < 2; ++n) { const f32x4 d = v[ai][bj][m][n] - mw; q += (d[0] * d[0] + d[1] * d[1]) + (d[2] * d[2] + d[3] * d[3]); }
;                 q += __shfl_xor(q, 16); q += __shfl_xor(q, 32);
;                 if (fq == 0) Pt[(ai * HALF + wr * 64 + m * 16 + fr) * 4 + wc] = (f32x2v){mw, q};
;             }
;     __device__ __forceinline__ void fused(f32x4 (&acc)[2][2][4][2], const Unit& u, int wr, int wc, int fr, int fq, LAS unsigned char* lds, int wid, int lane) const {
;     ...
;                     const u32x4 hb = *(const u32x4*)(H + ro + bj * HALF);
;                     const f32x4 h0 = {bflo(hb.x), bfhi(hb.x), bflo(hb.y), bfhi(hb.y)}, h1 = {bflo(hb.z), bfhi(hb.z), bflo(hb.w), bfhi(hb.w)};
;                     acc[ai][bj][m][0] = h0 * ALPHA + acc[ai][bj][m][0]; acc[ai][bj][m][1] = h1 * ALPHA + acc[ai][bj][m][1];
.LBB0_1103:
	s_or_b64 exec, exec, s[46:47]
	v_lshlrev_b32_e32 v20, 16, v136
	v_and_b32_e32 v21, 0xffff0000, v136
	s_waitcnt lgkmcnt(0)
	v_lshlrev_b32_e32 v22, 16, v137
	v_and_b32_e32 v23, 0xffff0000, v137
	v_lshlrev_b32_e32 v24, 16, v138
	v_and_b32_e32 v25, 0xffff0000, v138
	v_lshlrev_b32_e32 v26, 16, v139
	v_and_b32_e32 v27, 0xffff0000, v139
	v_pk_fma_f32 v[140:141], v[20:21], s[24:25], v[16:17] op_sel_hi:[1,0,1]
	v_pk_fma_f32 v[142:143], v[22:23], s[24:25], v[18:19] op_sel_hi:[1,0,1]
	v_lshlrev_b32_e32 v16, 16, v134
	v_and_b32_e32 v17, 0xffff0000, v134
	v_lshlrev_b32_e32 v18, 16, v135
	v_and_b32_e32 v19, 0xffff0000, v135
	v_pk_fma_f32 v[136:137], v[24:25], s[24:25], v[12:13] op_sel_hi:[1,0,1]
	v_pk_fma_f32 v[138:139], v[26:27], s[24:25], v[14:15] op_sel_hi:[1,0,1]
	v_lshlrev_b32_e32 v12, 16, v132
	v_and_b32_e32 v13, 0xffff0000, v132
	v_pk_fma_f32 v[50:51], v[18:19], s[24:25], v[6:7] op_sel_hi:[1,0,1]
	v_pk_fma_f32 v[60:61], v[16:17], s[24:25], v[4:5] op_sel_hi:[1,0,1]
	v_pk_mov_b32 v[4:5], v[140:141], v[142:143] op_sel:[1,0]
	v_mov_b32_e32 v6, v140
	v_mov_b32_e32 v7, v143
	v_pk_fma_f32 v[62:63], v[12:13], s[24:25], v[8:9] op_sel_hi:[1,0,1]
	v_pk_add_f32 v[4:5], v[4:5], v[6:7]
	v_pk_mov_b32 v[6:7], v[136:137], v[138:139] op_sel:[1,0]
	v_mov_b32_e32 v8, v136
	v_mov_b32_e32 v9, v139
	v_lshlrev_b32_e32 v14, 16, v133
	v_and_b32_e32 v15, 0xffff0000, v133
	v_pk_add_f32 v[6:7], v[6:7], v[8:9]
	v_pk_fma_f32 v[64:65], v[14:15], s[24:25], v[10:11] op_sel_hi:[1,0,1]
	v_add_f32_e32 v4, v4, v5
	v_pk_add_f32 v[6:7], v[6:7], v[6:7] op_sel_hi:[0,1]
	v_add_f32_e32 v5, 0, v4
	v_add_f32_e32 v9, v62, v63
	v_add_f32_e32 v11, v64, v65
	v_mov_b32_e32 v8, v60
	v_mov_b32_e32 v10, v61
	v_mov_b32_e32 v6, v50
	v_mov_b32_e32 v4, v51
	v_pk_add_f32 v[8:9], v[8:9], v[10:11]
	v_pk_add_f32 v[4:5], v[6:7], v[4:5]
	s_nop 0
	v_pk_add_f32 v[4:5], v[8:9], v[4:5]
	s_nop 0
	v_add_f32_e32 v4, v4, v5
	v_mov_b32_e32 v5, v4
	s_nop 1
	v_permlane16_swap_b32 v5, v4
	s_waitcnt lgkmcnt(0)
	v_add_f32_e32 v4, v4, v5
	v_mov_b32_e32 v5, v4
	s_nop 1
	v_permlane32_swap_b32 v5, v4
	s_waitcnt lgkmcnt(0)
	v_add_f32_e32 v4, v4, v5
	v_fmamk_f32 v6, v4, 0xbc800000, v143
	v_fmamk_f32 v8, v4, 0xbc800000, v141
	v_fmamk_f32 v5, v4, 0xbc800000, v142
	v_fmamk_f32 v7, v4, 0xbc800000, v140
	v_mul_f32_e32 v8, v8, v8
	v_mul_f32_e32 v6, v6, v6
	v_fmac_f32_e32 v8, v7, v7
	v_fmac_f32_e32 v6, v5, v5
	v_fmamk_f32 v7, v4, 0xbc800000, v139
	v_fmamk_f32 v9, v4, 0xbc800000, v137
	v_add_f32_e32 v5, v8, v6
	v_fmamk_f32 v6, v4, 0xbc800000, v138
	v_fmamk_f32 v8, v4, 0xbc800000, v136
	v_mul_f32_e32 v9, v9, v9
	v_mul_f32_e32 v7, v7, v7
	v_fmac_f32_e32 v9, v8, v8
	v_fmac_f32_e32 v7, v6, v6
	v_add_f32_e32 v6, v9, v7
	v_fmamk_f32 v7, v4, 0xbc800000, v65
	v_fmamk_f32 v9, v4, 0xbc800000, v63
	v_add_f32_e32 v5, v5, v6
	v_fmamk_f32 v6, v4, 0xbc800000, v64
	v_fmamk_f32 v8, v4, 0xbc800000, v62
	v_mul_f32_e32 v9, v9, v9
	v_mul_f32_e32 v7, v7, v7
	v_fmac_f32_e32 v9, v8, v8
	v_fmac_f32_e32 v7, v6, v6
	v_add_f32_e32 v6, v9, v7
	v_fmamk_f32 v7, v4, 0xbc800000, v51
	v_fmamk_f32 v9, v4, 0xbc800000, v61
	v_add_f32_e32 v5, v6, v5
	v_fmamk_f32 v6, v4, 0xbc800000, v50
	v_fmamk_f32 v8, v4, 0xbc800000, v60
	v_mul_f32_e32 v9, v9, v9
	v_mul_f32_e32 v7, v7, v7
	v_fmac_f32_e32 v9, v8, v8
	v_fmac_f32_e32 v7, v6, v6
	v_add_f32_e32 v6, v9, v7
	v_add_f32_e32 v5, v6, v5
	v_mov_b32_e32 v6, v5
	s_nop 1
	v_permlane16_swap_b32 v6, v5
	s_waitcnt lgkmcnt(0)
	v_add_f32_e32 v5, v5, v6
	v_mov_b32_e32 v6, v5
	s_nop 1
	v_permlane32_swap_b32 v6, v5
	s_and_saveexec_b64 s[46:47], s[44:45]
	s_cbranch_execz .LBB0_1105
	s_lshl_b32 s8, s83, 11
	s_add_i32 s36, s36, s8
	v_mul_f32_e32 v4, 0x3c800000, v4
	v_lshl_add_u32 v7, v228, 5, s36
	s_waitcnt lgkmcnt(0)
	v_add_f32_e32 v5, v5, v6
	ds_write_b64 v7, v[4:5] offset:5632

; #define LAS __attribute__((address_space(3)))
;     __device__ __forceinline__ void fused(f32x4 (&acc)[2][2][4][2], const Unit& u, int wr, int wc, int fr, int fq, LAS unsigned char* lds, int wid, int lane) const {
;     ...
;             for (int g = 0; g < 8; ++g) {
;                 const LAS float* wq = wgl + g * 256 + wc * 32 + 8 * fq;
;                 const f32x4 q00 = *(const LAS f32x4*)(wq), q01 = *(const LAS f32x4*)(wq + 4), q10 = *(const LAS f32x4*)(wq + HALF), q11 = *(const LAS f32x4*)(wq + HALF + 4);
; #pragma unroll
;                 for (int ai = 0; ai < 2; ++ai)
; #pragma unroll
;                     for (int m = 0; m < 4; ++m) {
;                         const f32x4 a0 = acc[ai][0][m][0] * q00 + acc[ai][0][m][1] * q01 + acc[ai][1][m][0] * q10 + acc[ai][1][m][1] * q11;
;                         float p = (a0[0] + a0[1]) + (a0[2] + a0[3]);
;                         p += __shfl_xor(p, 16); p += __shfl_xor(p, 32);
;                         if (fq == 0) GP[((ai * HALF + wr * 64 + m * 16 + fr) * 8 + g) * 4 + wc] = p;
;                     }
.LBB0_1118:
	ds_read_b128 v[14:17], v33 offset:16
	ds_read_b128 v[10:13], v33
	ds_read_b128 v[6:9], v33 offset:512
	s_waitcnt lgkmcnt(3)
	ds_read_b128 v[2:5], v33 offset:528
	s_waitcnt lgkmcnt(3)
	v_pk_mul_f32 v[44:45], v[96:97], v[16:17]
	v_pk_mul_f32 v[50:51], v[98:99], v[14:15]
	s_waitcnt lgkmcnt(2)
	v_pk_fma_f32 v[44:45], v[92:93], v[12:13], v[44:45]
	v_pk_fma_f32 v[50:51], v[94:95], v[10:11], v[50:51]
	s_waitcnt lgkmcnt(1)
	v_pk_fma_f32 v[44:45], v[120:121], v[8:9], v[44:45]
	v_pk_fma_f32 v[50:51], v[122:123], v[6:7], v[50:51]
	s_waitcnt lgkmcnt(0)
	v_pk_fma_f32 v[44:45], v[26:27], v[4:5], v[44:45]
	v_pk_fma_f32 v[50:51], v[116:117], v[2:3], v[50:51]
	v_add_f32_e32 v44, v44, v45
	v_add_f32_e32 v50, v50, v51
	v_add_f32_e32 v44, v50, v44
	v_mov_b32_e32 v45, v44
	s_nop 1
	v_permlane16_swap_b32 v45, v44
	s_waitcnt lgkmcnt(0)
	v_add_f32_e32 v45, v44, v45
	v_mov_b32_e32 v50, v45
	s_nop 1
	v_permlane32_swap_b32 v50, v45
	v_add_u32_e32 v44, s5, v32
	s_and_saveexec_b64 s[28:29], s[44:45]
	s_cbranch_execz .LBB0_1120
	s_waitcnt lgkmcnt(0)
	v_add_f32_e32 v45, v45, v50
	ds_write_b32 v44, v45
.LBB0_1120:
	s_or_b64 exec, exec, s[28:29]
	s_waitcnt lgkmcnt(0)
	v_pk_mul_f32 v[50:51], v[112:113], v[16:17]
	v_pk_mul_f32 v[60:61], v[114:115], v[14:15]
	v_pk_fma_f32 v[50:51], v[108:109], v[12:13], v[50:51]
	v_pk_fma_f32 v[60:61], v[110:111], v[10:11], v[60:61]
	v_pk_fma_f32 v[50:51], v[104:105], v[8:9], v[50:51]
	v_pk_fma_f32 v[60:61], v[106:107], v[6:7], v[60:61]
	v_pk_fma_f32 v[50:51], v[28:29], v[4:5], v[50:51]
	v_pk_fma_f32 v[60:61], v[100:101], v[2:3], v[60:61]
	v_add_f32_e32 v50, v50, v51
	v_add_f32_e32 v45, v60, v61
	v_add_f32_e32 v45, v45, v50
	v_mov_b32_e32 v50, v45
	s_nop 1
	v_permlane16_swap_b32 v50, v45
	s_waitcnt lgkmcnt(0)
	v_add_f32_e32 v45, v45, v50
	v_mov_b32_e32 v50, v45
	s_nop 1
	v_permlane32_swap_b32 v50, v45
	s_and_saveexec_b64 s[28:29], s[44:45]
	s_cbranch_execz .LBB0_1122
	s_waitcnt lgkmcnt(0)
	v_add_f32_e32 v45, v45, v50
	ds_write_b32 v44, v45 offset:2048
.LBB0_1122:
	s_or_b64 exec, exec, s[28:29]
	s_waitcnt lgkmcnt(0)
	v_pk_mul_f32 v[50:51], v[128:129], v[16:17]
	v_pk_mul_f32 v[60:61], v[130:131], v[14:15]
	v_pk_fma_f32 v[50:51], v[124:125], v[12:13], v[50:51]
	v_pk_fma_f32 v[60:61], v[126:127], v[10:11], v[60:61]
	v_pk_fma_f32 v[50:51], v[88:89], v[8:9], v[50:51]
	v_pk_fma_f32 v[60:61], v[90:91], v[6:7], v[60:61]
	v_pk_fma_f32 v[50:51], v[84:85], v[4:5], v[50:51]
	v_pk_fma_f32 v[60:61], v[86:87], v[2:3], v[60:61]
	v_add_f32_e32 v50, v50, v51
	v_add_f32_e32 v45, v60, v61
	v_add_f32_e32 v45, v45, v50
	v_mov_b32_e32 v50, v45
	s_nop 1
	v_permlane16_swap_b32 v50, v45
	s_waitcnt lgkmcnt(0)
	v_add_f32_e32 v45, v45, v50
	v_mov_b32_e32 v50, v45
	s_nop 1
	v_permlane32_swap_b32 v50, v45
	s_and_saveexec_b64 s[28:29], s[44:45]
	s_cbranch_execz .LBB0_1124
	s_waitcnt lgkmcnt(0)
	v_add_f32_e32 v45, v45, v50
	ds_write_b32 v44, v45 offset:4096
.LBB0_1124:
	s_or_b64 exec, exec, s[28:29]
	s_waitcnt lgkmcnt(0)
	v_pk_mul_f32 v[50:51], v[76:77], v[16:17]
	v_pk_mul_f32 v[60:61], v[78:79], v[14:15]
	v_pk_fma_f32 v[50:51], v[80:81], v[12:13], v[50:51]
	v_pk_fma_f32 v[60:61], v[82:83], v[10:11], v[60:61]
	v_pk_fma_f32 v[50:51], v[72:73], v[8:9], v[50:51]
	v_pk_fma_f32 v[60:61], v[74:75], v[6:7], v[60:61]
	v_pk_fma_f32 v[50:51], v[68:69], v[4:5], v[50:51]
	v_pk_fma_f32 v[60:61], v[70:71], v[2:3], v[60:61]
	v_add_f32_e32 v50, v50, v51
	v_add_f32_e32 v45, v60, v61
	v_add_f32_e32 v45, v45, v50
	v_mov_b32_e32 v50, v45
	s_nop 1
	v_permlane16_swap_b32 v50, v45
	s_waitcnt lgkmcnt(0)
	v_add_f32_e32 v45, v45, v50
	v_mov_b32_e32 v50, v45
	s_nop 1
	v_permlane32_swap_b32 v50, v45
	s_and_saveexec_b64 s[28:29], s[44:45]
	s_cbranch_execz .LBB0_1126
	s_waitcnt lgkmcnt(0)
	v_add_f32_e32 v45, v45, v50
	ds_write_b32 v44, v45 offset:6144
; #define LAS __attribute__((address_space(3)))
;     __device__ __forceinline__ void fused(f32x4 (&acc)[2][2][4][2], const Unit& u, int wr, int wc, int fr, int fq, LAS unsigned char* lds, int wid, int lane) const {
;     ...
;             for (int g = 0; g < 8; ++g) {
;                 const LAS float* wq = wgl + g * 256 + wc * 32 + 8 * fq;
;                 const f32x4 q00 = *(const LAS f32x4*)(wq), q01 = *(const LAS f32x4*)(wq + 4), q10 = *(const LAS f32x4*)(wq + HALF), q11 = *(const LAS f32x4*)(wq + HALF + 4);
; #pragma unroll
;                 for (int ai = 0; ai < 2; ++ai)
; #pragma unroll
;                     for (int m = 0; m < 4; ++m) {
;                         const f32x4 a0 = acc[ai][0][m][0] * q00 + acc[ai][0][m][1] * q01 + acc[ai][1][m][0] * q10 + acc[ai][1][m][1] * q11;
;                         float p = (a0[0] + a0[1]) + (a0[2] + a0[3]);
;                         p += __shfl_xor(p, 16); p += __shfl_xor(p, 32);
;                         if (fq == 0) GP[((ai * HALF + wr * 64 + m * 16 + fr) * 8 + g) * 4 + wc] = p;
;                     }
.LBB0_1126:
	s_or_b64 exec, exec, s[28:29]
	s_waitcnt lgkmcnt(0)
	v_pk_mul_f32 v[50:51], v[66:67], v[16:17]
	v_pk_mul_f32 v[60:61], v[160:161], v[14:15]
	v_pk_fma_f32 v[50:51], v[132:133], v[12:13], v[50:51]
	v_pk_fma_f32 v[60:61], v[134:135], v[10:11], v[60:61]
	v_pk_fma_f32 v[50:51], v[56:57], v[8:9], v[50:51]
	v_pk_fma_f32 v[60:61], v[58:59], v[6:7], v[60:61]
	v_pk_fma_f32 v[50:51], v[52:53], v[4:5], v[50:51]
	v_pk_fma_f32 v[60:61], v[54:55], v[2:3], v[60:61]
	v_add_f32_e32 v50, v50, v51
	v_add_f32_e32 v45, v60, v61
	v_add_f32_e32 v45, v45, v50
	v_mov_b32_e32 v50, v45
	s_nop 1
	v_permlane16_swap_b32 v50, v45
	s_waitcnt lgkmcnt(0)
	v_add_f32_e32 v45, v45, v50
	v_mov_b32_e32 v50, v45
	s_nop 1
	v_permlane32_swap_b32 v50, v45
	s_and_saveexec_b64 s[28:29], s[44:45]
	s_cbranch_execz .LBB0_1128
	s_waitcnt lgkmcnt(0)
	v_add_f32_e32 v45, v45, v50
	ds_write_b32 v44, v45 offset:16384
.LBB0_1128:
	s_or_b64 exec, exec, s[28:29]
	s_waitcnt lgkmcnt(0)
	v_pk_mul_f32 v[50:51], v[152:153], v[16:17]
	v_pk_mul_f32 v[60:61], v[154:155], v[14:15]
	v_pk_fma_f32 v[50:51], v[156:157], v[12:13], v[50:51]
	v_pk_fma_f32 v[60:61], v[158:159], v[10:11], v[60:61]
	v_pk_fma_f32 v[50:51], v[40:41], v[8:9], v[50:51]
	v_pk_fma_f32 v[60:61], v[42:43], v[6:7], v[60:61]
	v_pk_fma_f32 v[50:51], v[36:37], v[4:5], v[50:51]
	v_pk_fma_f32 v[60:61], v[38:39], v[2:3], v[60:61]
	v_add_f32_e32 v50, v50, v51
	v_add_f32_e32 v45, v60, v61
	v_add_f32_e32 v45, v45, v50
	v_mov_b32_e32 v50, v45
	s_nop 1
	v_permlane16_swap_b32 v50, v45
	s_waitcnt lgkmcnt(0)
	v_add_f32_e32 v45, v45, v50
	v_mov_b32_e32 v50, v45
	s_nop 1
	v_permlane32_swap_b32 v50, v45
	s_and_saveexec_b64 s[28:29], s[44:45]
	s_cbranch_execz .LBB0_1130
	s_waitcnt lgkmcnt(0)
	v_add_f32_e32 v45, v45, v50
	ds_write_b32 v44, v45 offset:18432
.LBB0_1130:
	s_or_b64 exec, exec, s[28:29]
	s_waitcnt lgkmcnt(0)
	v_pk_mul_f32 v[50:51], v[144:145], v[16:17]
	v_pk_mul_f32 v[60:61], v[146:147], v[14:15]
	v_pk_fma_f32 v[50:51], v[148:149], v[12:13], v[50:51]
	v_pk_fma_f32 v[60:61], v[150:151], v[10:11], v[60:61]
	v_pk_fma_f32 v[50:51], v[46:47], v[8:9], v[50:51]
	v_pk_fma_f32 v[60:61], v[48:49], v[6:7], v[60:61]
	v_pk_fma_f32 v[50:51], v[30:31], v[4:5], v[50:51]
	v_pk_fma_f32 v[60:61], v[34:35], v[2:3], v[60:61]
	v_add_f32_e32 v50, v50, v51
	v_add_f32_e32 v45, v60, v61
	v_add_f32_e32 v45, v45, v50
	v_mov_b32_e32 v50, v45
	s_nop 1
	v_permlane16_swap_b32 v50, v45
	s_waitcnt lgkmcnt(0)
	v_add_f32_e32 v45, v45, v50
	v_mov_b32_e32 v50, v45
	s_nop 1
	v_permlane32_swap_b32 v50, v45
	s_and_saveexec_b64 s[28:29], s[44:45]
	s_cbranch_execz .LBB0_1132
	s_waitcnt lgkmcnt(0)
	v_add_f32_e32 v45, v45, v50
	ds_write_b32 v44, v45 offset:20480
.LBB0_1132:
	s_or_b64 exec, exec, s[28:29]
	v_pk_mul_f32 v[16:17], v[136:137], v[16:17]
	v_pk_mul_f32 v[14:15], v[138:139], v[14:15]
	v_pk_fma_f32 v[12:13], v[140:141], v[12:13], v[16:17]
	v_pk_fma_f32 v[10:11], v[142:143], v[10:11], v[14:15]
	v_pk_fma_f32 v[8:9], v[20:21], v[8:9], v[12:13]
	v_pk_fma_f32 v[6:7], v[18:19], v[6:7], v[10:11]
	v_pk_fma_f32 v[4:5], v[22:23], v[4:5], v[8:9]
	v_pk_fma_f32 v[2:3], v[24:25], v[2:3], v[6:7]
	s_nop 0
	v_add_f32_e32 v2, v2, v3
	v_add_f32_e32 v3, v4, v5
	v_add_f32_e32 v2, v2, v3
	v_mov_b32_e32 v3, v2
	s_nop 1
	v_permlane16_swap_b32 v3, v2
	s_waitcnt lgkmcnt(0)
	v_add_f32_e32 v2, v2, v3
	v_mov_b32_e32 v3, v2
	s_nop 1
	v_permlane32_swap_b32 v3, v2
	s_and_saveexec_b64 s[28:29], s[44:45]
	s_cbranch_execz .LBB0_1117
	s_waitcnt lgkmcnt(0)
	v_add_f32_e32 v2, v2, v3
	ds_write_b32 v44, v2 offset:22528
	s_branch .LBB0_1117
